# mix_state GLA items: gate weights/bias staged in LDS once per phase and read with ds_read_b128 (groups 1-5) instead of 170 wave-uniform global loads per item
# speedup vs baseline: 1.0137x; 1.0035x over previous
.LBB0_651:
	s_add_u32 s16, s12, 0x127b4000
	s_addc_u32 s17, s13, 0
	s_add_u32 s12, s14, 0x6554000
	s_addc_u32 s13, s15, 0
	v_writelane_b32 v253, s12, 51
	s_mov_b32 s59, s57
	s_mul_i32 s58, s80, 0x180
	v_writelane_b32 v253, s13, 52
	s_lshl_b32 s12, s80, 3
	s_mov_b32 s13, s57
	s_lshl_b64 s[12:13], s[12:13], 2
	s_add_u32 s10, s10, s12
	v_writelane_b32 v253, s10, 53
	s_addc_u32 s10, s11, s13
	v_writelane_b32 v253, s10, 54
	v_writelane_b32 v253, s56, 55
	s_and_b64 vcc, exec, s[0:1]
	s_nop 0
	v_writelane_b32 v253, s57, 56
	v_writelane_b32 v253, s80, 57
	s_cbranch_vccnz .LBB0_702
	s_waitcnt lgkmcnt(0)
	s_add_u32 s0, s4, 0x3b317600
	s_addc_u32 s1, s5, 0
	v_writelane_b32 v253, s0, 58
	v_and_b32_e32 v48, 63, v198
	v_lshl_add_u32 v58, v48, 1, 0
	v_writelane_b32 v253, s1, 59
	s_mul_i32 s0, s80, 0x6000
	s_add_u32 s12, s6, s0
	s_addc_u32 s13, s7, 0
	v_writelane_b32 v253, s58, 60
	s_lshl_b64 s[0:1], s[58:59], 2
	s_add_u32 s6, s8, s0
	s_addc_u32 s7, s9, s1
	v_lshlrev_b32_e32 v80, 4, v198
	v_add_u32_e32 v81, 0x2000, v80
	v_add_u32_e32 v82, 0x4000, v80
	global_load_dwordx4 v[64:67], v80, s[12:13]
	global_load_dwordx4 v[68:71], v81, s[12:13]
	global_load_dwordx4 v[72:75], v82, s[12:13]
	v_min_u32_e32 v83, 0x5f, v198
	v_lshlrev_b32_e32 v84, 4, v83
	global_load_dwordx4 v[76:79], v84, s[6:7]
	v_subrev_u32_e32 v85, 48, v83
	v_ashrrev_i32_e32 v85, 31, v85
	v_not_b32_e32 v85, v85
	v_and_b32_e32 v85, 0x2d00, v85
	v_add_u32_e32 v84, v84, v85
	v_add_u32_e32 v84, 0x21000, v84
	v_add_u32_e32 v80, 0x1b000, v80
	s_waitcnt vmcnt(0)
	ds_write_b128 v80, v[64:67]
	ds_write_b128 v80, v[68:71] offset:8192
	ds_write_b128 v80, v[72:75] offset:16384
	ds_write_b128 v84, v[76:79]
	s_ashr_i32 s4, s19, 7
	s_mul_i32 s20, s4, 48
	s_bfe_u32 s15, s19, 0x10006
	s_ashr_i32 s21, s20, 31
	s_mul_i32 s0, s18, 0x480
	s_mul_i32 s14, s15, 0xc0
	s_cmp_eq_u32 s15, 0
	v_add_u32_e32 v199, s0, v58
	s_cselect_b64 s[8:9], -1, 0
	s_add_i32 s0, s14, s20
	s_ashr_i32 s5, s4, 31
	s_lshl_b64 s[22:23], s[4:5], 1
	s_ashr_i32 s5, s0, 3
	v_writelane_b32 v253, s59, 61
	s_ashr_i32 s1, s5, 31
	v_writelane_b32 v253, s1, 62
	s_mul_i32 s1, s18, 0x1b00
	v_add_u32_e32 v208, s1, v58
	s_or_b32 s1, s5, 1
	v_writelane_b32 v254, s1, 0
	s_ashr_i32 s1, s1, 31
	v_writelane_b32 v254, s1, 1
	s_add_i32 s1, s0, 16
	s_ashr_i32 s1, s1, 3
	v_writelane_b32 v254, s1, 2
	s_ashr_i32 s1, s1, 31
	v_writelane_b32 v254, s1, 4
	s_add_i32 s1, s0, 24
	s_ashr_i32 s1, s1, 3
	v_writelane_b32 v254, s1, 6
	s_ashr_i32 s1, s1, 31
	v_writelane_b32 v254, s1, 8
	s_add_i32 s1, s0, 32
	s_ashr_i32 s1, s1, 3
	v_writelane_b32 v254, s1, 10
	s_ashr_i32 s1, s1, 31
	s_add_i32 s0, s0, 40
	v_writelane_b32 v254, s1, 12
	s_ashr_i32 s0, s0, 3
	v_writelane_b32 v254, s0, 14
	s_ashr_i32 s0, s0, 31
	v_writelane_b32 v253, s5, 63
	v_writelane_b32 v254, s0, 16
	s_lshl_b32 s5, s18, 3
	v_writelane_b32 v254, s5, 18
	s_lshl_b32 s5, s18, 1
	s_and_b32 s5, s5, 2
	s_or_b32 s18, s5, 0x120
	v_writelane_b32 v254, s18, 19
	s_or_b32 s5, s5, 0x121
	v_bitop3_b32 v58, v198, 63, v198 bitop3:0xc
	v_writelane_b32 v254, s5, 20
	s_lshl_b32 s5, s4, 1
	v_cmp_eq_u32_e64 s[10:11], 0, v48
	v_or_b32_e32 v209, 0xffffff00, v48
	s_lshl_b32 s0, s15, 2
	v_cndmask_b32_e64 v48, v48, v58, s[8:9]
	s_or_b32 s5, s5, s15
	s_add_i32 s0, s0, s4
	v_cvt_f32_ubyte0_e32 v210, v48
	v_and_b32_e32 v48, 15, v198
	s_mul_i32 s5, s5, 48
	s_mulk_i32 s4, 0x60
	v_or_b32_e32 v59, s5, v48
	v_or_b32_e32 v60, s4, v48
	s_movk_i32 s4, 0x90
	s_or_b32 s22, s22, s15
	s_ashr_i32 s1, s0, 31
	v_mul_lo_u32 v59, v59, s4
	v_mul_lo_u32 v60, v60, s4
	s_mulk_i32 s15, 0x3000
	s_mov_b32 s4, s20
	s_add_u32 s12, s12, s15
	v_writelane_b32 v254, s4, 21
	s_addc_u32 s13, s13, 0
	v_mul_u32_u24_e32 v61, 48, v48
	v_writelane_b32 v254, s5, 22
	s_lshl_b64 s[4:5], s[20:21], 2
	s_add_u32 s24, s12, s4
	s_addc_u32 s25, s13, s5
	s_lshl_b32 s12, s14, 2
	s_add_u32 s6, s6, s12
	s_addc_u32 s7, s7, 0
	s_add_u32 s26, s6, s4
	s_addc_u32 s27, s7, s5
	s_add_u32 s4, s24, 0x1200
	s_addc_u32 s5, s25, 0
	v_writelane_b32 v254, s4, 23
	v_lshrrev_b32_e32 v48, 1, v198
	v_and_b32_e32 v48, 24, v48
	v_writelane_b32 v254, s5, 24
	s_add_u32 s4, s24, 0x1500
	s_addc_u32 s5, s25, 0
	v_writelane_b32 v254, s4, 25
	v_lshl_add_u64 v[62:63], s[84:85], 0, v[48:49]
	v_and_b32_e32 v58, 48, v198
	v_writelane_b32 v254, s5, 26
	s_add_u32 s4, s24, 0x1800
	s_addc_u32 s5, s25, 0
	v_writelane_b32 v254, s4, 27
	v_add_u32_e32 v58, 0, v58
	v_lshlrev_b32_e32 v48, 1, v61
	v_writelane_b32 v254, s5, 28
	s_add_u32 s4, s24, 0x1b00
	s_addc_u32 s5, s25, 0
	v_writelane_b32 v254, s4, 29
	v_lshl_add_u64 v[200:201], v[62:63], 0, v[48:49]
	v_add_u32_e32 v211, v58, v59
	v_writelane_b32 v254, s5, 30
	s_add_u32 s4, s24, 0x1e00
	s_addc_u32 s5, s25, 0
	v_writelane_b32 v254, s4, 31
	v_add_u32_e32 v212, v58, v60
	s_mov_b32 s97, s2
	v_writelane_b32 v254, s5, 32
	s_add_u32 s4, s24, 0x2100
	s_addc_u32 s5, s25, 0
	v_writelane_b32 v254, s4, 33
	v_readlane_b32 s14, v252, 18
	v_readlane_b32 s13, v252, 19
	v_writelane_b32 v254, s5, 34
	s_add_u32 s4, s24, 0x2400
	s_addc_u32 s5, s25, 0
	v_writelane_b32 v254, s4, 35
	v_readlane_b32 s12, v252, 22
	s_nop 0
	v_writelane_b32 v254, s5, 36
	s_add_u32 s4, s24, 0x2700
	s_addc_u32 s5, s25, 0
	v_writelane_b32 v254, s4, 37
	s_nop 1
	v_writelane_b32 v254, s5, 38
	s_add_u32 s4, s24, 0x2a00
	s_addc_u32 s5, s25, 0
	v_writelane_b32 v254, s4, 39
	s_nop 1
	v_writelane_b32 v254, s5, 40
	s_add_u32 s4, s24, 0x2d00
	s_addc_u32 s5, s25, 0
	v_writelane_b32 v254, s4, 41
	s_nop 1
	v_writelane_b32 v254, s5, 42
	s_add_u32 s4, s24, 0x1220
	s_addc_u32 s5, s25, 0
	v_writelane_b32 v254, s4, 43
	s_nop 1
	v_writelane_b32 v254, s5, 44
	s_add_u32 s4, s24, 0x1520
	s_addc_u32 s5, s25, 0
	v_writelane_b32 v254, s4, 45
	s_nop 1
	v_writelane_b32 v254, s5, 46
	s_add_u32 s4, s24, 0x1820
	s_addc_u32 s5, s25, 0
	v_writelane_b32 v254, s4, 47
	s_nop 1
	v_writelane_b32 v254, s5, 48
	s_add_u32 s4, s24, 0x1b20
	s_addc_u32 s5, s25, 0
	v_writelane_b32 v254, s4, 49
	s_nop 1
	v_writelane_b32 v254, s5, 50
	s_add_u32 s4, s24, 0x1e20
	s_addc_u32 s5, s25, 0
	v_writelane_b32 v254, s4, 51
	s_nop 1
	v_writelane_b32 v254, s5, 52
	s_add_u32 s4, s24, 0x2120
	s_addc_u32 s5, s25, 0
	v_writelane_b32 v254, s4, 53
	s_nop 1
	v_writelane_b32 v254, s5, 54
	s_add_u32 s4, s24, 0x2420
	s_addc_u32 s5, s25, 0
	v_writelane_b32 v254, s4, 55
	s_nop 1
	v_writelane_b32 v254, s5, 56
	s_add_u32 s4, s24, 0x2720
	s_addc_u32 s5, s25, 0
	v_writelane_b32 v254, s4, 57
	s_nop 1
	v_writelane_b32 v254, s5, 58
	s_add_u32 s4, s24, 0x2a20
	s_addc_u32 s5, s25, 0
	v_writelane_b32 v254, s4, 59
	s_nop 1
	v_writelane_b32 v254, s5, 60
	s_add_u32 s4, s24, 0x2d20
	s_addc_u32 s5, s25, 0
	v_writelane_b32 v254, s4, 61
	s_nop 1
	v_writelane_b32 v254, s5, 62
	s_add_u32 s4, s24, 0x1240
	s_addc_u32 s5, s25, 0
	v_writelane_b32 v254, s4, 63
	s_nop 1
	v_writelane_b32 v255, s5, 0
	s_add_u32 s4, s24, 0x1540
	s_addc_u32 s5, s25, 0
	v_writelane_b32 v255, s4, 1
	s_nop 1
	v_writelane_b32 v255, s5, 2
	s_add_u32 s4, s24, 0x1840
	s_addc_u32 s5, s25, 0
	v_writelane_b32 v255, s4, 3
	s_nop 1
	v_writelane_b32 v255, s5, 4
	s_add_u32 s4, s24, 0x1b40
	s_addc_u32 s5, s25, 0
	v_writelane_b32 v255, s4, 5
	s_nop 1
	v_writelane_b32 v255, s5, 6
	s_add_u32 s4, s24, 0x1e40
	s_addc_u32 s5, s25, 0
	v_writelane_b32 v255, s4, 7
	s_nop 1
	v_writelane_b32 v255, s5, 8
	s_add_u32 s4, s24, 0x2140
	s_addc_u32 s5, s25, 0
	v_writelane_b32 v255, s4, 9
	s_nop 1
	v_writelane_b32 v255, s5, 10
	s_add_u32 s4, s24, 0x2440
	s_addc_u32 s5, s25, 0
	v_writelane_b32 v255, s4, 11
	s_nop 1
	v_writelane_b32 v255, s5, 12
	s_add_u32 s4, s24, 0x2740
	s_addc_u32 s5, s25, 0
	v_writelane_b32 v255, s4, 13
	s_nop 1
	v_writelane_b32 v255, s5, 14
	s_add_u32 s4, s24, 0x2a40
	s_addc_u32 s5, s25, 0
	v_writelane_b32 v255, s4, 15
	s_nop 1
	v_writelane_b32 v255, s5, 16
	s_add_u32 s4, s24, 0x2d40
	s_addc_u32 s5, s25, 0
	v_writelane_b32 v255, s4, 17
	s_nop 1
	v_writelane_b32 v255, s5, 18
	s_add_u32 s4, s24, 0x1260
	s_addc_u32 s5, s25, 0
	v_writelane_b32 v255, s4, 19
	s_nop 1
	v_writelane_b32 v255, s5, 20
	s_add_u32 s4, s24, 0x1560
	s_addc_u32 s5, s25, 0
	v_writelane_b32 v255, s4, 21
	s_nop 1
	v_writelane_b32 v255, s5, 22
	s_add_u32 s4, s24, 0x1860
	s_addc_u32 s5, s25, 0
	v_writelane_b32 v255, s4, 23
	s_nop 1
	v_writelane_b32 v255, s5, 24
	s_add_u32 s4, s24, 0x1b60
	s_addc_u32 s5, s25, 0
	v_writelane_b32 v255, s4, 25
	s_nop 1
	v_writelane_b32 v255, s5, 26
	s_add_u32 s4, s24, 0x1e60
	s_addc_u32 s5, s25, 0
	v_writelane_b32 v255, s4, 27
	s_nop 1
	v_writelane_b32 v255, s5, 28
	s_add_u32 s4, s24, 0x2160
	s_addc_u32 s5, s25, 0
	v_writelane_b32 v255, s4, 29
	s_nop 1
	v_writelane_b32 v255, s5, 30
	s_add_u32 s4, s24, 0x2460
	s_addc_u32 s5, s25, 0
	v_writelane_b32 v255, s4, 31
	s_nop 1
	v_writelane_b32 v255, s5, 32
	s_add_u32 s4, s24, 0x2760
	s_addc_u32 s5, s25, 0
	v_writelane_b32 v255, s4, 33
	s_nop 1
	v_writelane_b32 v255, s5, 34
	s_add_u32 s4, s24, 0x2a60
	s_addc_u32 s5, s25, 0
	v_writelane_b32 v255, s4, 35
	s_nop 1
	v_writelane_b32 v255, s5, 36
	s_add_u32 s4, s24, 0x2d60
	s_addc_u32 s5, s25, 0
	v_writelane_b32 v255, s4, 37
	s_nop 1
	v_writelane_b32 v255, s5, 38
	s_add_u32 s4, s24, 0x1280
	s_addc_u32 s5, s25, 0
	v_writelane_b32 v255, s4, 39
	s_nop 1
	v_writelane_b32 v255, s5, 40
	s_add_u32 s4, s24, 0x1580
	s_addc_u32 s5, s25, 0
	s_add_u32 s42, s24, 0x1880
	s_addc_u32 s43, s25, 0
	s_add_u32 s44, s24, 0x1b80
	s_addc_u32 s45, s25, 0
	s_add_u32 s46, s24, 0x1e80
	s_addc_u32 s47, s25, 0
	s_add_u32 s48, s24, 0x2180
	s_addc_u32 s49, s25, 0
	s_add_u32 s50, s24, 0x2480
	s_addc_u32 s51, s25, 0
	s_add_u32 s52, s24, 0x2780
	s_addc_u32 s53, s25, 0
	s_add_u32 s54, s24, 0x2a80
	s_addc_u32 s55, s25, 0
	s_add_u32 s56, s24, 0x2d80
	s_addc_u32 s57, s25, 0
	s_add_u32 s58, s24, 0x12a0
	s_addc_u32 s59, s25, 0
	s_add_u32 s60, s24, 0x15a0
	s_addc_u32 s61, s25, 0
	s_add_u32 s62, s24, 0x18a0
	s_addc_u32 s63, s25, 0
	s_add_u32 s72, s24, 0x1ba0
	s_addc_u32 s73, s25, 0
	s_add_u32 s74, s24, 0x1ea0
	s_addc_u32 s75, s25, 0
	s_add_u32 s76, s24, 0x21a0
	s_addc_u32 s77, s25, 0
	s_add_u32 s78, s24, 0x24a0
	s_addc_u32 s79, s25, 0
	s_add_u32 s80, s24, 0x27a0
	s_addc_u32 s81, s25, 0
	s_add_u32 s82, s24, 0x2aa0
	s_addc_u32 s83, s25, 0
	v_writelane_b32 v255, s4, 41
	s_add_u32 s84, s24, 0x2da0
	s_addc_u32 s85, s25, 0
	v_writelane_b32 v255, s5, 42
	s_lshl_b64 s[0:1], s[0:1], 2
	v_readlane_b32 s4, v253, 53
	s_add_u32 s86, s4, s0
	v_readlane_b32 s0, v253, 54
	s_addc_u32 s87, s0, s1
	s_branch .LBB0_656

.LBB0_659:
	s_or_b64 exec, exec, s[0:1]
	v_readlane_b32 s0, v254, 43
	v_readlane_b32 s1, v254, 44
	v_lshrrev_b32_e32 v182, 6, v198
	v_and_b32_e32 v183, 1, v182
	v_lshrrev_b32_e32 v182, 1, v182
	v_mul_u32_u24_e32 v183, 0x3000, v183
	v_lshl_add_u32 v183, v182, 7, v183
	v_lshl_add_u32 v182, v182, 6, v183
	v_add_u32_e32 v182, 0x1b000, v182
	ds_read_b128 v[58:61], v182 offset:24624
	ds_read_b128 v[126:129], v182 offset:24608
	ds_read_b128 v[62:65], v182 offset:48
	ds_read_b128 v[130:133], v182 offset:32
	ds_read_b128 v[66:69], v182 offset:816
	ds_read_b128 v[134:137], v182 offset:800
	ds_read_b128 v[70:73], v182 offset:1584
	ds_read_b128 v[138:141], v182 offset:1568
	ds_read_b128 v[74:77], v182 offset:2352
	ds_read_b128 v[142:145], v182 offset:2336
	ds_read_b128 v[78:81], v182 offset:3120
	ds_read_b128 v[146:149], v182 offset:3104
	s_waitcnt lgkmcnt(8)
	ds_read_b128 v[82:85], v182 offset:3888
	ds_read_b128 v[150:153], v182 offset:3872
	ds_read_b128 v[86:89], v182 offset:4656
	ds_read_b128 v[154:157], v182 offset:4640
	s_waitcnt lgkmcnt(8)
	v_readlane_b32 s0, v254, 45
	v_readlane_b32 s1, v254, 46
	s_nop 4
	ds_read_b128 v[90:93], v182 offset:5424
	ds_read_b128 v[158:161], v182 offset:5408
	v_readlane_b32 s0, v254, 47
	v_readlane_b32 s1, v254, 48
	s_nop 4
	ds_read_b128 v[94:97], v182 offset:6192
	ds_read_b128 v[162:165], v182 offset:6176
	s_waitcnt lgkmcnt(8)
	v_readlane_b32 s0, v254, 49
	v_readlane_b32 s1, v254, 50
	s_nop 4
	ds_read_b128 v[98:101], v182 offset:6960
	ds_read_b128 v[166:169], v182 offset:6944
	v_readlane_b32 s0, v254, 51
	v_readlane_b32 s1, v254, 52
	s_nop 4
	ds_read_b128 v[102:105], v182 offset:7728
	ds_read_b128 v[170:173], v182 offset:7712
	s_waitcnt lgkmcnt(8)
	v_readlane_b32 s0, v254, 53
	v_readlane_b32 s1, v254, 54
	s_nop 4
	ds_read_b128 v[106:109], v182 offset:8496
	ds_read_b128 v[174:177], v182 offset:8480
	v_readlane_b32 s0, v254, 55
	v_readlane_b32 s1, v254, 56
	s_nop 4
	ds_read_b128 v[110:113], v182 offset:9264
	ds_read_b128 v[178:181], v182 offset:9248
	s_waitcnt lgkmcnt(8)
	v_readlane_b32 s0, v254, 57
	v_readlane_b32 s1, v254, 58
	s_nop 4
	ds_read_b128 v[114:117], v182 offset:10032
	ds_read_b128 v[182:185], v182 offset:10016
	v_readlane_b32 s0, v254, 59
	v_readlane_b32 s1, v254, 60
	s_waitcnt lgkmcnt(14)
	v_fma_f32 v58, v62, v242, v58
	s_waitcnt lgkmcnt(14)
	v_fma_f32 v48, v130, v242, v126
	s_waitcnt lgkmcnt(14)
	v_fmac_f32_e32 v48, v134, v223
	s_waitcnt lgkmcnt(14)
	v_fmac_f32_e32 v48, v138, v222
	s_waitcnt lgkmcnt(14)
	v_fmac_f32_e32 v48, v142, v221
	s_waitcnt lgkmcnt(14)
	v_fmac_f32_e32 v48, v146, v220
	s_waitcnt lgkmcnt(14)
	v_fmac_f32_e32 v48, v150, v219
	s_waitcnt lgkmcnt(14)
	v_fmac_f32_e32 v48, v154, v218
	v_fmac_f32_e32 v129, v133, v242
	v_fmac_f32_e32 v129, v137, v223
	s_waitcnt lgkmcnt(12)
	v_fmac_f32_e32 v48, v158, v217
	v_fmac_f32_e32 v129, v141, v222
	v_fmac_f32_e32 v129, v145, v221
	s_waitcnt lgkmcnt(10)
	v_fmac_f32_e32 v48, v162, v216
	v_fmac_f32_e32 v129, v149, v220
	v_fmac_f32_e32 v129, v153, v219
	s_waitcnt lgkmcnt(8)
	v_fmac_f32_e32 v48, v166, v215
	v_fmac_f32_e32 v129, v157, v218
	v_fmac_f32_e32 v129, v161, v217
	s_waitcnt lgkmcnt(6)
	v_fmac_f32_e32 v48, v170, v214
	v_fmac_f32_e32 v129, v165, v216
	v_fmac_f32_e32 v129, v169, v215
	s_waitcnt lgkmcnt(4)
	v_fmac_f32_e32 v48, v174, v213
	v_fmac_f32_e32 v129, v173, v214
	v_fmac_f32_e32 v129, v177, v213
	s_waitcnt lgkmcnt(2)
	v_mov_b32_e32 v118, v178
	v_fmac_f32_e32 v58, v66, v223
	v_fmac_f32_e32 v58, v70, v222
	s_waitcnt lgkmcnt(0)
	v_mov_b32_e32 v119, v182
	v_pk_mul_f32 v[118:119], v[118:119], v[206:207]
	v_mov_b32_e32 v182, v179
	v_add_f32_e32 v48, v48, v118
	v_add_f32_e32 v48, v48, v119
	v_lshrrev_b32_e32 v190, 6, v198
	v_and_b32_e32 v191, 1, v190
	v_lshrrev_b32_e32 v190, 1, v190
	v_mul_u32_u24_e32 v191, 0x3000, v191
	v_lshl_add_u32 v191, v190, 7, v191
	v_lshl_add_u32 v190, v190, 6, v191
	v_add_u32_e32 v190, 0x1b000, v190
	ds_read_b128 v[118:121], v190 offset:10800
	ds_read_b128 v[186:189], v190 offset:10784
	v_readlane_b32 s0, v254, 61
	v_readlane_b32 s1, v254, 62
	s_nop 4
	ds_read_b128 v[122:125], v190 offset:11568
	ds_read_b128 v[190:193], v190 offset:11552
	v_fmac_f32_e32 v58, v74, v221
	v_fmac_f32_e32 v58, v78, v220
	v_fmac_f32_e32 v58, v82, v219
	v_fmac_f32_e32 v58, v86, v218
	v_fmac_f32_e32 v58, v90, v217
	v_fmac_f32_e32 v58, v94, v216
	v_fmac_f32_e32 v58, v98, v215
	v_fmac_f32_e32 v58, v102, v214
	v_fmac_f32_e32 v58, v106, v213
	v_fma_f32 v63, v63, v242, v59
	v_fmac_f32_e32 v63, v67, v223
	v_fmac_f32_e32 v63, v71, v222
	v_fmac_f32_e32 v63, v75, v221
	v_fmac_f32_e32 v63, v79, v220
	v_fmac_f32_e32 v63, v83, v219
	v_fmac_f32_e32 v63, v87, v218
	v_fmac_f32_e32 v63, v91, v217
	v_fmac_f32_e32 v63, v95, v216
	v_fmac_f32_e32 v63, v99, v215
	v_fmac_f32_e32 v63, v103, v214
	v_fmac_f32_e32 v63, v107, v213
	v_fma_f32 v60, v64, v242, v60
	v_fmac_f32_e32 v60, v68, v223
	v_fmac_f32_e32 v60, v72, v222
	v_fmac_f32_e32 v60, v76, v221
	v_fmac_f32_e32 v60, v80, v220
	v_fmac_f32_e32 v60, v84, v219
	v_fmac_f32_e32 v60, v88, v218
	v_fmac_f32_e32 v60, v92, v217
	v_fmac_f32_e32 v60, v96, v216
	v_fmac_f32_e32 v60, v100, v215
	v_fmac_f32_e32 v60, v104, v214
	v_fmac_f32_e32 v60, v108, v213
	v_fmac_f32_e32 v61, v65, v242
	v_fmac_f32_e32 v61, v69, v223
	v_fmac_f32_e32 v61, v73, v222
	v_fmac_f32_e32 v61, v77, v221
	v_fmac_f32_e32 v61, v81, v220
	v_fmac_f32_e32 v61, v85, v219
	v_fmac_f32_e32 v61, v89, v218
	v_fmac_f32_e32 v61, v93, v217
	v_fmac_f32_e32 v61, v97, v216
	v_fmac_f32_e32 v61, v101, v215
	v_fmac_f32_e32 v61, v105, v214
	v_fmac_f32_e32 v61, v109, v213
	v_lshlrev_b32_e32 v64, 16, v36
	v_and_b32_e32 v65, 0xffff0000, v36
	v_and_b32_e32 v67, 0xffff0000, v37
	v_lshlrev_b32_e32 v68, 16, v38
	v_and_b32_e32 v69, 0xffff0000, v38
	v_lshlrev_b32_e32 v70, 16, v39
	v_and_b32_e32 v71, 0xffff0000, v39
	s_waitcnt lgkmcnt(2)
	v_mov_b32_e32 v244, v186
	s_waitcnt lgkmcnt(0)
	v_mov_b32_e32 v245, v190
	v_pk_mul_f32 v[244:245], v[244:245], v[204:205]
	v_mov_b32_e32 v190, v187
	v_add_f32_e32 v48, v48, v244
	v_add_f32_e32 v48, v48, v245
	v_max_f32_e64 v126, -v48, 0
	v_mul_f32_e64 v48, |v48|, s93
	v_exp_f32_e32 v48, v48
	s_nop 0
	v_add_f32_e32 v48, 1.0, v48
	v_cmp_gt_f32_e32 vcc, s92, v48
	s_nop 1
	v_cndmask_b32_e64 v130, 0, 32, vcc
	v_ldexp_f32 v48, v48, v130
	v_log_f32_e32 v48, v48
	s_nop 0
	v_mul_f32_e32 v130, 0x3f317217, v48
	v_fma_f32 v130, v48, s94, -v130
	v_fmac_f32_e32 v130, 0x3377d1cf, v48
	v_fmac_f32_e32 v130, 0x3f317217, v48
	v_cmp_lt_f32_e64 s[0:1], |v48|, s95
	s_nop 1
	v_cndmask_b32_e64 v48, v48, v130, s[0:1]
	v_cndmask_b32_e32 v130, 0, v239, vcc
	v_sub_f32_e32 v48, v48, v130
	v_add_f32_e32 v48, v126, v48
	v_mul_f32_e32 v126, 0xbd800000, v48
	v_mov_b32_e32 v130, v49
	s_nop 1
	v_mov_b32_dpp v130, v126 row_shr:1 row_mask:0xf bank_mask:0xf
	v_fmac_f32_e32 v130, 0xbd800000, v48
	s_nop 1
	v_add_f32_dpp v126, v130, v130 row_shr:2 row_mask:0xf bank_mask:0xf bound_ctrl:1
	v_mov_b32_e32 v130, v49
	s_nop 0
	v_add_f32_dpp v126, v126, v126 row_shr:4 row_mask:0xf bank_mask:0xf bound_ctrl:1
	s_nop 1
	v_add_f32_dpp v126, v126, v126 row_shr:8 row_mask:0xf bank_mask:0xf bound_ctrl:1
	s_nop 1
	v_mov_b32_dpp v130, v126 row_bcast:15 row_mask:0xa bank_mask:0xf
	v_add_f32_e32 v126, v126, v130
	v_mov_b32_e32 v130, v49
	s_nop 1
	v_mov_b32_dpp v130, v126 row_bcast:31 row_mask:0xc bank_mask:0xf
	v_add_f32_e32 v126, v126, v130
	s_nop 0
	v_readlane_b32 s4, v126, 63
	s_nop 1
	v_sub_f32_e32 v130, s4, v126
	v_fmac_f32_e32 v126, 0x3d800000, v48
	v_cndmask_b32_e64 v48, v126, v130, s[8:9]
	v_fma_f32 v130, v131, v242, v127
	v_fmac_f32_e32 v130, v135, v223
	v_fmac_f32_e32 v130, v139, v222
	v_fmac_f32_e32 v130, v143, v221
	v_fmac_f32_e32 v130, v147, v220
	v_fmac_f32_e32 v130, v151, v219
	v_fmac_f32_e32 v130, v155, v218
	v_fmac_f32_e32 v130, v159, v217
	v_fmac_f32_e32 v130, v163, v216
	v_fmac_f32_e32 v130, v167, v215
	v_fmac_f32_e32 v130, v171, v214
	v_fmac_f32_e32 v130, v175, v213
	v_pk_mul_f32 v[126:127], v[182:183], v[206:207]
	v_mov_b32_e32 v131, v184
	v_add_f32_e32 v126, v130, v126
	v_add_f32_e32 v130, v126, v127
	v_pk_mul_f32 v[126:127], v[190:191], v[204:205]
	v_mov_b32_e32 v184, v181
	v_add_f32_e32 v126, v130, v126
	v_add_f32_e32 v126, v126, v127
	v_max_f32_e64 v127, -v126, 0
	v_mul_f32_e64 v126, |v126|, s93
	v_exp_f32_e32 v126, v126
	v_mul_f32_e32 v48, 0x3fb8aa3b, v48
	v_exp_f32_e32 v48, v48
	v_add_f32_e32 v126, 1.0, v126
	v_cmp_gt_f32_e32 vcc, s92, v126
	s_nop 1
	v_cndmask_b32_e64 v130, 0, 32, vcc
	v_ldexp_f32 v126, v126, v130
	v_log_f32_e32 v126, v126
	s_nop 0
	v_mul_f32_e32 v130, 0x3f317217, v126
	v_fma_f32 v130, v126, s94, -v130
	v_fmac_f32_e32 v130, 0x3377d1cf, v126
	v_fmac_f32_e32 v130, 0x3f317217, v126
	v_cmp_lt_f32_e64 s[0:1], |v126|, s95
	s_nop 1
	v_cndmask_b32_e64 v126, v126, v130, s[0:1]
	v_cndmask_b32_e32 v130, 0, v239, vcc
	v_sub_f32_e32 v126, v126, v130
	v_add_f32_e32 v126, v127, v126
	v_mul_f32_e32 v127, 0xbd800000, v126
	v_mov_b32_e32 v130, v49
	s_nop 1
	v_mov_b32_dpp v130, v127 row_shr:1 row_mask:0xf bank_mask:0xf
	v_fmac_f32_e32 v130, 0xbd800000, v126
	s_nop 1
	v_add_f32_dpp v127, v130, v130 row_shr:2 row_mask:0xf bank_mask:0xf bound_ctrl:1
	v_mov_b32_e32 v130, v49
	s_nop 0
	v_add_f32_dpp v127, v127, v127 row_shr:4 row_mask:0xf bank_mask:0xf bound_ctrl:1
	s_nop 1
	v_add_f32_dpp v127, v127, v127 row_shr:8 row_mask:0xf bank_mask:0xf bound_ctrl:1
	s_nop 1
	v_mov_b32_dpp v130, v127 row_bcast:15 row_mask:0xa bank_mask:0xf
	v_add_f32_e32 v127, v127, v130
	v_mov_b32_e32 v130, v49
	s_nop 1
	v_mov_b32_dpp v130, v127 row_bcast:31 row_mask:0xc bank_mask:0xf
	v_add_f32_e32 v127, v127, v130
	s_nop 0
	v_readlane_b32 s5, v127, 63
	s_nop 1
	v_sub_f32_e32 v130, s5, v127
	v_fmac_f32_e32 v127, 0x3d800000, v126
	v_cndmask_b32_e64 v126, v127, v130, s[8:9]
	v_fma_f32 v127, v132, v242, v128
	v_fmac_f32_e32 v127, v136, v223
	v_fmac_f32_e32 v127, v140, v222
	v_fmac_f32_e32 v127, v144, v221
	v_fmac_f32_e32 v127, v148, v220
	v_fmac_f32_e32 v127, v152, v219
	v_fmac_f32_e32 v127, v156, v218
	v_fmac_f32_e32 v127, v160, v217
	v_fmac_f32_e32 v127, v164, v216
	v_fmac_f32_e32 v127, v168, v215
	v_fmac_f32_e32 v127, v172, v214
	v_mov_b32_e32 v130, v180
	v_fmac_f32_e32 v127, v176, v213
	v_pk_mul_f32 v[130:131], v[130:131], v[206:207]
	s_nop 0
	v_add_f32_e32 v127, v127, v130
	v_add_f32_e32 v127, v127, v131
	v_mov_b32_e32 v130, v188
	v_mov_b32_e32 v131, v192
	v_pk_mul_f32 v[130:131], v[130:131], v[204:205]
	v_mov_b32_e32 v192, v189
	v_add_f32_e32 v127, v127, v130
	v_add_f32_e32 v127, v127, v131
	v_max_f32_e64 v128, -v127, 0
	v_mul_f32_e64 v127, |v127|, s93
	v_exp_f32_e32 v127, v127
	s_nop 0
	v_add_f32_e32 v127, 1.0, v127
	v_cmp_gt_f32_e32 vcc, s92, v127
	s_nop 1
	v_cndmask_b32_e64 v130, 0, 32, vcc
	v_ldexp_f32 v127, v127, v130
	v_log_f32_e32 v127, v127
	s_nop 0
	v_mul_f32_e32 v130, 0x3f317217, v127
	v_fma_f32 v130, v127, s94, -v130
	v_fmac_f32_e32 v130, 0x3377d1cf, v127
	v_fmac_f32_e32 v130, 0x3f317217, v127
	v_cmp_lt_f32_e64 s[0:1], |v127|, s95
	s_nop 1
	v_cndmask_b32_e64 v127, v127, v130, s[0:1]
	v_cndmask_b32_e32 v130, 0, v239, vcc
	v_sub_f32_e32 v127, v127, v130
	v_add_f32_e32 v127, v128, v127
	v_mul_f32_e32 v128, 0xbd800000, v127
	v_mov_b32_e32 v130, v49
	s_nop 1
	v_mov_b32_dpp v130, v128 row_shr:1 row_mask:0xf bank_mask:0xf
	v_fmac_f32_e32 v130, 0xbd800000, v127
	s_nop 1
	v_add_f32_dpp v128, v130, v130 row_shr:2 row_mask:0xf bank_mask:0xf bound_ctrl:1
	v_mov_b32_e32 v130, v49
	s_nop 0
	v_add_f32_dpp v128, v128, v128 row_shr:4 row_mask:0xf bank_mask:0xf bound_ctrl:1
	s_nop 1
	v_add_f32_dpp v128, v128, v128 row_shr:8 row_mask:0xf bank_mask:0xf bound_ctrl:1
	s_nop 1
	v_mov_b32_dpp v130, v128 row_bcast:15 row_mask:0xa bank_mask:0xf
	v_add_f32_e32 v128, v128, v130
	v_mov_b32_e32 v130, v49
	s_nop 1
	v_mov_b32_dpp v130, v128 row_bcast:31 row_mask:0xc bank_mask:0xf
	v_add_f32_e32 v128, v128, v130
	s_nop 0
	v_readlane_b32 s6, v128, 63
	s_nop 1
	v_sub_f32_e32 v130, s6, v128
	v_fmac_f32_e32 v128, 0x3d800000, v127
	v_cndmask_b32_e64 v127, v128, v130, s[8:9]
	v_pk_mul_f32 v[130:131], v[184:185], v[206:207]
	s_nop 0
	v_add_f32_e32 v128, v129, v130
	v_add_f32_e32 v130, v128, v131
	v_pk_mul_f32 v[128:129], v[192:193], v[204:205]
	s_nop 0
	v_add_f32_e32 v128, v130, v128
	v_add_f32_e32 v128, v128, v129
	v_max_f32_e64 v129, -v128, 0
	v_mul_f32_e64 v128, |v128|, s93
	v_exp_f32_e32 v128, v128
	s_nop 0
	v_add_f32_e32 v128, 1.0, v128
	v_cmp_gt_f32_e32 vcc, s92, v128
	s_nop 1
	v_cndmask_b32_e64 v130, 0, 32, vcc
	v_ldexp_f32 v128, v128, v130
	v_log_f32_e32 v128, v128
	s_nop 0
	v_mul_f32_e32 v130, 0x3f317217, v128
	v_fma_f32 v130, v128, s94, -v130
	v_fmac_f32_e32 v130, 0x3377d1cf, v128
	v_fmac_f32_e32 v130, 0x3f317217, v128
	v_cmp_lt_f32_e64 s[0:1], |v128|, s95
	s_nop 1
	v_cndmask_b32_e64 v128, v128, v130, s[0:1]
	v_cndmask_b32_e32 v130, 0, v239, vcc
	v_sub_f32_e32 v128, v128, v130
	v_add_f32_e32 v128, v129, v128
	v_mul_f32_e32 v129, 0xbd800000, v128
	v_mov_b32_e32 v130, v49
	s_nop 1
	v_mov_b32_dpp v130, v129 row_shr:1 row_mask:0xf bank_mask:0xf
	v_fmac_f32_e32 v130, 0xbd800000, v128
	s_nop 1
	v_add_f32_dpp v129, v130, v130 row_shr:2 row_mask:0xf bank_mask:0xf bound_ctrl:1
	v_mov_b32_e32 v130, v49
	s_nop 0
	v_add_f32_dpp v129, v129, v129 row_shr:4 row_mask:0xf bank_mask:0xf bound_ctrl:1
	s_nop 1
	v_add_f32_dpp v129, v129, v129 row_shr:8 row_mask:0xf bank_mask:0xf bound_ctrl:1
	s_nop 1
	v_mov_b32_dpp v130, v129 row_bcast:15 row_mask:0xa bank_mask:0xf
	v_add_f32_e32 v129, v129, v130
	v_mov_b32_e32 v130, v49
	s_nop 1
	v_mov_b32_dpp v130, v129 row_bcast:31 row_mask:0xc bank_mask:0xf
	v_add_f32_e32 v129, v129, v130
	s_nop 0
	v_readlane_b32 s7, v129, 63
	s_nop 1
	v_sub_f32_e32 v130, s7, v129
	v_fmac_f32_e32 v129, 0x3d800000, v128
	v_cndmask_b32_e64 v130, v129, v130, s[8:9]
	v_mov_b32_e32 v128, v110
	v_mov_b32_e32 v129, v114
	v_pk_mul_f32 v[128:129], v[128:129], v[206:207]
	v_mov_b32_e32 v114, v111
	v_add_f32_e32 v58, v58, v128
	v_add_f32_e32 v58, v58, v129
	v_mov_b32_e32 v128, v118
	v_mov_b32_e32 v129, v122
	v_pk_mul_f32 v[128:129], v[128:129], v[204:205]
	v_mov_b32_e32 v122, v119
	v_add_f32_e32 v58, v58, v128
	v_add_f32_e32 v58, v58, v129
	v_max_f32_e64 v62, -v58, 0
	v_mul_f32_e64 v58, |v58|, s93
	v_exp_f32_e32 v58, v58
	s_nop 0
	v_add_f32_e32 v58, 1.0, v58
	v_cmp_gt_f32_e32 vcc, s92, v58
	s_nop 1
	v_cndmask_b32_e64 v66, 0, 32, vcc
	v_ldexp_f32 v58, v58, v66
	v_log_f32_e32 v58, v58
	s_nop 0
	v_mul_f32_e32 v66, 0x3f317217, v58
	v_fma_f32 v66, v58, s94, -v66
	v_fmac_f32_e32 v66, 0x3377d1cf, v58
	v_fmac_f32_e32 v66, 0x3f317217, v58
	v_cmp_lt_f32_e64 s[0:1], |v58|, s95
	s_nop 1
	v_cndmask_b32_e64 v58, v58, v66, s[0:1]
	v_cndmask_b32_e32 v66, 0, v239, vcc
	v_sub_f32_e32 v58, v58, v66
	v_add_f32_e32 v58, v62, v58
	v_mul_f32_e32 v62, 0xbd800000, v58
	v_mov_b32_e32 v66, v49
	s_nop 1
	v_mov_b32_dpp v66, v62 row_shr:1 row_mask:0xf bank_mask:0xf
	v_fmac_f32_e32 v66, 0xbd800000, v58
	s_nop 1
	v_add_f32_dpp v62, v66, v66 row_shr:2 row_mask:0xf bank_mask:0xf bound_ctrl:1
	v_mov_b32_e32 v66, v49
	s_nop 0
	v_add_f32_dpp v62, v62, v62 row_shr:4 row_mask:0xf bank_mask:0xf bound_ctrl:1
	s_nop 1
	v_add_f32_dpp v62, v62, v62 row_shr:8 row_mask:0xf bank_mask:0xf bound_ctrl:1
	s_nop 1
	v_mov_b32_dpp v66, v62 row_bcast:15 row_mask:0xa bank_mask:0xf
	v_add_f32_e32 v62, v62, v66
	v_mov_b32_e32 v66, v49
	s_nop 1
	v_mov_b32_dpp v66, v62 row_bcast:31 row_mask:0xc bank_mask:0xf
	v_add_f32_e32 v62, v62, v66
	s_nop 0
	v_readlane_b32 s91, v62, 63
	s_nop 1
	v_sub_f32_e32 v66, s91, v62
	v_fmac_f32_e32 v62, 0x3d800000, v58
	v_pk_mul_f32 v[58:59], v[114:115], v[206:207]
	v_cndmask_b32_e64 v62, v62, v66, s[8:9]
	v_add_f32_e32 v58, v63, v58
	v_add_f32_e32 v63, v58, v59
	v_pk_mul_f32 v[58:59], v[122:123], v[204:205]
	v_lshlrev_b32_e32 v66, 16, v37
	v_add_f32_e32 v58, v63, v58
	v_add_f32_e32 v58, v58, v59
	v_max_f32_e64 v59, -v58, 0
	v_mul_f32_e64 v58, |v58|, s93
	v_exp_f32_e32 v58, v58
	s_nop 0
	v_add_f32_e32 v58, 1.0, v58
	v_cmp_gt_f32_e32 vcc, s92, v58
	s_nop 1
	v_cndmask_b32_e64 v63, 0, 32, vcc
	v_ldexp_f32 v58, v58, v63
	v_log_f32_e32 v58, v58
	s_nop 0
	v_mul_f32_e32 v63, 0x3f317217, v58
	v_fma_f32 v63, v58, s94, -v63
	v_fmac_f32_e32 v63, 0x3377d1cf, v58
	v_fmac_f32_e32 v63, 0x3f317217, v58
	v_cmp_lt_f32_e64 s[0:1], |v58|, s95
	s_nop 1
	v_cndmask_b32_e64 v58, v58, v63, s[0:1]
	v_cndmask_b32_e32 v63, 0, v239, vcc
	v_sub_f32_e32 v58, v58, v63
	v_add_f32_e32 v58, v59, v58
	v_mul_f32_e32 v59, 0xbd800000, v58
	v_mov_b32_e32 v63, v49
	s_nop 1
	v_mov_b32_dpp v63, v59 row_shr:1 row_mask:0xf bank_mask:0xf
	v_fmac_f32_e32 v63, 0xbd800000, v58
	s_nop 1
	v_add_f32_dpp v59, v63, v63 row_shr:2 row_mask:0xf bank_mask:0xf bound_ctrl:1
	v_mov_b32_e32 v63, v49
	s_nop 0
	v_add_f32_dpp v59, v59, v59 row_shr:4 row_mask:0xf bank_mask:0xf bound_ctrl:1
	s_nop 1
	v_add_f32_dpp v59, v59, v59 row_shr:8 row_mask:0xf bank_mask:0xf bound_ctrl:1
	s_nop 1
	v_mov_b32_dpp v63, v59 row_bcast:15 row_mask:0xa bank_mask:0xf
	v_add_f32_e32 v59, v59, v63
	v_mov_b32_e32 v63, v49
	s_nop 1
	v_mov_b32_dpp v63, v59 row_bcast:31 row_mask:0xc bank_mask:0xf
	v_add_f32_e32 v59, v59, v63
	s_nop 0
	v_readlane_b32 s20, v59, 63
	s_nop 1
	v_sub_f32_e32 v63, s20, v59
	v_fmac_f32_e32 v59, 0x3d800000, v58
	v_cndmask_b32_e64 v63, v59, v63, s[8:9]
	v_mov_b32_e32 v58, v112
	v_mov_b32_e32 v59, v116
	v_pk_mul_f32 v[58:59], v[58:59], v[206:207]
	v_mov_b32_e32 v116, v113
	v_add_f32_e32 v58, v60, v58
	v_add_f32_e32 v60, v58, v59
	v_mov_b32_e32 v58, v120
	v_mov_b32_e32 v59, v124
	v_pk_mul_f32 v[58:59], v[58:59], v[204:205]
	v_mov_b32_e32 v124, v121
	v_add_f32_e32 v58, v60, v58
	v_add_f32_e32 v58, v58, v59
	v_max_f32_e64 v59, -v58, 0
	v_mul_f32_e64 v58, |v58|, s93
	v_exp_f32_e32 v58, v58
	s_nop 0
	v_add_f32_e32 v58, 1.0, v58
	v_cmp_gt_f32_e32 vcc, s92, v58
	s_nop 1
	v_cndmask_b32_e64 v60, 0, 32, vcc
	v_ldexp_f32 v58, v58, v60
	v_log_f32_e32 v58, v58
	s_nop 0
	v_mul_f32_e32 v60, 0x3f317217, v58
	v_fma_f32 v60, v58, s94, -v60
	v_fmac_f32_e32 v60, 0x3377d1cf, v58
	v_fmac_f32_e32 v60, 0x3f317217, v58
	v_cmp_lt_f32_e64 s[0:1], |v58|, s95
	s_nop 1
	v_cndmask_b32_e64 v58, v58, v60, s[0:1]
	v_cndmask_b32_e32 v60, 0, v239, vcc
	v_sub_f32_e32 v58, v58, v60
	v_add_f32_e32 v58, v59, v58
	v_mul_f32_e32 v59, 0xbd800000, v58
	v_mov_b32_e32 v60, v49
	s_nop 1
	v_mov_b32_dpp v60, v59 row_shr:1 row_mask:0xf bank_mask:0xf
	v_fmac_f32_e32 v60, 0xbd800000, v58
	s_nop 1
	v_add_f32_dpp v59, v60, v60 row_shr:2 row_mask:0xf bank_mask:0xf bound_ctrl:1
	v_mov_b32_e32 v60, v49
	s_nop 0
	v_add_f32_dpp v59, v59, v59 row_shr:4 row_mask:0xf bank_mask:0xf bound_ctrl:1
	s_nop 1
	v_add_f32_dpp v59, v59, v59 row_shr:8 row_mask:0xf bank_mask:0xf bound_ctrl:1
	s_nop 1
	v_mov_b32_dpp v60, v59 row_bcast:15 row_mask:0xa bank_mask:0xf
	v_add_f32_e32 v59, v59, v60
	v_mov_b32_e32 v60, v49
	s_nop 1
	v_mov_b32_dpp v60, v59 row_bcast:31 row_mask:0xc bank_mask:0xf
	v_add_f32_e32 v59, v59, v60
	s_nop 0
	v_readlane_b32 s21, v59, 63
	s_nop 1
	v_sub_f32_e32 v60, s21, v59
	v_fmac_f32_e32 v59, 0x3d800000, v58
	v_cndmask_b32_e64 v60, v59, v60, s[8:9]
	v_pk_mul_f32 v[58:59], v[116:117], v[206:207]
	s_nop 0
	v_add_f32_e32 v58, v61, v58
	v_add_f32_e32 v61, v58, v59
	v_pk_mul_f32 v[58:59], v[124:125], v[204:205]
	s_nop 0
	v_add_f32_e32 v58, v61, v58
	v_add_f32_e32 v58, v58, v59
	v_max_f32_e64 v59, -v58, 0
	v_mul_f32_e64 v58, |v58|, s93
	v_exp_f32_e32 v58, v58
	s_nop 0
	v_add_f32_e32 v58, 1.0, v58
	v_cmp_gt_f32_e32 vcc, s92, v58
	s_nop 1
	v_cndmask_b32_e64 v61, 0, 32, vcc
	v_ldexp_f32 v58, v58, v61
	v_log_f32_e32 v58, v58
	s_nop 0
	v_mul_f32_e32 v61, 0x3f317217, v58
	v_fma_f32 v61, v58, s94, -v61
	v_fmac_f32_e32 v61, 0x3377d1cf, v58
	v_fmac_f32_e32 v61, 0x3f317217, v58
	v_cmp_lt_f32_e64 s[0:1], |v58|, s95
	s_nop 1
	v_cndmask_b32_e64 v58, v58, v61, s[0:1]
	v_cndmask_b32_e32 v61, 0, v239, vcc
	v_sub_f32_e32 v58, v58, v61
	v_add_f32_e32 v58, v59, v58
	v_mul_f32_e32 v59, 0xbd800000, v58
	v_mov_b32_e32 v61, v49
	v_readlane_b32 s0, v254, 0
	s_add_u32 s0, s90, s0
	v_mov_b32_dpp v61, v59 row_shr:1 row_mask:0xf bank_mask:0xf
	v_fmac_f32_e32 v61, 0xbd800000, v58
	v_readlane_b32 s1, v254, 1
	s_addc_u32 s1, s15, s1
	v_add_f32_dpp v59, v61, v61 row_shr:2 row_mask:0xf bank_mask:0xf bound_ctrl:1
	v_mov_b32_e32 v61, v49
	s_lshl_b64 s[0:1], s[0:1], 10
	v_add_f32_dpp v59, v59, v59 row_shr:4 row_mask:0xf bank_mask:0xf bound_ctrl:1
	s_nop 1
	v_add_f32_dpp v59, v59, v59 row_shr:8 row_mask:0xf bank_mask:0xf bound_ctrl:1
	s_nop 1
	v_mov_b32_dpp v61, v59 row_bcast:15 row_mask:0xa bank_mask:0xf
	v_add_f32_e32 v59, v59, v61
	v_mov_b32_e32 v61, v49
	s_nop 1
	v_mov_b32_dpp v61, v59 row_bcast:31 row_mask:0xc bank_mask:0xf
	v_add_f32_e32 v59, v59, v61
	s_nop 0
	v_readlane_b32 s18, v59, 63
	s_nop 1
	v_sub_f32_e32 v61, s18, v59
	v_fmac_f32_e32 v59, 0x3d800000, v58
	v_cndmask_b32_e64 v58, v59, v61, s[8:9]
	v_mul_f32_e32 v59, 0x3fb8aa3b, v126
	v_exp_f32_e32 v72, v59
	v_mul_f32_e32 v59, 0x3fb8aa3b, v127
	v_mul_f32_e32 v58, 0x3fb8aa3b, v58
	v_exp_f32_e32 v73, v59
	v_exp_f32_e32 v78, v58
	v_cvt_pk_bf16_f32 v58, v48, v72
	v_mul_f32_e32 v48, v48, v64
	v_mul_f32_e32 v59, 0x3fb8aa3b, v130
	v_cvt_pk_bf16_f32 v48, v48, s0
	v_exp_f32_e32 v74, v59
	ds_write_b16 v208, v48 offset:56448
	v_mul_f32_e32 v48, v72, v65
	v_mul_f32_e32 v59, 0x3fb8aa3b, v62
	v_cvt_pk_bf16_f32 v48, v48, s0
	v_exp_f32_e32 v75, v59
	ds_write_b16 v208, v48 offset:56592
	v_mul_f32_e32 v48, v73, v66
	v_mul_f32_e32 v59, 0x3fb8aa3b, v63
	v_cvt_pk_bf16_f32 v48, v48, s0
	v_exp_f32_e32 v76, v59
	ds_write_b16 v208, v48 offset:56736
	v_mul_f32_e32 v48, v74, v67
	v_mul_f32_e32 v59, 0x3fb8aa3b, v60
	v_cvt_pk_bf16_f32 v48, v48, s0
	v_exp_f32_e32 v77, v59
	ds_write_b16 v208, v48 offset:56880
	v_mul_f32_e32 v48, v75, v68
	v_cvt_pk_bf16_f32 v48, v48, s0
	ds_write_b16 v208, v48 offset:57024
	v_mul_f32_e32 v48, v76, v69
	v_cvt_pk_bf16_f32 v48, v48, s0
	ds_write_b16 v208, v48 offset:57168
	v_mul_f32_e32 v48, v77, v70
	v_cvt_pk_bf16_f32 v48, v48, s0
	ds_write_b16 v208, v48 offset:57312
	v_mul_f32_e32 v48, v78, v71
	v_cvt_pk_bf16_f32 v59, v73, v74
	v_cvt_pk_bf16_f32 v60, v75, v76
	v_cvt_pk_bf16_f32 v61, v77, v78
	v_lshl_add_u64 v[62:63], v[202:203], 0, s[0:1]
	v_cvt_pk_bf16_f32 v48, v48, s0
	global_store_dwordx4 v[62:63], v[58:61], off
	ds_write_b16 v208, v48 offset:57456
	s_and_saveexec_b64 s[0:1], s[10:11]
	s_cbranch_execz .LBB0_661
	v_mul_f32_e32 v48, s4, v240
	v_exp_f32_e32 v58, v48
	v_mul_f32_e32 v48, s5, v240
	v_exp_f32_e32 v59, v48
	v_mul_f32_e32 v48, s6, v240
	v_exp_f32_e32 v60, v48
	v_mul_f32_e32 v48, s7, v240
	v_exp_f32_e32 v61, v48
	v_mul_f32_e32 v48, s91, v240
	v_exp_f32_e32 v62, v48
	v_mul_f32_e32 v48, s20, v240
	v_exp_f32_e32 v63, v48
	v_mul_f32_e32 v48, s21, v240
	v_exp_f32_e32 v64, v48
	v_mul_f32_e32 v48, s18, v240
	v_exp_f32_e32 v65, v48
	s_add_u32 s4, s16, s88
	s_addc_u32 s5, s17, s89
	global_store_dwordx4 v49, v[58:61], s[4:5] offset:32
	global_store_dwordx4 v49, v[62:65], s[4:5] offset:48
.LBB0_661:
	s_or_b64 exec, exec, s[0:1]
	v_readlane_b32 s0, v254, 63
	v_readlane_b32 s1, v255, 0
	v_lshrrev_b32_e32 v182, 6, v198
	v_and_b32_e32 v183, 1, v182
	v_lshrrev_b32_e32 v182, 1, v182
	v_mul_u32_u24_e32 v183, 0x3000, v183
	v_lshl_add_u32 v183, v182, 7, v183
	v_lshl_add_u32 v182, v182, 6, v183
	v_add_u32_e32 v182, 0x1b000, v182
	ds_read_b128 v[58:61], v182 offset:24656
	ds_read_b128 v[126:129], v182 offset:24640
	ds_read_b128 v[62:65], v182 offset:80
	ds_read_b128 v[130:133], v182 offset:64
	ds_read_b128 v[66:69], v182 offset:848
	ds_read_b128 v[134:137], v182 offset:832
	ds_read_b128 v[70:73], v182 offset:1616
	ds_read_b128 v[138:141], v182 offset:1600
	ds_read_b128 v[74:77], v182 offset:2384
	ds_read_b128 v[142:145], v182 offset:2368
	ds_read_b128 v[78:81], v182 offset:3152
	ds_read_b128 v[146:149], v182 offset:3136
	s_waitcnt lgkmcnt(8)
	ds_read_b128 v[82:85], v182 offset:3920
	ds_read_b128 v[150:153], v182 offset:3904
	ds_read_b128 v[86:89], v182 offset:4688
	ds_read_b128 v[154:157], v182 offset:4672
	s_waitcnt lgkmcnt(8)
	v_readlane_b32 s0, v255, 1
	v_readlane_b32 s1, v255, 2
	s_nop 4
	ds_read_b128 v[90:93], v182 offset:5456
	ds_read_b128 v[158:161], v182 offset:5440
	v_readlane_b32 s0, v255, 3
	v_readlane_b32 s1, v255, 4
	s_nop 4
	ds_read_b128 v[94:97], v182 offset:6224
	ds_read_b128 v[162:165], v182 offset:6208
	s_waitcnt lgkmcnt(8)
	v_readlane_b32 s0, v255, 5
	v_readlane_b32 s1, v255, 6
	s_nop 4
	ds_read_b128 v[98:101], v182 offset:6992
	ds_read_b128 v[166:169], v182 offset:6976
	v_readlane_b32 s0, v255, 7
	v_readlane_b32 s1, v255, 8
	s_nop 4
	ds_read_b128 v[102:105], v182 offset:7760
	ds_read_b128 v[170:173], v182 offset:7744
	s_waitcnt lgkmcnt(8)
	v_readlane_b32 s0, v255, 9
	v_readlane_b32 s1, v255, 10
	s_nop 4
	ds_read_b128 v[106:109], v182 offset:8528
	ds_read_b128 v[174:177], v182 offset:8512
	v_readlane_b32 s0, v255, 11
	v_readlane_b32 s1, v255, 12
	s_nop 4
	ds_read_b128 v[110:113], v182 offset:9296
	ds_read_b128 v[178:181], v182 offset:9280
	s_waitcnt lgkmcnt(8)
	v_readlane_b32 s0, v255, 13
	v_readlane_b32 s1, v255, 14
	s_nop 4
	ds_read_b128 v[114:117], v182 offset:10064
	ds_read_b128 v[182:185], v182 offset:10048
	v_readlane_b32 s0, v255, 15
	v_readlane_b32 s1, v255, 16
	s_waitcnt lgkmcnt(14)
	v_fma_f32 v58, v62, v242, v58
	s_waitcnt lgkmcnt(14)
	v_fma_f32 v48, v130, v242, v126
	s_waitcnt lgkmcnt(14)
	v_fmac_f32_e32 v48, v134, v223
	s_waitcnt lgkmcnt(14)
	v_fmac_f32_e32 v48, v138, v222
	s_waitcnt lgkmcnt(14)
	v_fmac_f32_e32 v48, v142, v221
	s_waitcnt lgkmcnt(14)
	v_fmac_f32_e32 v48, v146, v220
	s_waitcnt lgkmcnt(14)
	v_fmac_f32_e32 v48, v150, v219
	s_waitcnt lgkmcnt(14)
	v_fmac_f32_e32 v48, v154, v218
	v_fmac_f32_e32 v129, v133, v242
	v_fmac_f32_e32 v129, v137, v223
	s_waitcnt lgkmcnt(12)
	v_fmac_f32_e32 v48, v158, v217
	v_fmac_f32_e32 v129, v141, v222
	v_fmac_f32_e32 v129, v145, v221
	s_waitcnt lgkmcnt(10)
	v_fmac_f32_e32 v48, v162, v216
	v_fmac_f32_e32 v129, v149, v220
	v_fmac_f32_e32 v129, v153, v219
	s_waitcnt lgkmcnt(8)
	v_fmac_f32_e32 v48, v166, v215
	v_fmac_f32_e32 v129, v157, v218
	v_fmac_f32_e32 v129, v161, v217
	s_waitcnt lgkmcnt(6)
	v_fmac_f32_e32 v48, v170, v214
	v_fmac_f32_e32 v129, v165, v216
	v_fmac_f32_e32 v129, v169, v215
	s_waitcnt lgkmcnt(4)
	v_fmac_f32_e32 v48, v174, v213
	v_fmac_f32_e32 v129, v173, v214
	v_fmac_f32_e32 v129, v177, v213
	s_waitcnt lgkmcnt(2)
	v_mov_b32_e32 v118, v178
	v_fmac_f32_e32 v58, v66, v223
	v_fmac_f32_e32 v58, v70, v222
	s_waitcnt lgkmcnt(0)
	v_mov_b32_e32 v119, v182
	v_pk_mul_f32 v[118:119], v[118:119], v[206:207]
	v_mov_b32_e32 v182, v179
	v_add_f32_e32 v48, v48, v118
	v_add_f32_e32 v48, v48, v119
	v_lshrrev_b32_e32 v190, 6, v198
	v_and_b32_e32 v191, 1, v190
	v_lshrrev_b32_e32 v190, 1, v190
	v_mul_u32_u24_e32 v191, 0x3000, v191
	v_lshl_add_u32 v191, v190, 7, v191
	v_lshl_add_u32 v190, v190, 6, v191
	v_add_u32_e32 v190, 0x1b000, v190
	ds_read_b128 v[118:121], v190 offset:10832
	ds_read_b128 v[186:189], v190 offset:10816
	v_readlane_b32 s0, v255, 17
	v_readlane_b32 s1, v255, 18
	s_nop 4
	ds_read_b128 v[122:125], v190 offset:11600
	ds_read_b128 v[190:193], v190 offset:11584
	v_fmac_f32_e32 v58, v74, v221
	v_fmac_f32_e32 v58, v78, v220
	v_fmac_f32_e32 v58, v82, v219
	v_fmac_f32_e32 v58, v86, v218
	v_fmac_f32_e32 v58, v90, v217
	v_fmac_f32_e32 v58, v94, v216
	v_fmac_f32_e32 v58, v98, v215
	v_fmac_f32_e32 v58, v102, v214
	v_fmac_f32_e32 v58, v106, v213
	v_fma_f32 v63, v63, v242, v59
	v_fmac_f32_e32 v63, v67, v223
	v_fmac_f32_e32 v63, v71, v222
	v_fmac_f32_e32 v63, v75, v221
	v_fmac_f32_e32 v63, v79, v220
	v_fmac_f32_e32 v63, v83, v219
	v_fmac_f32_e32 v63, v87, v218
	v_fmac_f32_e32 v63, v91, v217
	v_fmac_f32_e32 v63, v95, v216
	v_fmac_f32_e32 v63, v99, v215
	v_fmac_f32_e32 v63, v103, v214
	v_fmac_f32_e32 v63, v107, v213
	v_fma_f32 v60, v64, v242, v60
	v_fmac_f32_e32 v60, v68, v223
	v_fmac_f32_e32 v60, v72, v222
	v_fmac_f32_e32 v60, v76, v221
	v_fmac_f32_e32 v60, v80, v220
	v_fmac_f32_e32 v60, v84, v219
	v_fmac_f32_e32 v60, v88, v218
	v_fmac_f32_e32 v60, v92, v217
	v_fmac_f32_e32 v60, v96, v216
	v_fmac_f32_e32 v60, v100, v215
	v_fmac_f32_e32 v60, v104, v214
	v_fmac_f32_e32 v60, v108, v213
	v_fmac_f32_e32 v61, v65, v242
	v_fmac_f32_e32 v61, v69, v223
	v_fmac_f32_e32 v61, v73, v222
	v_fmac_f32_e32 v61, v77, v221
	v_fmac_f32_e32 v61, v81, v220
	v_fmac_f32_e32 v61, v85, v219
	v_fmac_f32_e32 v61, v89, v218
	v_fmac_f32_e32 v61, v93, v217
	v_fmac_f32_e32 v61, v97, v216
	v_fmac_f32_e32 v61, v101, v215
	v_fmac_f32_e32 v61, v105, v214
	v_fmac_f32_e32 v61, v109, v213
	v_lshlrev_b32_e32 v64, 16, v40
	v_and_b32_e32 v65, 0xffff0000, v40
	v_and_b32_e32 v67, 0xffff0000, v41
	v_lshlrev_b32_e32 v68, 16, v42
	v_and_b32_e32 v69, 0xffff0000, v42
	v_lshlrev_b32_e32 v70, 16, v43
	v_and_b32_e32 v71, 0xffff0000, v43
	s_waitcnt lgkmcnt(2)
	v_mov_b32_e32 v244, v186
	s_waitcnt lgkmcnt(0)
	v_mov_b32_e32 v245, v190
	v_pk_mul_f32 v[244:245], v[244:245], v[204:205]
	v_mov_b32_e32 v190, v187
	v_add_f32_e32 v48, v48, v244
	v_add_f32_e32 v48, v48, v245
	v_max_f32_e64 v126, -v48, 0
	v_mul_f32_e64 v48, |v48|, s93
	v_exp_f32_e32 v48, v48
	s_nop 0
	v_add_f32_e32 v48, 1.0, v48
	v_cmp_gt_f32_e32 vcc, s92, v48
	s_nop 1
	v_cndmask_b32_e64 v130, 0, 32, vcc
	v_ldexp_f32 v48, v48, v130
	v_log_f32_e32 v48, v48
	s_nop 0
	v_mul_f32_e32 v130, 0x3f317217, v48
	v_fma_f32 v130, v48, s94, -v130
	v_fmac_f32_e32 v130, 0x3377d1cf, v48
	v_fmac_f32_e32 v130, 0x3f317217, v48
	v_cmp_lt_f32_e64 s[0:1], |v48|, s95
	s_nop 1
	v_cndmask_b32_e64 v48, v48, v130, s[0:1]
	v_cndmask_b32_e32 v130, 0, v239, vcc
	v_sub_f32_e32 v48, v48, v130
	v_add_f32_e32 v48, v126, v48
	v_mul_f32_e32 v126, 0xbd800000, v48
	v_mov_b32_e32 v130, v49
	s_nop 1
	v_mov_b32_dpp v130, v126 row_shr:1 row_mask:0xf bank_mask:0xf
	v_fmac_f32_e32 v130, 0xbd800000, v48
	s_nop 1
	v_add_f32_dpp v126, v130, v130 row_shr:2 row_mask:0xf bank_mask:0xf bound_ctrl:1
	v_mov_b32_e32 v130, v49
	s_nop 0
	v_add_f32_dpp v126, v126, v126 row_shr:4 row_mask:0xf bank_mask:0xf bound_ctrl:1
	s_nop 1
	v_add_f32_dpp v126, v126, v126 row_shr:8 row_mask:0xf bank_mask:0xf bound_ctrl:1
	s_nop 1
	v_mov_b32_dpp v130, v126 row_bcast:15 row_mask:0xa bank_mask:0xf
	v_add_f32_e32 v126, v126, v130
	v_mov_b32_e32 v130, v49
	s_nop 1
	v_mov_b32_dpp v130, v126 row_bcast:31 row_mask:0xc bank_mask:0xf
	v_add_f32_e32 v126, v126, v130
	s_nop 0
	v_readlane_b32 s4, v126, 63
	s_nop 1
	v_sub_f32_e32 v130, s4, v126
	v_fmac_f32_e32 v126, 0x3d800000, v48
	v_cndmask_b32_e64 v48, v126, v130, s[8:9]
	v_fma_f32 v130, v131, v242, v127
	v_fmac_f32_e32 v130, v135, v223
	v_fmac_f32_e32 v130, v139, v222
	v_fmac_f32_e32 v130, v143, v221
	v_fmac_f32_e32 v130, v147, v220
	v_fmac_f32_e32 v130, v151, v219
	v_fmac_f32_e32 v130, v155, v218
	v_fmac_f32_e32 v130, v159, v217
	v_fmac_f32_e32 v130, v163, v216
	v_fmac_f32_e32 v130, v167, v215
	v_fmac_f32_e32 v130, v171, v214
	v_fmac_f32_e32 v130, v175, v213
	v_pk_mul_f32 v[126:127], v[182:183], v[206:207]
	v_mov_b32_e32 v131, v184
	v_add_f32_e32 v126, v130, v126
	v_add_f32_e32 v130, v126, v127
	v_pk_mul_f32 v[126:127], v[190:191], v[204:205]
	v_mov_b32_e32 v184, v181
	v_add_f32_e32 v126, v130, v126
	v_add_f32_e32 v126, v126, v127
	v_max_f32_e64 v127, -v126, 0
	v_mul_f32_e64 v126, |v126|, s93
	v_exp_f32_e32 v126, v126
	v_mul_f32_e32 v48, 0x3fb8aa3b, v48
	v_exp_f32_e32 v48, v48
	v_add_f32_e32 v126, 1.0, v126
	v_cmp_gt_f32_e32 vcc, s92, v126
	s_nop 1
	v_cndmask_b32_e64 v130, 0, 32, vcc
	v_ldexp_f32 v126, v126, v130
	v_log_f32_e32 v126, v126
	s_nop 0
	v_mul_f32_e32 v130, 0x3f317217, v126
	v_fma_f32 v130, v126, s94, -v130
	v_fmac_f32_e32 v130, 0x3377d1cf, v126
	v_fmac_f32_e32 v130, 0x3f317217, v126
	v_cmp_lt_f32_e64 s[0:1], |v126|, s95
	s_nop 1
	v_cndmask_b32_e64 v126, v126, v130, s[0:1]
	v_cndmask_b32_e32 v130, 0, v239, vcc
	v_sub_f32_e32 v126, v126, v130
	v_add_f32_e32 v126, v127, v126
	v_mul_f32_e32 v127, 0xbd800000, v126
	v_mov_b32_e32 v130, v49
	s_nop 1
	v_mov_b32_dpp v130, v127 row_shr:1 row_mask:0xf bank_mask:0xf
	v_fmac_f32_e32 v130, 0xbd800000, v126
	s_nop 1
	v_add_f32_dpp v127, v130, v130 row_shr:2 row_mask:0xf bank_mask:0xf bound_ctrl:1
	v_mov_b32_e32 v130, v49
	s_nop 0
	v_add_f32_dpp v127, v127, v127 row_shr:4 row_mask:0xf bank_mask:0xf bound_ctrl:1
	s_nop 1
	v_add_f32_dpp v127, v127, v127 row_shr:8 row_mask:0xf bank_mask:0xf bound_ctrl:1
	s_nop 1
	v_mov_b32_dpp v130, v127 row_bcast:15 row_mask:0xa bank_mask:0xf
	v_add_f32_e32 v127, v127, v130
	v_mov_b32_e32 v130, v49
	s_nop 1
	v_mov_b32_dpp v130, v127 row_bcast:31 row_mask:0xc bank_mask:0xf
	v_add_f32_e32 v127, v127, v130
	s_nop 0
	v_readlane_b32 s5, v127, 63
	s_nop 1
	v_sub_f32_e32 v130, s5, v127
	v_fmac_f32_e32 v127, 0x3d800000, v126
	v_cndmask_b32_e64 v126, v127, v130, s[8:9]
	v_fma_f32 v127, v132, v242, v128
	v_fmac_f32_e32 v127, v136, v223
	v_fmac_f32_e32 v127, v140, v222
	v_fmac_f32_e32 v127, v144, v221
	v_fmac_f32_e32 v127, v148, v220
	v_fmac_f32_e32 v127, v152, v219
	v_fmac_f32_e32 v127, v156, v218
	v_fmac_f32_e32 v127, v160, v217
	v_fmac_f32_e32 v127, v164, v216
	v_fmac_f32_e32 v127, v168, v215
	v_fmac_f32_e32 v127, v172, v214
	v_mov_b32_e32 v130, v180
	v_fmac_f32_e32 v127, v176, v213
	v_pk_mul_f32 v[130:131], v[130:131], v[206:207]
	s_nop 0
	v_add_f32_e32 v127, v127, v130
	v_add_f32_e32 v127, v127, v131
	v_mov_b32_e32 v130, v188
	v_mov_b32_e32 v131, v192
	v_pk_mul_f32 v[130:131], v[130:131], v[204:205]
	v_mov_b32_e32 v192, v189
	v_add_f32_e32 v127, v127, v130
	v_add_f32_e32 v127, v127, v131
	v_max_f32_e64 v128, -v127, 0
	v_mul_f32_e64 v127, |v127|, s93
	v_exp_f32_e32 v127, v127
	s_nop 0
	v_add_f32_e32 v127, 1.0, v127
	v_cmp_gt_f32_e32 vcc, s92, v127
	s_nop 1
	v_cndmask_b32_e64 v130, 0, 32, vcc
	v_ldexp_f32 v127, v127, v130
	v_log_f32_e32 v127, v127
	s_nop 0
	v_mul_f32_e32 v130, 0x3f317217, v127
	v_fma_f32 v130, v127, s94, -v130
	v_fmac_f32_e32 v130, 0x3377d1cf, v127
	v_fmac_f32_e32 v130, 0x3f317217, v127
	v_cmp_lt_f32_e64 s[0:1], |v127|, s95
	s_nop 1
	v_cndmask_b32_e64 v127, v127, v130, s[0:1]
	v_cndmask_b32_e32 v130, 0, v239, vcc
	v_sub_f32_e32 v127, v127, v130
	v_add_f32_e32 v127, v128, v127
	v_mul_f32_e32 v128, 0xbd800000, v127
	v_mov_b32_e32 v130, v49
	s_nop 1
	v_mov_b32_dpp v130, v128 row_shr:1 row_mask:0xf bank_mask:0xf
	v_fmac_f32_e32 v130, 0xbd800000, v127
	s_nop 1
	v_add_f32_dpp v128, v130, v130 row_shr:2 row_mask:0xf bank_mask:0xf bound_ctrl:1
	v_mov_b32_e32 v130, v49
	s_nop 0
	v_add_f32_dpp v128, v128, v128 row_shr:4 row_mask:0xf bank_mask:0xf bound_ctrl:1
	s_nop 1
	v_add_f32_dpp v128, v128, v128 row_shr:8 row_mask:0xf bank_mask:0xf bound_ctrl:1
	s_nop 1
	v_mov_b32_dpp v130, v128 row_bcast:15 row_mask:0xa bank_mask:0xf
	v_add_f32_e32 v128, v128, v130
	v_mov_b32_e32 v130, v49
	s_nop 1
	v_mov_b32_dpp v130, v128 row_bcast:31 row_mask:0xc bank_mask:0xf
	v_add_f32_e32 v128, v128, v130
	s_nop 0
	v_readlane_b32 s6, v128, 63
	s_nop 1
	v_sub_f32_e32 v130, s6, v128
	v_fmac_f32_e32 v128, 0x3d800000, v127
	v_cndmask_b32_e64 v127, v128, v130, s[8:9]
	v_pk_mul_f32 v[130:131], v[184:185], v[206:207]
	s_nop 0
	v_add_f32_e32 v128, v129, v130
	v_add_f32_e32 v130, v128, v131
	v_pk_mul_f32 v[128:129], v[192:193], v[204:205]
	s_nop 0
	v_add_f32_e32 v128, v130, v128
	v_add_f32_e32 v128, v128, v129
	v_max_f32_e64 v129, -v128, 0
	v_mul_f32_e64 v128, |v128|, s93
	v_exp_f32_e32 v128, v128
	s_nop 0
	v_add_f32_e32 v128, 1.0, v128
	v_cmp_gt_f32_e32 vcc, s92, v128
	s_nop 1
	v_cndmask_b32_e64 v130, 0, 32, vcc
	v_ldexp_f32 v128, v128, v130
	v_log_f32_e32 v128, v128
	s_nop 0
	v_mul_f32_e32 v130, 0x3f317217, v128
	v_fma_f32 v130, v128, s94, -v130
	v_fmac_f32_e32 v130, 0x3377d1cf, v128
	v_fmac_f32_e32 v130, 0x3f317217, v128
	v_cmp_lt_f32_e64 s[0:1], |v128|, s95
	s_nop 1
	v_cndmask_b32_e64 v128, v128, v130, s[0:1]
	v_cndmask_b32_e32 v130, 0, v239, vcc
	v_sub_f32_e32 v128, v128, v130
	v_add_f32_e32 v128, v129, v128
	v_mul_f32_e32 v129, 0xbd800000, v128
	v_mov_b32_e32 v130, v49
	s_nop 1
	v_mov_b32_dpp v130, v129 row_shr:1 row_mask:0xf bank_mask:0xf
	v_fmac_f32_e32 v130, 0xbd800000, v128
	s_nop 1
	v_add_f32_dpp v129, v130, v130 row_shr:2 row_mask:0xf bank_mask:0xf bound_ctrl:1
	v_mov_b32_e32 v130, v49
	s_nop 0
	v_add_f32_dpp v129, v129, v129 row_shr:4 row_mask:0xf bank_mask:0xf bound_ctrl:1
	s_nop 1
	v_add_f32_dpp v129, v129, v129 row_shr:8 row_mask:0xf bank_mask:0xf bound_ctrl:1
	s_nop 1
	v_mov_b32_dpp v130, v129 row_bcast:15 row_mask:0xa bank_mask:0xf
	v_add_f32_e32 v129, v129, v130
	v_mov_b32_e32 v130, v49
	s_nop 1
	v_mov_b32_dpp v130, v129 row_bcast:31 row_mask:0xc bank_mask:0xf
	v_add_f32_e32 v129, v129, v130
	s_nop 0
	v_readlane_b32 s7, v129, 63
	s_nop 1
	v_sub_f32_e32 v130, s7, v129
	v_fmac_f32_e32 v129, 0x3d800000, v128
	v_cndmask_b32_e64 v130, v129, v130, s[8:9]
	v_mov_b32_e32 v128, v110
	v_mov_b32_e32 v129, v114
	v_pk_mul_f32 v[128:129], v[128:129], v[206:207]
	v_mov_b32_e32 v114, v111
	v_add_f32_e32 v58, v58, v128
	v_add_f32_e32 v58, v58, v129
	v_mov_b32_e32 v128, v118
	v_mov_b32_e32 v129, v122
	v_pk_mul_f32 v[128:129], v[128:129], v[204:205]
	v_mov_b32_e32 v122, v119
	v_add_f32_e32 v58, v58, v128
	v_add_f32_e32 v58, v58, v129
	v_max_f32_e64 v62, -v58, 0
	v_mul_f32_e64 v58, |v58|, s93
	v_exp_f32_e32 v58, v58
	s_nop 0
	v_add_f32_e32 v58, 1.0, v58
	v_cmp_gt_f32_e32 vcc, s92, v58
	s_nop 1
	v_cndmask_b32_e64 v66, 0, 32, vcc
	v_ldexp_f32 v58, v58, v66
	v_log_f32_e32 v58, v58
	s_nop 0
	v_mul_f32_e32 v66, 0x3f317217, v58
	v_fma_f32 v66, v58, s94, -v66
	v_fmac_f32_e32 v66, 0x3377d1cf, v58
	v_fmac_f32_e32 v66, 0x3f317217, v58
	v_cmp_lt_f32_e64 s[0:1], |v58|, s95
	s_nop 1
	v_cndmask_b32_e64 v58, v58, v66, s[0:1]
	v_cndmask_b32_e32 v66, 0, v239, vcc
	v_sub_f32_e32 v58, v58, v66
	v_add_f32_e32 v58, v62, v58
	v_mul_f32_e32 v62, 0xbd800000, v58
	v_mov_b32_e32 v66, v49
	s_nop 1
	v_mov_b32_dpp v66, v62 row_shr:1 row_mask:0xf bank_mask:0xf
	v_fmac_f32_e32 v66, 0xbd800000, v58
	s_nop 1
	v_add_f32_dpp v62, v66, v66 row_shr:2 row_mask:0xf bank_mask:0xf bound_ctrl:1
	v_mov_b32_e32 v66, v49
	s_nop 0
	v_add_f32_dpp v62, v62, v62 row_shr:4 row_mask:0xf bank_mask:0xf bound_ctrl:1
	s_nop 1
	v_add_f32_dpp v62, v62, v62 row_shr:8 row_mask:0xf bank_mask:0xf bound_ctrl:1
	s_nop 1
	v_mov_b32_dpp v66, v62 row_bcast:15 row_mask:0xa bank_mask:0xf
	v_add_f32_e32 v62, v62, v66
	v_mov_b32_e32 v66, v49
	s_nop 1
	v_mov_b32_dpp v66, v62 row_bcast:31 row_mask:0xc bank_mask:0xf
	v_add_f32_e32 v62, v62, v66
	s_nop 0
	v_readlane_b32 s91, v62, 63
	s_nop 1
	v_sub_f32_e32 v66, s91, v62
	v_fmac_f32_e32 v62, 0x3d800000, v58
	v_pk_mul_f32 v[58:59], v[114:115], v[206:207]
	v_cndmask_b32_e64 v62, v62, v66, s[8:9]
	v_add_f32_e32 v58, v63, v58
	v_add_f32_e32 v63, v58, v59
	v_pk_mul_f32 v[58:59], v[122:123], v[204:205]
	v_lshlrev_b32_e32 v66, 16, v41
	v_add_f32_e32 v58, v63, v58
	v_add_f32_e32 v58, v58, v59
	v_max_f32_e64 v59, -v58, 0
	v_mul_f32_e64 v58, |v58|, s93
	v_exp_f32_e32 v58, v58
	s_nop 0
	v_add_f32_e32 v58, 1.0, v58
	v_cmp_gt_f32_e32 vcc, s92, v58
	s_nop 1
	v_cndmask_b32_e64 v63, 0, 32, vcc
	v_ldexp_f32 v58, v58, v63
	v_log_f32_e32 v58, v58
	s_nop 0
	v_mul_f32_e32 v63, 0x3f317217, v58
	v_fma_f32 v63, v58, s94, -v63
	v_fmac_f32_e32 v63, 0x3377d1cf, v58
	v_fmac_f32_e32 v63, 0x3f317217, v58
	v_cmp_lt_f32_e64 s[0:1], |v58|, s95
	s_nop 1
	v_cndmask_b32_e64 v58, v58, v63, s[0:1]
	v_cndmask_b32_e32 v63, 0, v239, vcc
	v_sub_f32_e32 v58, v58, v63
	v_add_f32_e32 v58, v59, v58
	v_mul_f32_e32 v59, 0xbd800000, v58
	v_mov_b32_e32 v63, v49
	s_nop 1
	v_mov_b32_dpp v63, v59 row_shr:1 row_mask:0xf bank_mask:0xf
	v_fmac_f32_e32 v63, 0xbd800000, v58
	s_nop 1
	v_add_f32_dpp v59, v63, v63 row_shr:2 row_mask:0xf bank_mask:0xf bound_ctrl:1
	v_mov_b32_e32 v63, v49
	s_nop 0
	v_add_f32_dpp v59, v59, v59 row_shr:4 row_mask:0xf bank_mask:0xf bound_ctrl:1
	s_nop 1
	v_add_f32_dpp v59, v59, v59 row_shr:8 row_mask:0xf bank_mask:0xf bound_ctrl:1
	s_nop 1
	v_mov_b32_dpp v63, v59 row_bcast:15 row_mask:0xa bank_mask:0xf
	v_add_f32_e32 v59, v59, v63
	v_mov_b32_e32 v63, v49
	s_nop 1
	v_mov_b32_dpp v63, v59 row_bcast:31 row_mask:0xc bank_mask:0xf
	v_add_f32_e32 v59, v59, v63
	s_nop 0
	v_readlane_b32 s20, v59, 63
	s_nop 1
	v_sub_f32_e32 v63, s20, v59
	v_fmac_f32_e32 v59, 0x3d800000, v58
	v_cndmask_b32_e64 v63, v59, v63, s[8:9]
	v_mov_b32_e32 v58, v112
	v_mov_b32_e32 v59, v116
	v_pk_mul_f32 v[58:59], v[58:59], v[206:207]
	v_mov_b32_e32 v116, v113
	v_add_f32_e32 v58, v60, v58
	v_add_f32_e32 v60, v58, v59
	v_mov_b32_e32 v58, v120
	v_mov_b32_e32 v59, v124
	v_pk_mul_f32 v[58:59], v[58:59], v[204:205]
	v_mov_b32_e32 v124, v121
	v_add_f32_e32 v58, v60, v58
	v_add_f32_e32 v58, v58, v59
	v_max_f32_e64 v59, -v58, 0
	v_mul_f32_e64 v58, |v58|, s93
	v_exp_f32_e32 v58, v58
	s_nop 0
	v_add_f32_e32 v58, 1.0, v58
	v_cmp_gt_f32_e32 vcc, s92, v58
	s_nop 1
	v_cndmask_b32_e64 v60, 0, 32, vcc
	v_ldexp_f32 v58, v58, v60
	v_log_f32_e32 v58, v58
	s_nop 0
	v_mul_f32_e32 v60, 0x3f317217, v58
	v_fma_f32 v60, v58, s94, -v60
	v_fmac_f32_e32 v60, 0x3377d1cf, v58
	v_fmac_f32_e32 v60, 0x3f317217, v58
	v_cmp_lt_f32_e64 s[0:1], |v58|, s95
	s_nop 1
	v_cndmask_b32_e64 v58, v58, v60, s[0:1]
	v_cndmask_b32_e32 v60, 0, v239, vcc
	v_sub_f32_e32 v58, v58, v60
	v_add_f32_e32 v58, v59, v58
	v_mul_f32_e32 v59, 0xbd800000, v58
	v_mov_b32_e32 v60, v49
	s_nop 1
	v_mov_b32_dpp v60, v59 row_shr:1 row_mask:0xf bank_mask:0xf
	v_fmac_f32_e32 v60, 0xbd800000, v58
	s_nop 1
	v_add_f32_dpp v59, v60, v60 row_shr:2 row_mask:0xf bank_mask:0xf bound_ctrl:1
	v_mov_b32_e32 v60, v49
	s_nop 0
	v_add_f32_dpp v59, v59, v59 row_shr:4 row_mask:0xf bank_mask:0xf bound_ctrl:1
	s_nop 1
	v_add_f32_dpp v59, v59, v59 row_shr:8 row_mask:0xf bank_mask:0xf bound_ctrl:1
	s_nop 1
	v_mov_b32_dpp v60, v59 row_bcast:15 row_mask:0xa bank_mask:0xf
	v_add_f32_e32 v59, v59, v60
	v_mov_b32_e32 v60, v49
	s_nop 1
	v_mov_b32_dpp v60, v59 row_bcast:31 row_mask:0xc bank_mask:0xf
	v_add_f32_e32 v59, v59, v60
	s_nop 0
	v_readlane_b32 s21, v59, 63
	s_nop 1
	v_sub_f32_e32 v60, s21, v59
	v_fmac_f32_e32 v59, 0x3d800000, v58
	v_cndmask_b32_e64 v60, v59, v60, s[8:9]
	v_pk_mul_f32 v[58:59], v[116:117], v[206:207]
	s_nop 0
	v_add_f32_e32 v58, v61, v58
	v_add_f32_e32 v61, v58, v59
	v_pk_mul_f32 v[58:59], v[124:125], v[204:205]
	s_nop 0
	v_add_f32_e32 v58, v61, v58
	v_add_f32_e32 v58, v58, v59
	v_max_f32_e64 v59, -v58, 0
	v_mul_f32_e64 v58, |v58|, s93
	v_exp_f32_e32 v58, v58
	s_nop 0
	v_add_f32_e32 v58, 1.0, v58
	v_cmp_gt_f32_e32 vcc, s92, v58
	s_nop 1
	v_cndmask_b32_e64 v61, 0, 32, vcc
	v_ldexp_f32 v58, v58, v61
	v_log_f32_e32 v58, v58
	s_nop 0
	v_mul_f32_e32 v61, 0x3f317217, v58
	v_fma_f32 v61, v58, s94, -v61
	v_fmac_f32_e32 v61, 0x3377d1cf, v58
	v_fmac_f32_e32 v61, 0x3f317217, v58
	v_cmp_lt_f32_e64 s[0:1], |v58|, s95
	s_nop 1
	v_cndmask_b32_e64 v58, v58, v61, s[0:1]
	v_cndmask_b32_e32 v61, 0, v239, vcc
	v_sub_f32_e32 v58, v58, v61
	v_add_f32_e32 v58, v59, v58
	v_mul_f32_e32 v59, 0xbd800000, v58
	v_mov_b32_e32 v61, v49
	v_readlane_b32 s0, v254, 2
	s_add_u32 s0, s90, s0
	v_mov_b32_dpp v61, v59 row_shr:1 row_mask:0xf bank_mask:0xf
	v_fmac_f32_e32 v61, 0xbd800000, v58
	v_readlane_b32 s1, v254, 4
	s_addc_u32 s1, s15, s1
	v_add_f32_dpp v59, v61, v61 row_shr:2 row_mask:0xf bank_mask:0xf bound_ctrl:1
	v_mov_b32_e32 v61, v49
	s_lshl_b64 s[0:1], s[0:1], 10
	v_add_f32_dpp v59, v59, v59 row_shr:4 row_mask:0xf bank_mask:0xf bound_ctrl:1
	s_nop 1
	v_add_f32_dpp v59, v59, v59 row_shr:8 row_mask:0xf bank_mask:0xf bound_ctrl:1
	s_nop 1
	v_mov_b32_dpp v61, v59 row_bcast:15 row_mask:0xa bank_mask:0xf
	v_add_f32_e32 v59, v59, v61
	v_mov_b32_e32 v61, v49
	s_nop 1
	v_mov_b32_dpp v61, v59 row_bcast:31 row_mask:0xc bank_mask:0xf
	v_add_f32_e32 v59, v59, v61
	s_nop 0
	v_readlane_b32 s18, v59, 63
	s_nop 1
	v_sub_f32_e32 v61, s18, v59
	v_fmac_f32_e32 v59, 0x3d800000, v58
	v_cndmask_b32_e64 v58, v59, v61, s[8:9]
	v_mul_f32_e32 v59, 0x3fb8aa3b, v126
	v_exp_f32_e32 v72, v59
	v_mul_f32_e32 v59, 0x3fb8aa3b, v127
	v_mul_f32_e32 v58, 0x3fb8aa3b, v58
	v_exp_f32_e32 v73, v59
	v_exp_f32_e32 v78, v58
	v_cvt_pk_bf16_f32 v58, v48, v72
	v_mul_f32_e32 v48, v48, v64
	v_mul_f32_e32 v59, 0x3fb8aa3b, v130
	v_cvt_pk_bf16_f32 v48, v48, s0
	v_exp_f32_e32 v74, v59
	ds_write_b16 v208, v48 offset:57600
	v_mul_f32_e32 v48, v72, v65
	v_mul_f32_e32 v59, 0x3fb8aa3b, v62
	v_cvt_pk_bf16_f32 v48, v48, s0
	v_exp_f32_e32 v75, v59
	ds_write_b16 v208, v48 offset:57744
	v_mul_f32_e32 v48, v73, v66
	v_mul_f32_e32 v59, 0x3fb8aa3b, v63
	v_cvt_pk_bf16_f32 v48, v48, s0
	v_exp_f32_e32 v76, v59
	ds_write_b16 v208, v48 offset:57888
	v_mul_f32_e32 v48, v74, v67
	v_mul_f32_e32 v59, 0x3fb8aa3b, v60
	v_cvt_pk_bf16_f32 v48, v48, s0
	v_exp_f32_e32 v77, v59
	ds_write_b16 v208, v48 offset:58032
	v_mul_f32_e32 v48, v75, v68
	v_cvt_pk_bf16_f32 v48, v48, s0
	ds_write_b16 v208, v48 offset:58176
	v_mul_f32_e32 v48, v76, v69
	v_cvt_pk_bf16_f32 v48, v48, s0
	ds_write_b16 v208, v48 offset:58320
	v_mul_f32_e32 v48, v77, v70
	v_cvt_pk_bf16_f32 v48, v48, s0
	ds_write_b16 v208, v48 offset:58464
	v_mul_f32_e32 v48, v78, v71
	v_cvt_pk_bf16_f32 v59, v73, v74
	v_cvt_pk_bf16_f32 v60, v75, v76
	v_cvt_pk_bf16_f32 v61, v77, v78
	v_lshl_add_u64 v[62:63], v[202:203], 0, s[0:1]
	v_cvt_pk_bf16_f32 v48, v48, s0
	global_store_dwordx4 v[62:63], v[58:61], off
	ds_write_b16 v208, v48 offset:58608
	s_and_saveexec_b64 s[0:1], s[10:11]
	s_cbranch_execz .LBB0_663
	v_mul_f32_e32 v48, s4, v240
	v_exp_f32_e32 v58, v48
	v_mul_f32_e32 v48, s5, v240
	v_exp_f32_e32 v59, v48
	v_mul_f32_e32 v48, s6, v240
	v_exp_f32_e32 v60, v48
	v_mul_f32_e32 v48, s7, v240
	v_exp_f32_e32 v61, v48
	v_mul_f32_e32 v48, s91, v240
	v_exp_f32_e32 v62, v48
	v_mul_f32_e32 v48, s20, v240
	v_exp_f32_e32 v63, v48
	v_mul_f32_e32 v48, s21, v240
	v_exp_f32_e32 v64, v48
	v_mul_f32_e32 v48, s18, v240
	v_exp_f32_e32 v65, v48
	s_add_u32 s4, s16, s88
	s_addc_u32 s5, s17, s89
	global_store_dwordx4 v49, v[58:61], s[4:5] offset:64
	global_store_dwordx4 v49, v[62:65], s[4:5] offset:80
.LBB0_663:
	s_or_b64 exec, exec, s[0:1]
	v_readlane_b32 s0, v255, 19
	v_readlane_b32 s1, v255, 20
	v_lshrrev_b32_e32 v182, 6, v198
	v_and_b32_e32 v183, 1, v182
	v_lshrrev_b32_e32 v182, 1, v182
	v_mul_u32_u24_e32 v183, 0x3000, v183
	v_lshl_add_u32 v183, v182, 7, v183
	v_lshl_add_u32 v182, v182, 6, v183
	v_add_u32_e32 v182, 0x1b000, v182
	ds_read_b128 v[58:61], v182 offset:24688
	ds_read_b128 v[126:129], v182 offset:24672
	ds_read_b128 v[62:65], v182 offset:112
	ds_read_b128 v[130:133], v182 offset:96
	ds_read_b128 v[66:69], v182 offset:880
	ds_read_b128 v[134:137], v182 offset:864
	ds_read_b128 v[70:73], v182 offset:1648
	ds_read_b128 v[138:141], v182 offset:1632
	ds_read_b128 v[74:77], v182 offset:2416
	ds_read_b128 v[142:145], v182 offset:2400
	ds_read_b128 v[78:81], v182 offset:3184
	ds_read_b128 v[146:149], v182 offset:3168
	s_waitcnt lgkmcnt(8)
	ds_read_b128 v[82:85], v182 offset:3952
	ds_read_b128 v[150:153], v182 offset:3936
	ds_read_b128 v[86:89], v182 offset:4720
	ds_read_b128 v[154:157], v182 offset:4704
	s_waitcnt lgkmcnt(8)
	v_readlane_b32 s0, v255, 21
	v_readlane_b32 s1, v255, 22
	s_nop 4
	ds_read_b128 v[90:93], v182 offset:5488
	ds_read_b128 v[158:161], v182 offset:5472
	v_readlane_b32 s0, v255, 23
	v_readlane_b32 s1, v255, 24
	s_nop 4
	ds_read_b128 v[94:97], v182 offset:6256
	ds_read_b128 v[162:165], v182 offset:6240
	s_waitcnt lgkmcnt(8)
	v_readlane_b32 s0, v255, 25
	v_readlane_b32 s1, v255, 26
	s_nop 4
	ds_read_b128 v[98:101], v182 offset:7024
	ds_read_b128 v[166:169], v182 offset:7008
	v_readlane_b32 s0, v255, 27
	v_readlane_b32 s1, v255, 28
	s_nop 4
	ds_read_b128 v[102:105], v182 offset:7792
	ds_read_b128 v[170:173], v182 offset:7776
	s_waitcnt lgkmcnt(8)
	v_readlane_b32 s0, v255, 29
	v_readlane_b32 s1, v255, 30
	s_nop 4
	ds_read_b128 v[106:109], v182 offset:8560
	ds_read_b128 v[174:177], v182 offset:8544
	v_readlane_b32 s0, v255, 31
	v_readlane_b32 s1, v255, 32
	s_nop 4
	ds_read_b128 v[110:113], v182 offset:9328
	ds_read_b128 v[178:181], v182 offset:9312
	s_waitcnt lgkmcnt(8)
	v_readlane_b32 s0, v255, 33
	v_readlane_b32 s1, v255, 34
	s_nop 4
	ds_read_b128 v[114:117], v182 offset:10096
	ds_read_b128 v[182:185], v182 offset:10080
	v_readlane_b32 s0, v255, 35
	v_readlane_b32 s1, v255, 36
	s_waitcnt lgkmcnt(14)
	v_fma_f32 v58, v62, v242, v58
	s_waitcnt lgkmcnt(14)
	v_fma_f32 v48, v130, v242, v126
	s_waitcnt lgkmcnt(14)
	v_fmac_f32_e32 v48, v134, v223
	s_waitcnt lgkmcnt(14)
	v_fmac_f32_e32 v48, v138, v222
	s_waitcnt lgkmcnt(14)
	v_fmac_f32_e32 v48, v142, v221
	s_waitcnt lgkmcnt(14)
	v_fmac_f32_e32 v48, v146, v220
	s_waitcnt lgkmcnt(14)
	v_fmac_f32_e32 v48, v150, v219
	s_waitcnt lgkmcnt(14)
	v_fmac_f32_e32 v48, v154, v218
	v_fmac_f32_e32 v129, v133, v242
	v_fmac_f32_e32 v129, v137, v223
	s_waitcnt lgkmcnt(12)
	v_fmac_f32_e32 v48, v158, v217
	v_fmac_f32_e32 v129, v141, v222
	v_fmac_f32_e32 v129, v145, v221
	s_waitcnt lgkmcnt(10)
	v_fmac_f32_e32 v48, v162, v216
	v_fmac_f32_e32 v129, v149, v220
	v_fmac_f32_e32 v129, v153, v219
	s_waitcnt lgkmcnt(8)
	v_fmac_f32_e32 v48, v166, v215
	v_fmac_f32_e32 v129, v157, v218
	v_fmac_f32_e32 v129, v161, v217
	s_waitcnt lgkmcnt(6)
	v_fmac_f32_e32 v48, v170, v214
	v_fmac_f32_e32 v129, v165, v216
	v_fmac_f32_e32 v129, v169, v215
	s_waitcnt lgkmcnt(4)
	v_fmac_f32_e32 v48, v174, v213
	v_fmac_f32_e32 v129, v173, v214
	v_fmac_f32_e32 v129, v177, v213
	s_waitcnt lgkmcnt(2)
	v_mov_b32_e32 v118, v178
	v_fmac_f32_e32 v58, v66, v223
	v_fmac_f32_e32 v58, v70, v222
	s_waitcnt lgkmcnt(0)
	v_mov_b32_e32 v119, v182
	v_pk_mul_f32 v[118:119], v[118:119], v[206:207]
	v_mov_b32_e32 v182, v179
	v_add_f32_e32 v48, v48, v118
	v_add_f32_e32 v48, v48, v119
	v_lshrrev_b32_e32 v190, 6, v198
	v_and_b32_e32 v191, 1, v190
	v_lshrrev_b32_e32 v190, 1, v190
	v_mul_u32_u24_e32 v191, 0x3000, v191
	v_lshl_add_u32 v191, v190, 7, v191
	v_lshl_add_u32 v190, v190, 6, v191
	v_add_u32_e32 v190, 0x1b000, v190
	ds_read_b128 v[118:121], v190 offset:10864
	ds_read_b128 v[186:189], v190 offset:10848
	v_readlane_b32 s0, v255, 37
	v_readlane_b32 s1, v255, 38
	s_nop 4
	ds_read_b128 v[122:125], v190 offset:11632
	ds_read_b128 v[190:193], v190 offset:11616
	v_fmac_f32_e32 v58, v74, v221
	v_fmac_f32_e32 v58, v78, v220
	v_fmac_f32_e32 v58, v82, v219
	v_fmac_f32_e32 v58, v86, v218
	v_fmac_f32_e32 v58, v90, v217
	v_fmac_f32_e32 v58, v94, v216
	v_fmac_f32_e32 v58, v98, v215
	v_fmac_f32_e32 v58, v102, v214
	v_fmac_f32_e32 v58, v106, v213
	v_fma_f32 v63, v63, v242, v59
	v_fmac_f32_e32 v63, v67, v223
	v_fmac_f32_e32 v63, v71, v222
	v_fmac_f32_e32 v63, v75, v221
	v_fmac_f32_e32 v63, v79, v220
	v_fmac_f32_e32 v63, v83, v219
	v_fmac_f32_e32 v63, v87, v218
	v_fmac_f32_e32 v63, v91, v217
	v_fmac_f32_e32 v63, v95, v216
	v_fmac_f32_e32 v63, v99, v215
	v_fmac_f32_e32 v63, v103, v214
	v_fmac_f32_e32 v63, v107, v213
	v_fma_f32 v60, v64, v242, v60
	v_fmac_f32_e32 v60, v68, v223
	v_fmac_f32_e32 v60, v72, v222
	v_fmac_f32_e32 v60, v76, v221
	v_fmac_f32_e32 v60, v80, v220
	v_fmac_f32_e32 v60, v84, v219
	v_fmac_f32_e32 v60, v88, v218
	v_fmac_f32_e32 v60, v92, v217
	v_fmac_f32_e32 v60, v96, v216
	v_fmac_f32_e32 v60, v100, v215
	v_fmac_f32_e32 v60, v104, v214
	v_fmac_f32_e32 v60, v108, v213
	v_fmac_f32_e32 v61, v65, v242
	v_fmac_f32_e32 v61, v69, v223
	v_fmac_f32_e32 v61, v73, v222
	v_fmac_f32_e32 v61, v77, v221
	v_fmac_f32_e32 v61, v81, v220
	v_fmac_f32_e32 v61, v85, v219
	v_fmac_f32_e32 v61, v89, v218
	v_fmac_f32_e32 v61, v93, v217
	v_fmac_f32_e32 v61, v97, v216
	v_fmac_f32_e32 v61, v101, v215
	v_fmac_f32_e32 v61, v105, v214
	v_fmac_f32_e32 v61, v109, v213
	v_lshlrev_b32_e32 v64, 16, v44
	v_and_b32_e32 v65, 0xffff0000, v44
	v_and_b32_e32 v67, 0xffff0000, v45
	v_lshlrev_b32_e32 v68, 16, v46
	v_and_b32_e32 v69, 0xffff0000, v46
	v_lshlrev_b32_e32 v70, 16, v47
	v_and_b32_e32 v71, 0xffff0000, v47
	s_waitcnt lgkmcnt(2)
	v_mov_b32_e32 v244, v186
	s_waitcnt lgkmcnt(0)
	v_mov_b32_e32 v245, v190
	v_pk_mul_f32 v[244:245], v[244:245], v[204:205]
	v_mov_b32_e32 v190, v187
	v_add_f32_e32 v48, v48, v244
	v_add_f32_e32 v48, v48, v245
	v_max_f32_e64 v126, -v48, 0
	v_mul_f32_e64 v48, |v48|, s93
	v_exp_f32_e32 v48, v48
	s_nop 0
	v_add_f32_e32 v48, 1.0, v48
	v_cmp_gt_f32_e32 vcc, s92, v48
	s_nop 1
	v_cndmask_b32_e64 v130, 0, 32, vcc
	v_ldexp_f32 v48, v48, v130
	v_log_f32_e32 v48, v48
	s_nop 0
	v_mul_f32_e32 v130, 0x3f317217, v48
	v_fma_f32 v130, v48, s94, -v130
	v_fmac_f32_e32 v130, 0x3377d1cf, v48
	v_fmac_f32_e32 v130, 0x3f317217, v48
	v_cmp_lt_f32_e64 s[0:1], |v48|, s95
	s_nop 1
	v_cndmask_b32_e64 v48, v48, v130, s[0:1]
	v_cndmask_b32_e32 v130, 0, v239, vcc
	v_sub_f32_e32 v48, v48, v130
	v_add_f32_e32 v48, v126, v48
	v_mul_f32_e32 v126, 0xbd800000, v48
	v_mov_b32_e32 v130, v49
	s_nop 1
	v_mov_b32_dpp v130, v126 row_shr:1 row_mask:0xf bank_mask:0xf
	v_fmac_f32_e32 v130, 0xbd800000, v48
	s_nop 1
	v_add_f32_dpp v126, v130, v130 row_shr:2 row_mask:0xf bank_mask:0xf bound_ctrl:1
	v_mov_b32_e32 v130, v49
	s_nop 0
	v_add_f32_dpp v126, v126, v126 row_shr:4 row_mask:0xf bank_mask:0xf bound_ctrl:1
	s_nop 1
	v_add_f32_dpp v126, v126, v126 row_shr:8 row_mask:0xf bank_mask:0xf bound_ctrl:1
	s_nop 1
	v_mov_b32_dpp v130, v126 row_bcast:15 row_mask:0xa bank_mask:0xf
	v_add_f32_e32 v126, v126, v130
	v_mov_b32_e32 v130, v49
	s_nop 1
	v_mov_b32_dpp v130, v126 row_bcast:31 row_mask:0xc bank_mask:0xf
	v_add_f32_e32 v126, v126, v130
	s_nop 0
	v_readlane_b32 s4, v126, 63
	s_nop 1
	v_sub_f32_e32 v130, s4, v126
	v_fmac_f32_e32 v126, 0x3d800000, v48
	v_cndmask_b32_e64 v48, v126, v130, s[8:9]
	v_fma_f32 v130, v131, v242, v127
	v_fmac_f32_e32 v130, v135, v223
	v_fmac_f32_e32 v130, v139, v222
	v_fmac_f32_e32 v130, v143, v221
	v_fmac_f32_e32 v130, v147, v220
	v_fmac_f32_e32 v130, v151, v219
	v_fmac_f32_e32 v130, v155, v218
	v_fmac_f32_e32 v130, v159, v217
	v_fmac_f32_e32 v130, v163, v216
	v_fmac_f32_e32 v130, v167, v215
	v_fmac_f32_e32 v130, v171, v214
	v_fmac_f32_e32 v130, v175, v213
	v_pk_mul_f32 v[126:127], v[182:183], v[206:207]
	v_mov_b32_e32 v131, v184
	v_add_f32_e32 v126, v130, v126
	v_add_f32_e32 v130, v126, v127
	v_pk_mul_f32 v[126:127], v[190:191], v[204:205]
	v_mov_b32_e32 v184, v181
	v_add_f32_e32 v126, v130, v126
	v_add_f32_e32 v126, v126, v127
	v_max_f32_e64 v127, -v126, 0
	v_mul_f32_e64 v126, |v126|, s93
	v_exp_f32_e32 v126, v126
	v_mul_f32_e32 v48, 0x3fb8aa3b, v48
	v_exp_f32_e32 v48, v48
	v_add_f32_e32 v126, 1.0, v126
	v_cmp_gt_f32_e32 vcc, s92, v126
	s_nop 1
	v_cndmask_b32_e64 v130, 0, 32, vcc
	v_ldexp_f32 v126, v126, v130
	v_log_f32_e32 v126, v126
	s_nop 0
	v_mul_f32_e32 v130, 0x3f317217, v126
	v_fma_f32 v130, v126, s94, -v130
	v_fmac_f32_e32 v130, 0x3377d1cf, v126
	v_fmac_f32_e32 v130, 0x3f317217, v126
	v_cmp_lt_f32_e64 s[0:1], |v126|, s95
	s_nop 1
	v_cndmask_b32_e64 v126, v126, v130, s[0:1]
	v_cndmask_b32_e32 v130, 0, v239, vcc
	v_sub_f32_e32 v126, v126, v130
	v_add_f32_e32 v126, v127, v126
	v_mul_f32_e32 v127, 0xbd800000, v126
	v_mov_b32_e32 v130, v49
	s_nop 1
	v_mov_b32_dpp v130, v127 row_shr:1 row_mask:0xf bank_mask:0xf
	v_fmac_f32_e32 v130, 0xbd800000, v126
	s_nop 1
	v_add_f32_dpp v127, v130, v130 row_shr:2 row_mask:0xf bank_mask:0xf bound_ctrl:1
	v_mov_b32_e32 v130, v49
	s_nop 0
	v_add_f32_dpp v127, v127, v127 row_shr:4 row_mask:0xf bank_mask:0xf bound_ctrl:1
	s_nop 1
	v_add_f32_dpp v127, v127, v127 row_shr:8 row_mask:0xf bank_mask:0xf bound_ctrl:1
	s_nop 1
	v_mov_b32_dpp v130, v127 row_bcast:15 row_mask:0xa bank_mask:0xf
	v_add_f32_e32 v127, v127, v130
	v_mov_b32_e32 v130, v49
	s_nop 1
	v_mov_b32_dpp v130, v127 row_bcast:31 row_mask:0xc bank_mask:0xf
	v_add_f32_e32 v127, v127, v130
	s_nop 0
	v_readlane_b32 s5, v127, 63
	s_nop 1
	v_sub_f32_e32 v130, s5, v127
	v_fmac_f32_e32 v127, 0x3d800000, v126
	v_cndmask_b32_e64 v126, v127, v130, s[8:9]
	v_fma_f32 v127, v132, v242, v128
	v_fmac_f32_e32 v127, v136, v223
	v_fmac_f32_e32 v127, v140, v222
	v_fmac_f32_e32 v127, v144, v221
	v_fmac_f32_e32 v127, v148, v220
	v_fmac_f32_e32 v127, v152, v219
	v_fmac_f32_e32 v127, v156, v218
	v_fmac_f32_e32 v127, v160, v217
	v_fmac_f32_e32 v127, v164, v216
	v_fmac_f32_e32 v127, v168, v215
	v_fmac_f32_e32 v127, v172, v214
	v_mov_b32_e32 v130, v180
	v_fmac_f32_e32 v127, v176, v213
	v_pk_mul_f32 v[130:131], v[130:131], v[206:207]
	s_nop 0
	v_add_f32_e32 v127, v127, v130
	v_add_f32_e32 v127, v127, v131
	v_mov_b32_e32 v130, v188
	v_mov_b32_e32 v131, v192
	v_pk_mul_f32 v[130:131], v[130:131], v[204:205]
	v_mov_b32_e32 v192, v189
	v_add_f32_e32 v127, v127, v130
	v_add_f32_e32 v127, v127, v131
	v_max_f32_e64 v128, -v127, 0
	v_mul_f32_e64 v127, |v127|, s93
	v_exp_f32_e32 v127, v127
	s_nop 0
	v_add_f32_e32 v127, 1.0, v127
	v_cmp_gt_f32_e32 vcc, s92, v127
	s_nop 1
	v_cndmask_b32_e64 v130, 0, 32, vcc
	v_ldexp_f32 v127, v127, v130
	v_log_f32_e32 v127, v127
	s_nop 0
	v_mul_f32_e32 v130, 0x3f317217, v127
	v_fma_f32 v130, v127, s94, -v130
	v_fmac_f32_e32 v130, 0x3377d1cf, v127
	v_fmac_f32_e32 v130, 0x3f317217, v127
	v_cmp_lt_f32_e64 s[0:1], |v127|, s95
	s_nop 1
	v_cndmask_b32_e64 v127, v127, v130, s[0:1]
	v_cndmask_b32_e32 v130, 0, v239, vcc
	v_sub_f32_e32 v127, v127, v130
	v_add_f32_e32 v127, v128, v127
	v_mul_f32_e32 v128, 0xbd800000, v127
	v_mov_b32_e32 v130, v49
	s_nop 1
	v_mov_b32_dpp v130, v128 row_shr:1 row_mask:0xf bank_mask:0xf
	v_fmac_f32_e32 v130, 0xbd800000, v127
	s_nop 1
	v_add_f32_dpp v128, v130, v130 row_shr:2 row_mask:0xf bank_mask:0xf bound_ctrl:1
	v_mov_b32_e32 v130, v49
	s_nop 0
	v_add_f32_dpp v128, v128, v128 row_shr:4 row_mask:0xf bank_mask:0xf bound_ctrl:1
	s_nop 1
	v_add_f32_dpp v128, v128, v128 row_shr:8 row_mask:0xf bank_mask:0xf bound_ctrl:1
	s_nop 1
	v_mov_b32_dpp v130, v128 row_bcast:15 row_mask:0xa bank_mask:0xf
	v_add_f32_e32 v128, v128, v130
	v_mov_b32_e32 v130, v49
	s_nop 1
	v_mov_b32_dpp v130, v128 row_bcast:31 row_mask:0xc bank_mask:0xf
	v_add_f32_e32 v128, v128, v130
	s_nop 0
	v_readlane_b32 s6, v128, 63
	s_nop 1
	v_sub_f32_e32 v130, s6, v128
	v_fmac_f32_e32 v128, 0x3d800000, v127
	v_cndmask_b32_e64 v127, v128, v130, s[8:9]
	v_pk_mul_f32 v[130:131], v[184:185], v[206:207]
	s_nop 0
	v_add_f32_e32 v128, v129, v130
	v_add_f32_e32 v130, v128, v131
	v_pk_mul_f32 v[128:129], v[192:193], v[204:205]
	s_nop 0
	v_add_f32_e32 v128, v130, v128
	v_add_f32_e32 v128, v128, v129
	v_max_f32_e64 v129, -v128, 0
	v_mul_f32_e64 v128, |v128|, s93
	v_exp_f32_e32 v128, v128
	s_nop 0
	v_add_f32_e32 v128, 1.0, v128
	v_cmp_gt_f32_e32 vcc, s92, v128
	s_nop 1
	v_cndmask_b32_e64 v130, 0, 32, vcc
	v_ldexp_f32 v128, v128, v130
	v_log_f32_e32 v128, v128
	s_nop 0
	v_mul_f32_e32 v130, 0x3f317217, v128
	v_fma_f32 v130, v128, s94, -v130
	v_fmac_f32_e32 v130, 0x3377d1cf, v128
	v_fmac_f32_e32 v130, 0x3f317217, v128
	v_cmp_lt_f32_e64 s[0:1], |v128|, s95
	s_nop 1
	v_cndmask_b32_e64 v128, v128, v130, s[0:1]
	v_cndmask_b32_e32 v130, 0, v239, vcc
	v_sub_f32_e32 v128, v128, v130
	v_add_f32_e32 v128, v129, v128
	v_mul_f32_e32 v129, 0xbd800000, v128
	v_mov_b32_e32 v130, v49
	s_nop 1
	v_mov_b32_dpp v130, v129 row_shr:1 row_mask:0xf bank_mask:0xf
	v_fmac_f32_e32 v130, 0xbd800000, v128
	s_nop 1
	v_add_f32_dpp v129, v130, v130 row_shr:2 row_mask:0xf bank_mask:0xf bound_ctrl:1
	v_mov_b32_e32 v130, v49
	s_nop 0
	v_add_f32_dpp v129, v129, v129 row_shr:4 row_mask:0xf bank_mask:0xf bound_ctrl:1
	s_nop 1
	v_add_f32_dpp v129, v129, v129 row_shr:8 row_mask:0xf bank_mask:0xf bound_ctrl:1
	s_nop 1
	v_mov_b32_dpp v130, v129 row_bcast:15 row_mask:0xa bank_mask:0xf
	v_add_f32_e32 v129, v129, v130
	v_mov_b32_e32 v130, v49
	s_nop 1
	v_mov_b32_dpp v130, v129 row_bcast:31 row_mask:0xc bank_mask:0xf
	v_add_f32_e32 v129, v129, v130
	s_nop 0
	v_readlane_b32 s7, v129, 63
	s_nop 1
	v_sub_f32_e32 v130, s7, v129
	v_fmac_f32_e32 v129, 0x3d800000, v128
	v_cndmask_b32_e64 v130, v129, v130, s[8:9]
	v_mov_b32_e32 v128, v110
	v_mov_b32_e32 v129, v114
	v_pk_mul_f32 v[128:129], v[128:129], v[206:207]
	v_mov_b32_e32 v114, v111
	v_add_f32_e32 v58, v58, v128
	v_add_f32_e32 v58, v58, v129
	v_mov_b32_e32 v128, v118
	v_mov_b32_e32 v129, v122
	v_pk_mul_f32 v[128:129], v[128:129], v[204:205]
	v_mov_b32_e32 v122, v119
	v_add_f32_e32 v58, v58, v128
	v_add_f32_e32 v58, v58, v129
	v_max_f32_e64 v62, -v58, 0
	v_mul_f32_e64 v58, |v58|, s93
	v_exp_f32_e32 v58, v58
	s_nop 0
	v_add_f32_e32 v58, 1.0, v58
	v_cmp_gt_f32_e32 vcc, s92, v58
	s_nop 1
	v_cndmask_b32_e64 v66, 0, 32, vcc
	v_ldexp_f32 v58, v58, v66
	v_log_f32_e32 v58, v58
	s_nop 0
	v_mul_f32_e32 v66, 0x3f317217, v58
	v_fma_f32 v66, v58, s94, -v66
	v_fmac_f32_e32 v66, 0x3377d1cf, v58
	v_fmac_f32_e32 v66, 0x3f317217, v58
	v_cmp_lt_f32_e64 s[0:1], |v58|, s95
	s_nop 1
	v_cndmask_b32_e64 v58, v58, v66, s[0:1]
	v_cndmask_b32_e32 v66, 0, v239, vcc
	v_sub_f32_e32 v58, v58, v66
	v_add_f32_e32 v58, v62, v58
	v_mul_f32_e32 v62, 0xbd800000, v58
	v_mov_b32_e32 v66, v49
	s_nop 1
	v_mov_b32_dpp v66, v62 row_shr:1 row_mask:0xf bank_mask:0xf
	v_fmac_f32_e32 v66, 0xbd800000, v58
	s_nop 1
	v_add_f32_dpp v62, v66, v66 row_shr:2 row_mask:0xf bank_mask:0xf bound_ctrl:1
	v_mov_b32_e32 v66, v49
	s_nop 0
	v_add_f32_dpp v62, v62, v62 row_shr:4 row_mask:0xf bank_mask:0xf bound_ctrl:1
	s_nop 1
	v_add_f32_dpp v62, v62, v62 row_shr:8 row_mask:0xf bank_mask:0xf bound_ctrl:1
	s_nop 1
	v_mov_b32_dpp v66, v62 row_bcast:15 row_mask:0xa bank_mask:0xf
	v_add_f32_e32 v62, v62, v66
	v_mov_b32_e32 v66, v49
	s_nop 1
	v_mov_b32_dpp v66, v62 row_bcast:31 row_mask:0xc bank_mask:0xf
	v_add_f32_e32 v62, v62, v66
	s_nop 0
	v_readlane_b32 s91, v62, 63
	s_nop 1
	v_sub_f32_e32 v66, s91, v62
	v_fmac_f32_e32 v62, 0x3d800000, v58
	v_pk_mul_f32 v[58:59], v[114:115], v[206:207]
	v_cndmask_b32_e64 v62, v62, v66, s[8:9]
	v_add_f32_e32 v58, v63, v58
	v_add_f32_e32 v63, v58, v59
	v_pk_mul_f32 v[58:59], v[122:123], v[204:205]
	v_lshlrev_b32_e32 v66, 16, v45
	v_add_f32_e32 v58, v63, v58
	v_add_f32_e32 v58, v58, v59
	v_max_f32_e64 v59, -v58, 0
	v_mul_f32_e64 v58, |v58|, s93
	v_exp_f32_e32 v58, v58
	s_nop 0
	v_add_f32_e32 v58, 1.0, v58
	v_cmp_gt_f32_e32 vcc, s92, v58
	s_nop 1
	v_cndmask_b32_e64 v63, 0, 32, vcc
	v_ldexp_f32 v58, v58, v63
	v_log_f32_e32 v58, v58
	s_nop 0
	v_mul_f32_e32 v63, 0x3f317217, v58
	v_fma_f32 v63, v58, s94, -v63
	v_fmac_f32_e32 v63, 0x3377d1cf, v58
	v_fmac_f32_e32 v63, 0x3f317217, v58
	v_cmp_lt_f32_e64 s[0:1], |v58|, s95
	s_nop 1
	v_cndmask_b32_e64 v58, v58, v63, s[0:1]
	v_cndmask_b32_e32 v63, 0, v239, vcc
	v_sub_f32_e32 v58, v58, v63
	v_add_f32_e32 v58, v59, v58
	v_mul_f32_e32 v59, 0xbd800000, v58
	v_mov_b32_e32 v63, v49
	s_nop 1
	v_mov_b32_dpp v63, v59 row_shr:1 row_mask:0xf bank_mask:0xf
	v_fmac_f32_e32 v63, 0xbd800000, v58
	s_nop 1
	v_add_f32_dpp v59, v63, v63 row_shr:2 row_mask:0xf bank_mask:0xf bound_ctrl:1
	v_mov_b32_e32 v63, v49
	s_nop 0
	v_add_f32_dpp v59, v59, v59 row_shr:4 row_mask:0xf bank_mask:0xf bound_ctrl:1
	s_nop 1
	v_add_f32_dpp v59, v59, v59 row_shr:8 row_mask:0xf bank_mask:0xf bound_ctrl:1
	s_nop 1
	v_mov_b32_dpp v63, v59 row_bcast:15 row_mask:0xa bank_mask:0xf
	v_add_f32_e32 v59, v59, v63
	v_mov_b32_e32 v63, v49
	s_nop 1
	v_mov_b32_dpp v63, v59 row_bcast:31 row_mask:0xc bank_mask:0xf
	v_add_f32_e32 v59, v59, v63
	s_nop 0
	v_readlane_b32 s20, v59, 63
	s_nop 1
	v_sub_f32_e32 v63, s20, v59
	v_fmac_f32_e32 v59, 0x3d800000, v58
	v_cndmask_b32_e64 v63, v59, v63, s[8:9]
	v_mov_b32_e32 v58, v112
	v_mov_b32_e32 v59, v116
	v_pk_mul_f32 v[58:59], v[58:59], v[206:207]
	v_mov_b32_e32 v116, v113
	v_add_f32_e32 v58, v60, v58
	v_add_f32_e32 v60, v58, v59
	v_mov_b32_e32 v58, v120
	v_mov_b32_e32 v59, v124
	v_pk_mul_f32 v[58:59], v[58:59], v[204:205]
	v_mov_b32_e32 v124, v121
	v_add_f32_e32 v58, v60, v58
	v_add_f32_e32 v58, v58, v59
	v_max_f32_e64 v59, -v58, 0
	v_mul_f32_e64 v58, |v58|, s93
	v_exp_f32_e32 v58, v58
	s_nop 0
	v_add_f32_e32 v58, 1.0, v58
	v_cmp_gt_f32_e32 vcc, s92, v58
	s_nop 1
	v_cndmask_b32_e64 v60, 0, 32, vcc
	v_ldexp_f32 v58, v58, v60
	v_log_f32_e32 v58, v58
	s_nop 0
	v_mul_f32_e32 v60, 0x3f317217, v58
	v_fma_f32 v60, v58, s94, -v60
	v_fmac_f32_e32 v60, 0x3377d1cf, v58
	v_fmac_f32_e32 v60, 0x3f317217, v58
	v_cmp_lt_f32_e64 s[0:1], |v58|, s95
	s_nop 1
	v_cndmask_b32_e64 v58, v58, v60, s[0:1]
	v_cndmask_b32_e32 v60, 0, v239, vcc
	v_sub_f32_e32 v58, v58, v60
	v_add_f32_e32 v58, v59, v58
	v_mul_f32_e32 v59, 0xbd800000, v58
	v_mov_b32_e32 v60, v49
	s_nop 1
	v_mov_b32_dpp v60, v59 row_shr:1 row_mask:0xf bank_mask:0xf
	v_fmac_f32_e32 v60, 0xbd800000, v58
	s_nop 1
	v_add_f32_dpp v59, v60, v60 row_shr:2 row_mask:0xf bank_mask:0xf bound_ctrl:1
	v_mov_b32_e32 v60, v49
	s_nop 0
	v_add_f32_dpp v59, v59, v59 row_shr:4 row_mask:0xf bank_mask:0xf bound_ctrl:1
	s_nop 1
	v_add_f32_dpp v59, v59, v59 row_shr:8 row_mask:0xf bank_mask:0xf bound_ctrl:1
	s_nop 1
	v_mov_b32_dpp v60, v59 row_bcast:15 row_mask:0xa bank_mask:0xf
	v_add_f32_e32 v59, v59, v60
	v_mov_b32_e32 v60, v49
	s_nop 1
	v_mov_b32_dpp v60, v59 row_bcast:31 row_mask:0xc bank_mask:0xf
	v_add_f32_e32 v59, v59, v60
	s_nop 0
	v_readlane_b32 s21, v59, 63
	s_nop 1
	v_sub_f32_e32 v60, s21, v59
	v_fmac_f32_e32 v59, 0x3d800000, v58
	v_cndmask_b32_e64 v60, v59, v60, s[8:9]
	v_pk_mul_f32 v[58:59], v[116:117], v[206:207]
	s_nop 0
	v_add_f32_e32 v58, v61, v58
	v_add_f32_e32 v61, v58, v59
	v_pk_mul_f32 v[58:59], v[124:125], v[204:205]
	s_nop 0
	v_add_f32_e32 v58, v61, v58
	v_add_f32_e32 v58, v58, v59
	v_max_f32_e64 v59, -v58, 0
	v_mul_f32_e64 v58, |v58|, s93
	v_exp_f32_e32 v58, v58
	s_nop 0
	v_add_f32_e32 v58, 1.0, v58
	v_cmp_gt_f32_e32 vcc, s92, v58
	s_nop 1
	v_cndmask_b32_e64 v61, 0, 32, vcc
	v_ldexp_f32 v58, v58, v61
	v_log_f32_e32 v58, v58
	s_nop 0
	v_mul_f32_e32 v61, 0x3f317217, v58
	v_fma_f32 v61, v58, s94, -v61
	v_fmac_f32_e32 v61, 0x3377d1cf, v58
	v_fmac_f32_e32 v61, 0x3f317217, v58
	v_cmp_lt_f32_e64 s[0:1], |v58|, s95
	s_nop 1
	v_cndmask_b32_e64 v58, v58, v61, s[0:1]
	v_cndmask_b32_e32 v61, 0, v239, vcc
	v_sub_f32_e32 v58, v58, v61
	v_add_f32_e32 v58, v59, v58
	v_mul_f32_e32 v59, 0xbd800000, v58
	v_mov_b32_e32 v61, v49
	v_readlane_b32 s0, v254, 6
	s_add_u32 s0, s90, s0
	v_mov_b32_dpp v61, v59 row_shr:1 row_mask:0xf bank_mask:0xf
	v_fmac_f32_e32 v61, 0xbd800000, v58
	v_readlane_b32 s1, v254, 8
	s_addc_u32 s1, s15, s1
	v_add_f32_dpp v59, v61, v61 row_shr:2 row_mask:0xf bank_mask:0xf bound_ctrl:1
	v_mov_b32_e32 v61, v49
	s_lshl_b64 s[0:1], s[0:1], 10
	v_add_f32_dpp v59, v59, v59 row_shr:4 row_mask:0xf bank_mask:0xf bound_ctrl:1
	s_nop 1
	v_add_f32_dpp v59, v59, v59 row_shr:8 row_mask:0xf bank_mask:0xf bound_ctrl:1
	s_nop 1
	v_mov_b32_dpp v61, v59 row_bcast:15 row_mask:0xa bank_mask:0xf
	v_add_f32_e32 v59, v59, v61
	v_mov_b32_e32 v61, v49
	s_nop 1
	v_mov_b32_dpp v61, v59 row_bcast:31 row_mask:0xc bank_mask:0xf
	v_add_f32_e32 v59, v59, v61
	s_nop 0
	v_readlane_b32 s18, v59, 63
	s_nop 1
	v_sub_f32_e32 v61, s18, v59
	v_fmac_f32_e32 v59, 0x3d800000, v58
	v_cndmask_b32_e64 v58, v59, v61, s[8:9]
	v_mul_f32_e32 v59, 0x3fb8aa3b, v126
	v_exp_f32_e32 v72, v59
	v_mul_f32_e32 v59, 0x3fb8aa3b, v127
	v_mul_f32_e32 v58, 0x3fb8aa3b, v58
	v_exp_f32_e32 v73, v59
	v_exp_f32_e32 v78, v58
	v_cvt_pk_bf16_f32 v58, v48, v72
	v_mul_f32_e32 v48, v48, v64
	v_mul_f32_e32 v59, 0x3fb8aa3b, v130
	v_cvt_pk_bf16_f32 v48, v48, s0
	v_exp_f32_e32 v74, v59
	ds_write_b16 v208, v48 offset:58752
	v_mul_f32_e32 v48, v72, v65
	v_mul_f32_e32 v59, 0x3fb8aa3b, v62
	v_cvt_pk_bf16_f32 v48, v48, s0
	v_exp_f32_e32 v75, v59
	ds_write_b16 v208, v48 offset:58896
	v_mul_f32_e32 v48, v73, v66
	v_mul_f32_e32 v59, 0x3fb8aa3b, v63
	v_cvt_pk_bf16_f32 v48, v48, s0
	v_exp_f32_e32 v76, v59
	ds_write_b16 v208, v48 offset:59040
	v_mul_f32_e32 v48, v74, v67
	v_mul_f32_e32 v59, 0x3fb8aa3b, v60
	v_cvt_pk_bf16_f32 v48, v48, s0
	v_exp_f32_e32 v77, v59
	ds_write_b16 v208, v48 offset:59184
	v_mul_f32_e32 v48, v75, v68
	v_cvt_pk_bf16_f32 v48, v48, s0
	ds_write_b16 v208, v48 offset:59328
	v_mul_f32_e32 v48, v76, v69
	v_cvt_pk_bf16_f32 v48, v48, s0
	ds_write_b16 v208, v48 offset:59472
	v_mul_f32_e32 v48, v77, v70
	v_cvt_pk_bf16_f32 v48, v48, s0
	ds_write_b16 v208, v48 offset:59616
	v_mul_f32_e32 v48, v78, v71
	v_cvt_pk_bf16_f32 v59, v73, v74
	v_cvt_pk_bf16_f32 v60, v75, v76
	v_cvt_pk_bf16_f32 v61, v77, v78
	v_lshl_add_u64 v[62:63], v[202:203], 0, s[0:1]
	v_cvt_pk_bf16_f32 v48, v48, s0
	global_store_dwordx4 v[62:63], v[58:61], off
	ds_write_b16 v208, v48 offset:59760
	s_and_saveexec_b64 s[0:1], s[10:11]
	s_cbranch_execz .LBB0_665
	v_mul_f32_e32 v48, s4, v240
	v_exp_f32_e32 v58, v48
	v_mul_f32_e32 v48, s5, v240
	v_exp_f32_e32 v59, v48
	v_mul_f32_e32 v48, s6, v240
	v_exp_f32_e32 v60, v48
	v_mul_f32_e32 v48, s7, v240
	v_exp_f32_e32 v61, v48
	v_mul_f32_e32 v48, s91, v240
	v_exp_f32_e32 v62, v48
	v_mul_f32_e32 v48, s20, v240
	v_exp_f32_e32 v63, v48
	v_mul_f32_e32 v48, s21, v240
	v_exp_f32_e32 v64, v48
	v_mul_f32_e32 v48, s18, v240
	v_exp_f32_e32 v65, v48
	s_add_u32 s4, s16, s88
	s_addc_u32 s5, s17, s89
	global_store_dwordx4 v49, v[58:61], s[4:5] offset:96
	global_store_dwordx4 v49, v[62:65], s[4:5] offset:112
.LBB0_665:
	s_or_b64 exec, exec, s[0:1]
	v_lshrrev_b32_e32 v182, 6, v198
	v_and_b32_e32 v183, 1, v182
	v_lshrrev_b32_e32 v182, 1, v182
	v_mul_u32_u24_e32 v183, 0x3000, v183
	v_lshl_add_u32 v183, v182, 7, v183
	v_lshl_add_u32 v182, v182, 6, v183
	v_add_u32_e32 v182, 0x1b000, v182
	ds_read_b128 v[58:61], v182 offset:24720
	ds_read_b128 v[126:129], v182 offset:24704
	ds_read_b128 v[62:65], v182 offset:144
	ds_read_b128 v[130:133], v182 offset:128
	ds_read_b128 v[66:69], v182 offset:912
	ds_read_b128 v[134:137], v182 offset:896
	ds_read_b128 v[70:73], v182 offset:1680
	ds_read_b128 v[138:141], v182 offset:1664
	ds_read_b128 v[74:77], v182 offset:2448
	ds_read_b128 v[142:145], v182 offset:2432
	v_readlane_b32 s0, v255, 39
	ds_read_b128 v[78:81], v182 offset:3216
	ds_read_b128 v[146:149], v182 offset:3200
	s_waitcnt lgkmcnt(8)
	v_readlane_b32 s1, v255, 40
	ds_read_b128 v[82:85], v182 offset:3984
	ds_read_b128 v[150:153], v182 offset:3968
	s_nop 2
	ds_read_b128 v[86:89], v182 offset:4752
	ds_read_b128 v[154:157], v182 offset:4736
	s_waitcnt lgkmcnt(8)
	v_readlane_b32 s0, v255, 41
	v_readlane_b32 s1, v255, 42
	s_nop 4
	ds_read_b128 v[90:93], v182 offset:5520
	ds_read_b128 v[158:161], v182 offset:5504
	ds_read_b128 v[94:97], v182 offset:6288
	ds_read_b128 v[162:165], v182 offset:6272
	s_waitcnt lgkmcnt(8)
	ds_read_b128 v[98:101], v182 offset:7056
	ds_read_b128 v[166:169], v182 offset:7040
	ds_read_b128 v[102:105], v182 offset:7824
	ds_read_b128 v[170:173], v182 offset:7808
	s_waitcnt lgkmcnt(8)
	ds_read_b128 v[106:109], v182 offset:8592
	ds_read_b128 v[174:177], v182 offset:8576
	ds_read_b128 v[110:113], v182 offset:9360
	ds_read_b128 v[178:181], v182 offset:9344
	s_waitcnt lgkmcnt(8)
	ds_read_b128 v[114:117], v182 offset:10128
	ds_read_b128 v[182:185], v182 offset:10112
	s_waitcnt lgkmcnt(14)
	v_fma_f32 v58, v62, v242, v58
	s_waitcnt lgkmcnt(14)
	v_fma_f32 v48, v130, v242, v126
	s_waitcnt lgkmcnt(14)
	v_fmac_f32_e32 v48, v134, v223
	s_waitcnt lgkmcnt(14)
	v_fmac_f32_e32 v48, v138, v222
	s_waitcnt lgkmcnt(14)
	v_fmac_f32_e32 v48, v142, v221
	v_fmac_f32_e32 v129, v133, v242
	s_waitcnt lgkmcnt(14)
	v_fmac_f32_e32 v48, v146, v220
	v_fmac_f32_e32 v129, v137, v223
	s_waitcnt lgkmcnt(14)
	v_fmac_f32_e32 v48, v150, v219
	s_waitcnt lgkmcnt(14)
	v_fmac_f32_e32 v48, v154, v218
	v_fmac_f32_e32 v129, v141, v222
	v_fmac_f32_e32 v129, v145, v221
	s_waitcnt lgkmcnt(12)
	v_fmac_f32_e32 v48, v158, v217
	s_waitcnt lgkmcnt(10)
	v_fmac_f32_e32 v48, v162, v216
	s_waitcnt lgkmcnt(8)
	v_fmac_f32_e32 v48, v166, v215
	s_waitcnt lgkmcnt(6)
	v_fmac_f32_e32 v48, v170, v214
	s_waitcnt lgkmcnt(2)
	v_mov_b32_e32 v118, v178
	s_waitcnt lgkmcnt(0)
	v_mov_b32_e32 v119, v182
	v_fmac_f32_e32 v48, v174, v213
	v_pk_mul_f32 v[118:119], v[118:119], v[206:207]
	v_mov_b32_e32 v182, v179
	v_add_f32_e32 v48, v48, v118
	v_add_f32_e32 v48, v48, v119
	v_lshrrev_b32_e32 v190, 6, v198
	v_and_b32_e32 v191, 1, v190
	v_lshrrev_b32_e32 v190, 1, v190
	v_mul_u32_u24_e32 v191, 0x3000, v191
	v_lshl_add_u32 v191, v190, 7, v191
	v_lshl_add_u32 v190, v190, 6, v191
	v_add_u32_e32 v190, 0x1b000, v190
	ds_read_b128 v[118:121], v190 offset:10896
	ds_read_b128 v[186:189], v190 offset:10880
	ds_read_b128 v[122:125], v190 offset:11664
	ds_read_b128 v[190:193], v190 offset:11648
	v_fmac_f32_e32 v129, v149, v220
	v_fmac_f32_e32 v129, v153, v219
	v_fmac_f32_e32 v129, v157, v218
	v_fmac_f32_e32 v129, v161, v217
	v_fmac_f32_e32 v129, v165, v216
	v_fmac_f32_e32 v129, v169, v215
	v_fmac_f32_e32 v129, v173, v214
	v_fmac_f32_e32 v129, v177, v213
	v_fmac_f32_e32 v58, v66, v223
	v_fmac_f32_e32 v58, v70, v222
	v_fmac_f32_e32 v58, v74, v221
	v_fmac_f32_e32 v58, v78, v220
	v_fmac_f32_e32 v58, v82, v219
	v_fmac_f32_e32 v58, v86, v218
	v_fmac_f32_e32 v58, v90, v217
	v_fmac_f32_e32 v58, v94, v216
	v_fmac_f32_e32 v58, v98, v215
	v_fmac_f32_e32 v58, v102, v214
	v_fmac_f32_e32 v58, v106, v213
	v_fma_f32 v63, v63, v242, v59
	v_fmac_f32_e32 v63, v67, v223
	v_fmac_f32_e32 v63, v71, v222
	v_fmac_f32_e32 v63, v75, v221
	v_fmac_f32_e32 v63, v79, v220
	v_fmac_f32_e32 v63, v83, v219
	v_fmac_f32_e32 v63, v87, v218
	v_fmac_f32_e32 v63, v91, v217
	v_fmac_f32_e32 v63, v95, v216
	v_fmac_f32_e32 v63, v99, v215
	v_fmac_f32_e32 v63, v103, v214
	v_fmac_f32_e32 v63, v107, v213
	v_fma_f32 v60, v64, v242, v60
	v_fmac_f32_e32 v60, v68, v223
	v_fmac_f32_e32 v60, v72, v222
	v_fmac_f32_e32 v60, v76, v221
	v_fmac_f32_e32 v60, v80, v220
	v_fmac_f32_e32 v60, v84, v219
	v_fmac_f32_e32 v60, v88, v218
	v_fmac_f32_e32 v60, v92, v217
	v_fmac_f32_e32 v60, v96, v216
	v_fmac_f32_e32 v60, v100, v215
	v_fmac_f32_e32 v60, v104, v214
	v_fmac_f32_e32 v60, v108, v213
	v_fmac_f32_e32 v61, v65, v242
	v_fmac_f32_e32 v61, v69, v223
	v_fmac_f32_e32 v61, v73, v222
	v_fmac_f32_e32 v61, v77, v221
	v_fmac_f32_e32 v61, v81, v220
	v_fmac_f32_e32 v61, v85, v219
	v_fmac_f32_e32 v61, v89, v218
	v_fmac_f32_e32 v61, v93, v217
	v_fmac_f32_e32 v61, v97, v216
	v_fmac_f32_e32 v61, v101, v215
	v_fmac_f32_e32 v61, v105, v214
	v_fmac_f32_e32 v61, v109, v213
	v_lshlrev_b32_e32 v64, 16, v50
	v_and_b32_e32 v65, 0xffff0000, v50
	v_and_b32_e32 v67, 0xffff0000, v51
	v_lshlrev_b32_e32 v68, 16, v52
	v_and_b32_e32 v69, 0xffff0000, v52
	v_lshlrev_b32_e32 v70, 16, v53
	v_and_b32_e32 v71, 0xffff0000, v53
	s_waitcnt lgkmcnt(2)
	v_mov_b32_e32 v244, v186
	s_waitcnt lgkmcnt(0)
	v_mov_b32_e32 v245, v190
	v_pk_mul_f32 v[244:245], v[244:245], v[204:205]
	v_mov_b32_e32 v190, v187
	v_add_f32_e32 v48, v48, v244
	v_add_f32_e32 v48, v48, v245
	v_max_f32_e64 v126, -v48, 0
	v_mul_f32_e64 v48, |v48|, s93
	v_exp_f32_e32 v48, v48
	s_nop 0
	v_add_f32_e32 v48, 1.0, v48
	v_cmp_gt_f32_e32 vcc, s92, v48
	s_nop 1
	v_cndmask_b32_e64 v130, 0, 32, vcc
	v_ldexp_f32 v48, v48, v130
	v_log_f32_e32 v48, v48
	s_nop 0
	v_mul_f32_e32 v130, 0x3f317217, v48
	v_fma_f32 v130, v48, s94, -v130
	v_fmac_f32_e32 v130, 0x3377d1cf, v48
	v_fmac_f32_e32 v130, 0x3f317217, v48
	v_cmp_lt_f32_e64 s[0:1], |v48|, s95
	s_nop 1
	v_cndmask_b32_e64 v48, v48, v130, s[0:1]
	v_cndmask_b32_e32 v130, 0, v239, vcc
	v_sub_f32_e32 v48, v48, v130
	v_add_f32_e32 v48, v126, v48
	v_mul_f32_e32 v126, 0xbd800000, v48
	v_mov_b32_e32 v130, v49
	s_nop 1
	v_mov_b32_dpp v130, v126 row_shr:1 row_mask:0xf bank_mask:0xf
	v_fmac_f32_e32 v130, 0xbd800000, v48
	s_nop 1
	v_add_f32_dpp v126, v130, v130 row_shr:2 row_mask:0xf bank_mask:0xf bound_ctrl:1
	v_mov_b32_e32 v130, v49
	s_nop 0
	v_add_f32_dpp v126, v126, v126 row_shr:4 row_mask:0xf bank_mask:0xf bound_ctrl:1
	s_nop 1
	v_add_f32_dpp v126, v126, v126 row_shr:8 row_mask:0xf bank_mask:0xf bound_ctrl:1
	s_nop 1
	v_mov_b32_dpp v130, v126 row_bcast:15 row_mask:0xa bank_mask:0xf
	v_add_f32_e32 v126, v126, v130
	v_mov_b32_e32 v130, v49
	s_nop 1
	v_mov_b32_dpp v130, v126 row_bcast:31 row_mask:0xc bank_mask:0xf
	v_add_f32_e32 v126, v126, v130
	s_nop 0
	v_readlane_b32 s4, v126, 63
	s_nop 1
	v_sub_f32_e32 v130, s4, v126
	v_fmac_f32_e32 v126, 0x3d800000, v48
	v_cndmask_b32_e64 v48, v126, v130, s[8:9]
	v_fma_f32 v130, v131, v242, v127
	v_fmac_f32_e32 v130, v135, v223
	v_fmac_f32_e32 v130, v139, v222
	v_fmac_f32_e32 v130, v143, v221
	v_fmac_f32_e32 v130, v147, v220
	v_fmac_f32_e32 v130, v151, v219
	v_fmac_f32_e32 v130, v155, v218
	v_fmac_f32_e32 v130, v159, v217
	v_fmac_f32_e32 v130, v163, v216
	v_fmac_f32_e32 v130, v167, v215
	v_fmac_f32_e32 v130, v171, v214
	v_fmac_f32_e32 v130, v175, v213
	v_pk_mul_f32 v[126:127], v[182:183], v[206:207]
	v_mov_b32_e32 v131, v184
	v_add_f32_e32 v126, v130, v126
	v_add_f32_e32 v130, v126, v127
	v_pk_mul_f32 v[126:127], v[190:191], v[204:205]
	v_mov_b32_e32 v184, v181
	v_add_f32_e32 v126, v130, v126
	v_add_f32_e32 v126, v126, v127
	v_max_f32_e64 v127, -v126, 0
	v_mul_f32_e64 v126, |v126|, s93
	v_exp_f32_e32 v126, v126
	v_mul_f32_e32 v48, 0x3fb8aa3b, v48
	v_exp_f32_e32 v48, v48
	v_add_f32_e32 v126, 1.0, v126
	v_cmp_gt_f32_e32 vcc, s92, v126
	s_nop 1
	v_cndmask_b32_e64 v130, 0, 32, vcc
	v_ldexp_f32 v126, v126, v130
	v_log_f32_e32 v126, v126
	s_nop 0
	v_mul_f32_e32 v130, 0x3f317217, v126
	v_fma_f32 v130, v126, s94, -v130
	v_fmac_f32_e32 v130, 0x3377d1cf, v126
	v_fmac_f32_e32 v130, 0x3f317217, v126
	v_cmp_lt_f32_e64 s[0:1], |v126|, s95
	s_nop 1
	v_cndmask_b32_e64 v126, v126, v130, s[0:1]
	v_cndmask_b32_e32 v130, 0, v239, vcc
	v_sub_f32_e32 v126, v126, v130
	v_add_f32_e32 v126, v127, v126
	v_mul_f32_e32 v127, 0xbd800000, v126
	v_mov_b32_e32 v130, v49
	s_nop 1
	v_mov_b32_dpp v130, v127 row_shr:1 row_mask:0xf bank_mask:0xf
	v_fmac_f32_e32 v130, 0xbd800000, v126
	s_nop 1
	v_add_f32_dpp v127, v130, v130 row_shr:2 row_mask:0xf bank_mask:0xf bound_ctrl:1
	v_mov_b32_e32 v130, v49
	s_nop 0
	v_add_f32_dpp v127, v127, v127 row_shr:4 row_mask:0xf bank_mask:0xf bound_ctrl:1
	s_nop 1
	v_add_f32_dpp v127, v127, v127 row_shr:8 row_mask:0xf bank_mask:0xf bound_ctrl:1
	s_nop 1
	v_mov_b32_dpp v130, v127 row_bcast:15 row_mask:0xa bank_mask:0xf
	v_add_f32_e32 v127, v127, v130
	v_mov_b32_e32 v130, v49
	s_nop 1
	v_mov_b32_dpp v130, v127 row_bcast:31 row_mask:0xc bank_mask:0xf
	v_add_f32_e32 v127, v127, v130
	s_nop 0
	v_readlane_b32 s5, v127, 63
	s_nop 1
	v_sub_f32_e32 v130, s5, v127
	v_fmac_f32_e32 v127, 0x3d800000, v126
	v_cndmask_b32_e64 v126, v127, v130, s[8:9]
	v_fma_f32 v127, v132, v242, v128
	v_fmac_f32_e32 v127, v136, v223
	v_fmac_f32_e32 v127, v140, v222
	v_fmac_f32_e32 v127, v144, v221
	v_fmac_f32_e32 v127, v148, v220
	v_fmac_f32_e32 v127, v152, v219
	v_fmac_f32_e32 v127, v156, v218
	v_fmac_f32_e32 v127, v160, v217
	v_fmac_f32_e32 v127, v164, v216
	v_fmac_f32_e32 v127, v168, v215
	v_fmac_f32_e32 v127, v172, v214
	v_mov_b32_e32 v130, v180
	v_fmac_f32_e32 v127, v176, v213
	v_pk_mul_f32 v[130:131], v[130:131], v[206:207]
	s_nop 0
	v_add_f32_e32 v127, v127, v130
	v_add_f32_e32 v127, v127, v131
	v_mov_b32_e32 v130, v188
	v_mov_b32_e32 v131, v192
	v_pk_mul_f32 v[130:131], v[130:131], v[204:205]
	v_mov_b32_e32 v192, v189
	v_add_f32_e32 v127, v127, v130
	v_add_f32_e32 v127, v127, v131
	v_max_f32_e64 v128, -v127, 0
	v_mul_f32_e64 v127, |v127|, s93
	v_exp_f32_e32 v127, v127
	s_nop 0
	v_add_f32_e32 v127, 1.0, v127
	v_cmp_gt_f32_e32 vcc, s92, v127
	s_nop 1
	v_cndmask_b32_e64 v130, 0, 32, vcc
	v_ldexp_f32 v127, v127, v130
	v_log_f32_e32 v127, v127
	s_nop 0
	v_mul_f32_e32 v130, 0x3f317217, v127
	v_fma_f32 v130, v127, s94, -v130
	v_fmac_f32_e32 v130, 0x3377d1cf, v127
	v_fmac_f32_e32 v130, 0x3f317217, v127
	v_cmp_lt_f32_e64 s[0:1], |v127|, s95
	s_nop 1
	v_cndmask_b32_e64 v127, v127, v130, s[0:1]
	v_cndmask_b32_e32 v130, 0, v239, vcc
	v_sub_f32_e32 v127, v127, v130
	v_add_f32_e32 v127, v128, v127
	v_mul_f32_e32 v128, 0xbd800000, v127
	v_mov_b32_e32 v130, v49
	s_nop 1
	v_mov_b32_dpp v130, v128 row_shr:1 row_mask:0xf bank_mask:0xf
	v_fmac_f32_e32 v130, 0xbd800000, v127
	s_nop 1
	v_add_f32_dpp v128, v130, v130 row_shr:2 row_mask:0xf bank_mask:0xf bound_ctrl:1
	v_mov_b32_e32 v130, v49
	s_nop 0
	v_add_f32_dpp v128, v128, v128 row_shr:4 row_mask:0xf bank_mask:0xf bound_ctrl:1
	s_nop 1
	v_add_f32_dpp v128, v128, v128 row_shr:8 row_mask:0xf bank_mask:0xf bound_ctrl:1
	s_nop 1
	v_mov_b32_dpp v130, v128 row_bcast:15 row_mask:0xa bank_mask:0xf
	v_add_f32_e32 v128, v128, v130
	v_mov_b32_e32 v130, v49
	s_nop 1
	v_mov_b32_dpp v130, v128 row_bcast:31 row_mask:0xc bank_mask:0xf
	v_add_f32_e32 v128, v128, v130
	s_nop 0
	v_readlane_b32 s6, v128, 63
	s_nop 1
	v_sub_f32_e32 v130, s6, v128
	v_fmac_f32_e32 v128, 0x3d800000, v127
	v_cndmask_b32_e64 v127, v128, v130, s[8:9]
	v_pk_mul_f32 v[130:131], v[184:185], v[206:207]
	s_nop 0
	v_add_f32_e32 v128, v129, v130
	v_add_f32_e32 v130, v128, v131
	v_pk_mul_f32 v[128:129], v[192:193], v[204:205]
	s_nop 0
	v_add_f32_e32 v128, v130, v128
	v_add_f32_e32 v128, v128, v129
	v_max_f32_e64 v129, -v128, 0
	v_mul_f32_e64 v128, |v128|, s93
	v_exp_f32_e32 v128, v128
	s_nop 0
	v_add_f32_e32 v128, 1.0, v128
	v_cmp_gt_f32_e32 vcc, s92, v128
	s_nop 1
	v_cndmask_b32_e64 v130, 0, 32, vcc
	v_ldexp_f32 v128, v128, v130
	v_log_f32_e32 v128, v128
	s_nop 0
	v_mul_f32_e32 v130, 0x3f317217, v128
	v_fma_f32 v130, v128, s94, -v130
	v_fmac_f32_e32 v130, 0x3377d1cf, v128
	v_fmac_f32_e32 v130, 0x3f317217, v128
	v_cmp_lt_f32_e64 s[0:1], |v128|, s95
	s_nop 1
	v_cndmask_b32_e64 v128, v128, v130, s[0:1]
	v_cndmask_b32_e32 v130, 0, v239, vcc
	v_sub_f32_e32 v128, v128, v130
	v_add_f32_e32 v128, v129, v128
	v_mul_f32_e32 v129, 0xbd800000, v128
	v_mov_b32_e32 v130, v49
	s_nop 1
	v_mov_b32_dpp v130, v129 row_shr:1 row_mask:0xf bank_mask:0xf
	v_fmac_f32_e32 v130, 0xbd800000, v128
	s_nop 1
	v_add_f32_dpp v129, v130, v130 row_shr:2 row_mask:0xf bank_mask:0xf bound_ctrl:1
	v_mov_b32_e32 v130, v49
	s_nop 0
	v_add_f32_dpp v129, v129, v129 row_shr:4 row_mask:0xf bank_mask:0xf bound_ctrl:1
	s_nop 1
	v_add_f32_dpp v129, v129, v129 row_shr:8 row_mask:0xf bank_mask:0xf bound_ctrl:1
	s_nop 1
	v_mov_b32_dpp v130, v129 row_bcast:15 row_mask:0xa bank_mask:0xf
	v_add_f32_e32 v129, v129, v130
	v_mov_b32_e32 v130, v49
	s_nop 1
	v_mov_b32_dpp v130, v129 row_bcast:31 row_mask:0xc bank_mask:0xf
	v_add_f32_e32 v129, v129, v130
	s_nop 0
	v_readlane_b32 s7, v129, 63
	s_nop 1
	v_sub_f32_e32 v130, s7, v129
	v_fmac_f32_e32 v129, 0x3d800000, v128
	v_cndmask_b32_e64 v130, v129, v130, s[8:9]
	v_mov_b32_e32 v128, v110
	v_mov_b32_e32 v129, v114
	v_pk_mul_f32 v[128:129], v[128:129], v[206:207]
	v_mov_b32_e32 v114, v111
	v_add_f32_e32 v58, v58, v128
	v_add_f32_e32 v58, v58, v129
	v_mov_b32_e32 v128, v118
	v_mov_b32_e32 v129, v122
	v_pk_mul_f32 v[128:129], v[128:129], v[204:205]
	v_mov_b32_e32 v122, v119
	v_add_f32_e32 v58, v58, v128
	v_add_f32_e32 v58, v58, v129
	v_max_f32_e64 v62, -v58, 0
	v_mul_f32_e64 v58, |v58|, s93
	v_exp_f32_e32 v58, v58
	s_nop 0
	v_add_f32_e32 v58, 1.0, v58
	v_cmp_gt_f32_e32 vcc, s92, v58
	s_nop 1
	v_cndmask_b32_e64 v66, 0, 32, vcc
	v_ldexp_f32 v58, v58, v66
	v_log_f32_e32 v58, v58
	s_nop 0
	v_mul_f32_e32 v66, 0x3f317217, v58
	v_fma_f32 v66, v58, s94, -v66
	v_fmac_f32_e32 v66, 0x3377d1cf, v58
	v_fmac_f32_e32 v66, 0x3f317217, v58
	v_cmp_lt_f32_e64 s[0:1], |v58|, s95
	s_nop 1
	v_cndmask_b32_e64 v58, v58, v66, s[0:1]
	v_cndmask_b32_e32 v66, 0, v239, vcc
	v_sub_f32_e32 v58, v58, v66
	v_add_f32_e32 v58, v62, v58
	v_mul_f32_e32 v62, 0xbd800000, v58
	v_mov_b32_e32 v66, v49
	s_nop 1
	v_mov_b32_dpp v66, v62 row_shr:1 row_mask:0xf bank_mask:0xf
	v_fmac_f32_e32 v66, 0xbd800000, v58
	s_nop 1
	v_add_f32_dpp v62, v66, v66 row_shr:2 row_mask:0xf bank_mask:0xf bound_ctrl:1
	v_mov_b32_e32 v66, v49
	s_nop 0
	v_add_f32_dpp v62, v62, v62 row_shr:4 row_mask:0xf bank_mask:0xf bound_ctrl:1
	s_nop 1
	v_add_f32_dpp v62, v62, v62 row_shr:8 row_mask:0xf bank_mask:0xf bound_ctrl:1
	s_nop 1
	v_mov_b32_dpp v66, v62 row_bcast:15 row_mask:0xa bank_mask:0xf
	v_add_f32_e32 v62, v62, v66
	v_mov_b32_e32 v66, v49
	s_nop 1
	v_mov_b32_dpp v66, v62 row_bcast:31 row_mask:0xc bank_mask:0xf
	v_add_f32_e32 v62, v62, v66
	s_nop 0
	v_readlane_b32 s91, v62, 63
	s_nop 1
	v_sub_f32_e32 v66, s91, v62
	v_fmac_f32_e32 v62, 0x3d800000, v58
	v_pk_mul_f32 v[58:59], v[114:115], v[206:207]
	v_cndmask_b32_e64 v62, v62, v66, s[8:9]
	v_add_f32_e32 v58, v63, v58
	v_add_f32_e32 v63, v58, v59
	v_pk_mul_f32 v[58:59], v[122:123], v[204:205]
	v_lshlrev_b32_e32 v66, 16, v51
	v_add_f32_e32 v58, v63, v58
	v_add_f32_e32 v58, v58, v59
	v_max_f32_e64 v59, -v58, 0
	v_mul_f32_e64 v58, |v58|, s93
	v_exp_f32_e32 v58, v58
	s_nop 0
	v_add_f32_e32 v58, 1.0, v58
	v_cmp_gt_f32_e32 vcc, s92, v58
	s_nop 1
	v_cndmask_b32_e64 v63, 0, 32, vcc
	v_ldexp_f32 v58, v58, v63
	v_log_f32_e32 v58, v58
	s_nop 0
	v_mul_f32_e32 v63, 0x3f317217, v58
	v_fma_f32 v63, v58, s94, -v63
	v_fmac_f32_e32 v63, 0x3377d1cf, v58
	v_fmac_f32_e32 v63, 0x3f317217, v58
	v_cmp_lt_f32_e64 s[0:1], |v58|, s95
	s_nop 1
	v_cndmask_b32_e64 v58, v58, v63, s[0:1]
	v_cndmask_b32_e32 v63, 0, v239, vcc
	v_sub_f32_e32 v58, v58, v63
	v_add_f32_e32 v58, v59, v58
	v_mul_f32_e32 v59, 0xbd800000, v58
	v_mov_b32_e32 v63, v49
	s_nop 1
	v_mov_b32_dpp v63, v59 row_shr:1 row_mask:0xf bank_mask:0xf
	v_fmac_f32_e32 v63, 0xbd800000, v58
	s_nop 1
	v_add_f32_dpp v59, v63, v63 row_shr:2 row_mask:0xf bank_mask:0xf bound_ctrl:1
	v_mov_b32_e32 v63, v49
	s_nop 0
	v_add_f32_dpp v59, v59, v59 row_shr:4 row_mask:0xf bank_mask:0xf bound_ctrl:1
	s_nop 1
	v_add_f32_dpp v59, v59, v59 row_shr:8 row_mask:0xf bank_mask:0xf bound_ctrl:1
	s_nop 1
	v_mov_b32_dpp v63, v59 row_bcast:15 row_mask:0xa bank_mask:0xf
	v_add_f32_e32 v59, v59, v63
	v_mov_b32_e32 v63, v49
	s_nop 1
	v_mov_b32_dpp v63, v59 row_bcast:31 row_mask:0xc bank_mask:0xf
	v_add_f32_e32 v59, v59, v63
	s_nop 0
	v_readlane_b32 s20, v59, 63
	s_nop 1
	v_sub_f32_e32 v63, s20, v59
	v_fmac_f32_e32 v59, 0x3d800000, v58
	v_cndmask_b32_e64 v63, v59, v63, s[8:9]
	v_mov_b32_e32 v58, v112
	v_mov_b32_e32 v59, v116
	v_pk_mul_f32 v[58:59], v[58:59], v[206:207]
	v_mov_b32_e32 v116, v113
	v_add_f32_e32 v58, v60, v58
	v_add_f32_e32 v60, v58, v59
	v_mov_b32_e32 v58, v120
	v_mov_b32_e32 v59, v124
	v_pk_mul_f32 v[58:59], v[58:59], v[204:205]
	v_mov_b32_e32 v124, v121
	v_add_f32_e32 v58, v60, v58
	v_add_f32_e32 v58, v58, v59
	v_max_f32_e64 v59, -v58, 0
	v_mul_f32_e64 v58, |v58|, s93
	v_exp_f32_e32 v58, v58
	s_nop 0
	v_add_f32_e32 v58, 1.0, v58
	v_cmp_gt_f32_e32 vcc, s92, v58
	s_nop 1
	v_cndmask_b32_e64 v60, 0, 32, vcc
	v_ldexp_f32 v58, v58, v60
	v_log_f32_e32 v58, v58
	s_nop 0
	v_mul_f32_e32 v60, 0x3f317217, v58
	v_fma_f32 v60, v58, s94, -v60
	v_fmac_f32_e32 v60, 0x3377d1cf, v58
	v_fmac_f32_e32 v60, 0x3f317217, v58
	v_cmp_lt_f32_e64 s[0:1], |v58|, s95
	s_nop 1
	v_cndmask_b32_e64 v58, v58, v60, s[0:1]
	v_cndmask_b32_e32 v60, 0, v239, vcc
	v_sub_f32_e32 v58, v58, v60
	v_add_f32_e32 v58, v59, v58
	v_mul_f32_e32 v59, 0xbd800000, v58
	v_mov_b32_e32 v60, v49
	s_nop 1
	v_mov_b32_dpp v60, v59 row_shr:1 row_mask:0xf bank_mask:0xf
	v_fmac_f32_e32 v60, 0xbd800000, v58
	s_nop 1
	v_add_f32_dpp v59, v60, v60 row_shr:2 row_mask:0xf bank_mask:0xf bound_ctrl:1
	v_mov_b32_e32 v60, v49
	s_nop 0
	v_add_f32_dpp v59, v59, v59 row_shr:4 row_mask:0xf bank_mask:0xf bound_ctrl:1
	s_nop 1
	v_add_f32_dpp v59, v59, v59 row_shr:8 row_mask:0xf bank_mask:0xf bound_ctrl:1
	s_nop 1
	v_mov_b32_dpp v60, v59 row_bcast:15 row_mask:0xa bank_mask:0xf
	v_add_f32_e32 v59, v59, v60
	v_mov_b32_e32 v60, v49
	s_nop 1
	v_mov_b32_dpp v60, v59 row_bcast:31 row_mask:0xc bank_mask:0xf
	v_add_f32_e32 v59, v59, v60
	s_nop 0
	v_readlane_b32 s21, v59, 63
	s_nop 1
	v_sub_f32_e32 v60, s21, v59
	v_fmac_f32_e32 v59, 0x3d800000, v58
	v_cndmask_b32_e64 v60, v59, v60, s[8:9]
	v_pk_mul_f32 v[58:59], v[116:117], v[206:207]
	s_nop 0
	v_add_f32_e32 v58, v61, v58
	v_add_f32_e32 v61, v58, v59
	v_pk_mul_f32 v[58:59], v[124:125], v[204:205]
	s_nop 0
	v_add_f32_e32 v58, v61, v58
	v_add_f32_e32 v58, v58, v59
	v_max_f32_e64 v59, -v58, 0
	v_mul_f32_e64 v58, |v58|, s93
	v_exp_f32_e32 v58, v58
	s_nop 0
	v_add_f32_e32 v58, 1.0, v58
	v_cmp_gt_f32_e32 vcc, s92, v58
	s_nop 1
	v_cndmask_b32_e64 v61, 0, 32, vcc
	v_ldexp_f32 v58, v58, v61
	v_log_f32_e32 v58, v58
	s_nop 0
	v_mul_f32_e32 v61, 0x3f317217, v58
	v_fma_f32 v61, v58, s94, -v61
	v_fmac_f32_e32 v61, 0x3377d1cf, v58
	v_fmac_f32_e32 v61, 0x3f317217, v58
	v_cmp_lt_f32_e64 s[0:1], |v58|, s95
	s_nop 1
	v_cndmask_b32_e64 v58, v58, v61, s[0:1]
	v_cndmask_b32_e32 v61, 0, v239, vcc
	v_sub_f32_e32 v58, v58, v61
	v_add_f32_e32 v58, v59, v58
	v_mul_f32_e32 v59, 0xbd800000, v58
	v_mov_b32_e32 v61, v49
	v_readlane_b32 s0, v254, 10
	s_add_u32 s0, s90, s0
	v_mov_b32_dpp v61, v59 row_shr:1 row_mask:0xf bank_mask:0xf
	v_fmac_f32_e32 v61, 0xbd800000, v58
	v_readlane_b32 s1, v254, 12
	s_addc_u32 s1, s15, s1
	v_add_f32_dpp v59, v61, v61 row_shr:2 row_mask:0xf bank_mask:0xf bound_ctrl:1
	v_mov_b32_e32 v61, v49
	s_lshl_b64 s[0:1], s[0:1], 10
	v_add_f32_dpp v59, v59, v59 row_shr:4 row_mask:0xf bank_mask:0xf bound_ctrl:1
	s_nop 1
	v_add_f32_dpp v59, v59, v59 row_shr:8 row_mask:0xf bank_mask:0xf bound_ctrl:1
	s_nop 1
	v_mov_b32_dpp v61, v59 row_bcast:15 row_mask:0xa bank_mask:0xf
	v_add_f32_e32 v59, v59, v61
	v_mov_b32_e32 v61, v49
	s_nop 1
	v_mov_b32_dpp v61, v59 row_bcast:31 row_mask:0xc bank_mask:0xf
	v_add_f32_e32 v59, v59, v61
	s_nop 0
	v_readlane_b32 s18, v59, 63
	s_nop 1
	v_sub_f32_e32 v61, s18, v59
	v_fmac_f32_e32 v59, 0x3d800000, v58
	v_cndmask_b32_e64 v58, v59, v61, s[8:9]
	v_mul_f32_e32 v59, 0x3fb8aa3b, v126
	v_exp_f32_e32 v72, v59
	v_mul_f32_e32 v59, 0x3fb8aa3b, v127
	v_mul_f32_e32 v58, 0x3fb8aa3b, v58
	v_exp_f32_e32 v73, v59
	v_exp_f32_e32 v78, v58
	v_cvt_pk_bf16_f32 v58, v48, v72
	v_mul_f32_e32 v48, v48, v64
	v_mul_f32_e32 v59, 0x3fb8aa3b, v130
	v_cvt_pk_bf16_f32 v48, v48, s0
	v_exp_f32_e32 v74, v59
	ds_write_b16 v208, v48 offset:59904
	v_mul_f32_e32 v48, v72, v65
	v_mul_f32_e32 v59, 0x3fb8aa3b, v62
	v_cvt_pk_bf16_f32 v48, v48, s0
	v_exp_f32_e32 v75, v59
	ds_write_b16 v208, v48 offset:60048
	v_mul_f32_e32 v48, v73, v66
	v_mul_f32_e32 v59, 0x3fb8aa3b, v63
	v_cvt_pk_bf16_f32 v48, v48, s0
	v_exp_f32_e32 v76, v59
	ds_write_b16 v208, v48 offset:60192
	v_mul_f32_e32 v48, v74, v67
	v_mul_f32_e32 v59, 0x3fb8aa3b, v60
	v_cvt_pk_bf16_f32 v48, v48, s0
	v_exp_f32_e32 v77, v59
	ds_write_b16 v208, v48 offset:60336
	v_mul_f32_e32 v48, v75, v68
	v_cvt_pk_bf16_f32 v48, v48, s0
	ds_write_b16 v208, v48 offset:60480
	v_mul_f32_e32 v48, v76, v69
	v_cvt_pk_bf16_f32 v48, v48, s0
	ds_write_b16 v208, v48 offset:60624
	v_mul_f32_e32 v48, v77, v70
	v_cvt_pk_bf16_f32 v48, v48, s0
	ds_write_b16 v208, v48 offset:60768
	v_mul_f32_e32 v48, v78, v71
	v_cvt_pk_bf16_f32 v59, v73, v74
	v_cvt_pk_bf16_f32 v60, v75, v76
	v_cvt_pk_bf16_f32 v61, v77, v78
	v_lshl_add_u64 v[62:63], v[202:203], 0, s[0:1]
	v_cvt_pk_bf16_f32 v48, v48, s0
	global_store_dwordx4 v[62:63], v[58:61], off
	ds_write_b16 v208, v48 offset:60912
	s_and_saveexec_b64 s[0:1], s[10:11]
	s_cbranch_execz .LBB0_667
	v_mul_f32_e32 v48, s4, v240
	v_exp_f32_e32 v58, v48
	v_mul_f32_e32 v48, s5, v240
	v_exp_f32_e32 v59, v48
	v_mul_f32_e32 v48, s6, v240
	v_exp_f32_e32 v60, v48
	v_mul_f32_e32 v48, s7, v240
	v_exp_f32_e32 v61, v48
	v_mul_f32_e32 v48, s91, v240
	v_exp_f32_e32 v62, v48
	v_mul_f32_e32 v48, s20, v240
	v_exp_f32_e32 v63, v48
	v_mul_f32_e32 v48, s21, v240
	v_exp_f32_e32 v64, v48
	v_mul_f32_e32 v48, s18, v240
	v_exp_f32_e32 v65, v48
	s_add_u32 s4, s16, s88
	s_addc_u32 s5, s17, s89
	global_store_dwordx4 v49, v[58:61], s[4:5] offset:128
	global_store_dwordx4 v49, v[62:65], s[4:5] offset:144
.LBB0_667:
	s_or_b64 exec, exec, s[0:1]
	v_lshrrev_b32_e32 v182, 6, v198
	v_and_b32_e32 v183, 1, v182
	v_lshrrev_b32_e32 v182, 1, v182
	v_mul_u32_u24_e32 v183, 0x3000, v183
	v_lshl_add_u32 v183, v182, 7, v183
	v_lshl_add_u32 v182, v182, 6, v183
	v_add_u32_e32 v182, 0x1b000, v182
	ds_read_b128 v[58:61], v182 offset:24752
	ds_read_b128 v[126:129], v182 offset:24736
	ds_read_b128 v[62:65], v182 offset:176
	ds_read_b128 v[130:133], v182 offset:160
	ds_read_b128 v[66:69], v182 offset:944
	ds_read_b128 v[134:137], v182 offset:928
	ds_read_b128 v[70:73], v182 offset:1712
	ds_read_b128 v[138:141], v182 offset:1696
	ds_read_b128 v[74:77], v182 offset:2480
	ds_read_b128 v[142:145], v182 offset:2464
	ds_read_b128 v[78:81], v182 offset:3248
	ds_read_b128 v[146:149], v182 offset:3232
	s_waitcnt lgkmcnt(8)
	ds_read_b128 v[82:85], v182 offset:4016
	ds_read_b128 v[150:153], v182 offset:4000
	ds_read_b128 v[86:89], v182 offset:4784
	ds_read_b128 v[154:157], v182 offset:4768
	s_waitcnt lgkmcnt(8)
	ds_read_b128 v[90:93], v182 offset:5552
	ds_read_b128 v[158:161], v182 offset:5536
	ds_read_b128 v[94:97], v182 offset:6320
	ds_read_b128 v[162:165], v182 offset:6304
	s_waitcnt lgkmcnt(8)
	ds_read_b128 v[98:101], v182 offset:7088
	ds_read_b128 v[166:169], v182 offset:7072
	ds_read_b128 v[102:105], v182 offset:7856
	ds_read_b128 v[170:173], v182 offset:7840
	s_waitcnt lgkmcnt(8)
	ds_read_b128 v[106:109], v182 offset:8624
	ds_read_b128 v[174:177], v182 offset:8608
	ds_read_b128 v[110:113], v182 offset:9392
	ds_read_b128 v[178:181], v182 offset:9376
	s_waitcnt lgkmcnt(8)
	ds_read_b128 v[114:117], v182 offset:10160
	ds_read_b128 v[182:185], v182 offset:10144
	s_waitcnt lgkmcnt(14)
	v_fma_f32 v58, v62, v242, v58
	s_waitcnt lgkmcnt(14)
	v_fma_f32 v48, v130, v242, v126
	s_waitcnt lgkmcnt(14)
	v_fmac_f32_e32 v48, v134, v223
	s_waitcnt lgkmcnt(14)
	v_fmac_f32_e32 v48, v138, v222
	s_waitcnt lgkmcnt(14)
	v_fmac_f32_e32 v48, v142, v221
	s_waitcnt lgkmcnt(14)
	v_fmac_f32_e32 v48, v146, v220
	s_waitcnt lgkmcnt(14)
	v_fmac_f32_e32 v48, v150, v219
	s_waitcnt lgkmcnt(14)
	v_fmac_f32_e32 v48, v154, v218
	s_waitcnt lgkmcnt(12)
	v_fmac_f32_e32 v48, v158, v217
	s_waitcnt lgkmcnt(10)
	v_fmac_f32_e32 v48, v162, v216
	s_waitcnt lgkmcnt(8)
	v_fmac_f32_e32 v48, v166, v215
	s_waitcnt lgkmcnt(6)
	v_fmac_f32_e32 v48, v170, v214
	s_waitcnt lgkmcnt(2)
	v_mov_b32_e32 v118, v178
	s_waitcnt lgkmcnt(0)
	v_mov_b32_e32 v119, v182
	v_fmac_f32_e32 v48, v174, v213
	v_pk_mul_f32 v[118:119], v[118:119], v[206:207]
	v_mov_b32_e32 v182, v179
	v_add_f32_e32 v48, v48, v118
	v_add_f32_e32 v48, v48, v119
	v_lshrrev_b32_e32 v190, 6, v198
	v_and_b32_e32 v191, 1, v190
	v_lshrrev_b32_e32 v190, 1, v190
	v_mul_u32_u24_e32 v191, 0x3000, v191
	v_lshl_add_u32 v191, v190, 7, v191
	v_lshl_add_u32 v190, v190, 6, v191
	v_add_u32_e32 v190, 0x1b000, v190
	ds_read_b128 v[118:121], v190 offset:10928
	ds_read_b128 v[186:189], v190 offset:10912
	ds_read_b128 v[122:125], v190 offset:11696
	ds_read_b128 v[190:193], v190 offset:11680
	v_fmac_f32_e32 v129, v133, v242
	v_fmac_f32_e32 v129, v137, v223
	v_fmac_f32_e32 v129, v141, v222
	v_fmac_f32_e32 v129, v145, v221
	v_fmac_f32_e32 v129, v149, v220
	v_fmac_f32_e32 v129, v153, v219
	v_fmac_f32_e32 v129, v157, v218
	v_fmac_f32_e32 v129, v161, v217
	v_fmac_f32_e32 v129, v165, v216
	v_fmac_f32_e32 v129, v169, v215
	v_fmac_f32_e32 v129, v173, v214
	v_fmac_f32_e32 v129, v177, v213
	v_fmac_f32_e32 v58, v66, v223
	v_fmac_f32_e32 v58, v70, v222
	v_fmac_f32_e32 v58, v74, v221
	v_fmac_f32_e32 v58, v78, v220
	v_fmac_f32_e32 v58, v82, v219
	v_fmac_f32_e32 v58, v86, v218
	v_fmac_f32_e32 v58, v90, v217
	v_fmac_f32_e32 v58, v94, v216
	v_fmac_f32_e32 v58, v98, v215
	v_fmac_f32_e32 v58, v102, v214
	v_fmac_f32_e32 v58, v106, v213
	v_fma_f32 v63, v63, v242, v59
	v_fmac_f32_e32 v63, v67, v223
	v_fmac_f32_e32 v63, v71, v222
	v_fmac_f32_e32 v63, v75, v221
	v_fmac_f32_e32 v63, v79, v220
	v_fmac_f32_e32 v63, v83, v219
	v_fmac_f32_e32 v63, v87, v218
	v_fmac_f32_e32 v63, v91, v217
	v_fmac_f32_e32 v63, v95, v216
	v_fmac_f32_e32 v63, v99, v215
	v_fmac_f32_e32 v63, v103, v214
	v_fmac_f32_e32 v63, v107, v213
	v_fma_f32 v60, v64, v242, v60
	v_fmac_f32_e32 v60, v68, v223
	v_fmac_f32_e32 v60, v72, v222
	v_fmac_f32_e32 v60, v76, v221
	v_fmac_f32_e32 v60, v80, v220
	v_fmac_f32_e32 v60, v84, v219
	v_fmac_f32_e32 v60, v88, v218
	v_fmac_f32_e32 v60, v92, v217
	v_fmac_f32_e32 v60, v96, v216
	v_fmac_f32_e32 v60, v100, v215
	v_fmac_f32_e32 v60, v104, v214
	v_fmac_f32_e32 v60, v108, v213
	v_fmac_f32_e32 v61, v65, v242
	v_fmac_f32_e32 v61, v69, v223
	v_fmac_f32_e32 v61, v73, v222
	v_fmac_f32_e32 v61, v77, v221
	v_fmac_f32_e32 v61, v81, v220
	v_fmac_f32_e32 v61, v85, v219
	v_fmac_f32_e32 v61, v89, v218
	v_fmac_f32_e32 v61, v93, v217
	v_fmac_f32_e32 v61, v97, v216
	v_fmac_f32_e32 v61, v101, v215
	v_fmac_f32_e32 v61, v105, v214
	v_fmac_f32_e32 v61, v109, v213
	v_lshlrev_b32_e32 v64, 16, v54
	v_and_b32_e32 v65, 0xffff0000, v54
	v_and_b32_e32 v67, 0xffff0000, v55
	v_lshlrev_b32_e32 v68, 16, v56
	v_and_b32_e32 v69, 0xffff0000, v56
	v_lshlrev_b32_e32 v70, 16, v57
	v_and_b32_e32 v71, 0xffff0000, v57
	s_waitcnt lgkmcnt(2)
	v_mov_b32_e32 v244, v186
	s_waitcnt lgkmcnt(0)
	v_mov_b32_e32 v245, v190
	v_pk_mul_f32 v[244:245], v[244:245], v[204:205]
	v_mov_b32_e32 v190, v187
	v_add_f32_e32 v48, v48, v244
	v_add_f32_e32 v48, v48, v245
	v_max_f32_e64 v126, -v48, 0
	v_mul_f32_e64 v48, |v48|, s93
	v_exp_f32_e32 v48, v48
	s_nop 0
	v_add_f32_e32 v48, 1.0, v48
	v_cmp_gt_f32_e32 vcc, s92, v48
	s_nop 1
	v_cndmask_b32_e64 v130, 0, 32, vcc
	v_ldexp_f32 v48, v48, v130
	v_log_f32_e32 v48, v48
	s_nop 0
	v_mul_f32_e32 v130, 0x3f317217, v48
	v_fma_f32 v130, v48, s94, -v130
	v_fmac_f32_e32 v130, 0x3377d1cf, v48
	v_fmac_f32_e32 v130, 0x3f317217, v48
	v_cmp_lt_f32_e64 s[0:1], |v48|, s95
	s_nop 1
	v_cndmask_b32_e64 v48, v48, v130, s[0:1]
	v_cndmask_b32_e32 v130, 0, v239, vcc
	v_sub_f32_e32 v48, v48, v130
	v_add_f32_e32 v48, v126, v48
	v_mul_f32_e32 v126, 0xbd800000, v48
	v_mov_b32_e32 v130, v49
	s_nop 1
	v_mov_b32_dpp v130, v126 row_shr:1 row_mask:0xf bank_mask:0xf
	v_fmac_f32_e32 v130, 0xbd800000, v48
	s_nop 1
	v_add_f32_dpp v126, v130, v130 row_shr:2 row_mask:0xf bank_mask:0xf bound_ctrl:1
	v_mov_b32_e32 v130, v49
	s_nop 0
	v_add_f32_dpp v126, v126, v126 row_shr:4 row_mask:0xf bank_mask:0xf bound_ctrl:1
	s_nop 1
	v_add_f32_dpp v126, v126, v126 row_shr:8 row_mask:0xf bank_mask:0xf bound_ctrl:1
	s_nop 1
	v_mov_b32_dpp v130, v126 row_bcast:15 row_mask:0xa bank_mask:0xf
	v_add_f32_e32 v126, v126, v130
	v_mov_b32_e32 v130, v49
	s_nop 1
	v_mov_b32_dpp v130, v126 row_bcast:31 row_mask:0xc bank_mask:0xf
	v_add_f32_e32 v126, v126, v130
	s_nop 0
	v_readlane_b32 s4, v126, 63
	s_nop 1
	v_sub_f32_e32 v130, s4, v126
	v_fmac_f32_e32 v126, 0x3d800000, v48
	v_cndmask_b32_e64 v48, v126, v130, s[8:9]
	v_fma_f32 v130, v131, v242, v127
	v_fmac_f32_e32 v130, v135, v223
	v_fmac_f32_e32 v130, v139, v222
	v_fmac_f32_e32 v130, v143, v221
	v_fmac_f32_e32 v130, v147, v220
	v_fmac_f32_e32 v130, v151, v219
	v_fmac_f32_e32 v130, v155, v218
	v_fmac_f32_e32 v130, v159, v217
	v_fmac_f32_e32 v130, v163, v216
	v_fmac_f32_e32 v130, v167, v215
	v_fmac_f32_e32 v130, v171, v214
	v_fmac_f32_e32 v130, v175, v213
	v_pk_mul_f32 v[126:127], v[182:183], v[206:207]
	v_mov_b32_e32 v131, v184
	v_add_f32_e32 v126, v130, v126
	v_add_f32_e32 v130, v126, v127
	v_pk_mul_f32 v[126:127], v[190:191], v[204:205]
	v_mov_b32_e32 v184, v181
	v_add_f32_e32 v126, v130, v126
	v_add_f32_e32 v126, v126, v127
	v_max_f32_e64 v127, -v126, 0
	v_mul_f32_e64 v126, |v126|, s93
	v_exp_f32_e32 v126, v126
	v_mul_f32_e32 v48, 0x3fb8aa3b, v48
	v_exp_f32_e32 v48, v48
	v_add_f32_e32 v126, 1.0, v126
	v_cmp_gt_f32_e32 vcc, s92, v126
	s_nop 1
	v_cndmask_b32_e64 v130, 0, 32, vcc
	v_ldexp_f32 v126, v126, v130
	v_log_f32_e32 v126, v126
	s_nop 0
	v_mul_f32_e32 v130, 0x3f317217, v126
	v_fma_f32 v130, v126, s94, -v130
	v_fmac_f32_e32 v130, 0x3377d1cf, v126
	v_fmac_f32_e32 v130, 0x3f317217, v126
	v_cmp_lt_f32_e64 s[0:1], |v126|, s95
	s_nop 1
	v_cndmask_b32_e64 v126, v126, v130, s[0:1]
	v_cndmask_b32_e32 v130, 0, v239, vcc
	v_sub_f32_e32 v126, v126, v130
	v_add_f32_e32 v126, v127, v126
	v_mul_f32_e32 v127, 0xbd800000, v126
	v_mov_b32_e32 v130, v49
	s_nop 1
	v_mov_b32_dpp v130, v127 row_shr:1 row_mask:0xf bank_mask:0xf
	v_fmac_f32_e32 v130, 0xbd800000, v126
	s_nop 1
	v_add_f32_dpp v127, v130, v130 row_shr:2 row_mask:0xf bank_mask:0xf bound_ctrl:1
	v_mov_b32_e32 v130, v49
	s_nop 0
	v_add_f32_dpp v127, v127, v127 row_shr:4 row_mask:0xf bank_mask:0xf bound_ctrl:1
	s_nop 1
	v_add_f32_dpp v127, v127, v127 row_shr:8 row_mask:0xf bank_mask:0xf bound_ctrl:1
	s_nop 1
	v_mov_b32_dpp v130, v127 row_bcast:15 row_mask:0xa bank_mask:0xf
	v_add_f32_e32 v127, v127, v130
	v_mov_b32_e32 v130, v49
	s_nop 1
	v_mov_b32_dpp v130, v127 row_bcast:31 row_mask:0xc bank_mask:0xf
	v_add_f32_e32 v127, v127, v130
	s_nop 0
	v_readlane_b32 s5, v127, 63
	s_nop 1
	v_sub_f32_e32 v130, s5, v127
	v_fmac_f32_e32 v127, 0x3d800000, v126
	v_cndmask_b32_e64 v126, v127, v130, s[8:9]
	v_fma_f32 v127, v132, v242, v128
	v_fmac_f32_e32 v127, v136, v223
	v_fmac_f32_e32 v127, v140, v222
	v_fmac_f32_e32 v127, v144, v221
	v_fmac_f32_e32 v127, v148, v220
	v_fmac_f32_e32 v127, v152, v219
	v_fmac_f32_e32 v127, v156, v218
	v_fmac_f32_e32 v127, v160, v217
	v_fmac_f32_e32 v127, v164, v216
	v_fmac_f32_e32 v127, v168, v215
	v_fmac_f32_e32 v127, v172, v214
	v_mov_b32_e32 v130, v180
	v_fmac_f32_e32 v127, v176, v213
	v_pk_mul_f32 v[130:131], v[130:131], v[206:207]
	s_nop 0
	v_add_f32_e32 v127, v127, v130
	v_add_f32_e32 v127, v127, v131
	v_mov_b32_e32 v130, v188
	v_mov_b32_e32 v131, v192
	v_pk_mul_f32 v[130:131], v[130:131], v[204:205]
	v_mov_b32_e32 v192, v189
	v_add_f32_e32 v127, v127, v130
	v_add_f32_e32 v127, v127, v131
	v_max_f32_e64 v128, -v127, 0
	v_mul_f32_e64 v127, |v127|, s93
	v_exp_f32_e32 v127, v127
	s_nop 0
	v_add_f32_e32 v127, 1.0, v127
	v_cmp_gt_f32_e32 vcc, s92, v127
	s_nop 1
	v_cndmask_b32_e64 v130, 0, 32, vcc
	v_ldexp_f32 v127, v127, v130
	v_log_f32_e32 v127, v127
	s_nop 0
	v_mul_f32_e32 v130, 0x3f317217, v127
	v_fma_f32 v130, v127, s94, -v130
	v_fmac_f32_e32 v130, 0x3377d1cf, v127
	v_fmac_f32_e32 v130, 0x3f317217, v127
	v_cmp_lt_f32_e64 s[0:1], |v127|, s95
	s_nop 1
	v_cndmask_b32_e64 v127, v127, v130, s[0:1]
	v_cndmask_b32_e32 v130, 0, v239, vcc
	v_sub_f32_e32 v127, v127, v130
	v_add_f32_e32 v127, v128, v127
	v_mul_f32_e32 v128, 0xbd800000, v127
	v_mov_b32_e32 v130, v49
	s_nop 1
	v_mov_b32_dpp v130, v128 row_shr:1 row_mask:0xf bank_mask:0xf
	v_fmac_f32_e32 v130, 0xbd800000, v127
	s_nop 1
	v_add_f32_dpp v128, v130, v130 row_shr:2 row_mask:0xf bank_mask:0xf bound_ctrl:1
	v_mov_b32_e32 v130, v49
	s_nop 0
	v_add_f32_dpp v128, v128, v128 row_shr:4 row_mask:0xf bank_mask:0xf bound_ctrl:1
	s_nop 1
	v_add_f32_dpp v128, v128, v128 row_shr:8 row_mask:0xf bank_mask:0xf bound_ctrl:1
	s_nop 1
	v_mov_b32_dpp v130, v128 row_bcast:15 row_mask:0xa bank_mask:0xf
	v_add_f32_e32 v128, v128, v130
	v_mov_b32_e32 v130, v49
	s_nop 1
	v_mov_b32_dpp v130, v128 row_bcast:31 row_mask:0xc bank_mask:0xf
	v_add_f32_e32 v128, v128, v130
	s_nop 0
	v_readlane_b32 s6, v128, 63
	s_nop 1
	v_sub_f32_e32 v130, s6, v128
	v_fmac_f32_e32 v128, 0x3d800000, v127
	v_cndmask_b32_e64 v127, v128, v130, s[8:9]
	v_pk_mul_f32 v[130:131], v[184:185], v[206:207]
	s_nop 0
	v_add_f32_e32 v128, v129, v130
	v_add_f32_e32 v130, v128, v131
	v_pk_mul_f32 v[128:129], v[192:193], v[204:205]
	s_nop 0
	v_add_f32_e32 v128, v130, v128
	v_add_f32_e32 v128, v128, v129
	v_max_f32_e64 v129, -v128, 0
	v_mul_f32_e64 v128, |v128|, s93
	v_exp_f32_e32 v128, v128
	s_nop 0
	v_add_f32_e32 v128, 1.0, v128
	v_cmp_gt_f32_e32 vcc, s92, v128
	s_nop 1
	v_cndmask_b32_e64 v130, 0, 32, vcc
	v_ldexp_f32 v128, v128, v130
	v_log_f32_e32 v128, v128
	s_nop 0
	v_mul_f32_e32 v130, 0x3f317217, v128
	v_fma_f32 v130, v128, s94, -v130
	v_fmac_f32_e32 v130, 0x3377d1cf, v128
	v_fmac_f32_e32 v130, 0x3f317217, v128
	v_cmp_lt_f32_e64 s[0:1], |v128|, s95
	s_nop 1
	v_cndmask_b32_e64 v128, v128, v130, s[0:1]
	v_cndmask_b32_e32 v130, 0, v239, vcc
	v_sub_f32_e32 v128, v128, v130
	v_add_f32_e32 v128, v129, v128
	v_mul_f32_e32 v129, 0xbd800000, v128
	v_mov_b32_e32 v130, v49
	s_nop 1
	v_mov_b32_dpp v130, v129 row_shr:1 row_mask:0xf bank_mask:0xf
	v_fmac_f32_e32 v130, 0xbd800000, v128
	s_nop 1
	v_add_f32_dpp v129, v130, v130 row_shr:2 row_mask:0xf bank_mask:0xf bound_ctrl:1
	v_mov_b32_e32 v130, v49
	s_nop 0
	v_add_f32_dpp v129, v129, v129 row_shr:4 row_mask:0xf bank_mask:0xf bound_ctrl:1
	s_nop 1
	v_add_f32_dpp v129, v129, v129 row_shr:8 row_mask:0xf bank_mask:0xf bound_ctrl:1
	s_nop 1
	v_mov_b32_dpp v130, v129 row_bcast:15 row_mask:0xa bank_mask:0xf
	v_add_f32_e32 v129, v129, v130
	v_mov_b32_e32 v130, v49
	s_nop 1
	v_mov_b32_dpp v130, v129 row_bcast:31 row_mask:0xc bank_mask:0xf
	v_add_f32_e32 v129, v129, v130
	s_nop 0
	v_readlane_b32 s7, v129, 63
	s_nop 1
	v_sub_f32_e32 v130, s7, v129
	v_fmac_f32_e32 v129, 0x3d800000, v128
	v_cndmask_b32_e64 v130, v129, v130, s[8:9]
	v_mov_b32_e32 v128, v110
	v_mov_b32_e32 v129, v114
	v_pk_mul_f32 v[128:129], v[128:129], v[206:207]
	v_mov_b32_e32 v114, v111
	v_add_f32_e32 v58, v58, v128
	v_add_f32_e32 v58, v58, v129
	v_mov_b32_e32 v128, v118
	v_mov_b32_e32 v129, v122
	v_pk_mul_f32 v[128:129], v[128:129], v[204:205]
	v_mov_b32_e32 v122, v119
	v_add_f32_e32 v58, v58, v128
	v_add_f32_e32 v58, v58, v129
	v_max_f32_e64 v62, -v58, 0
	v_mul_f32_e64 v58, |v58|, s93
	v_exp_f32_e32 v58, v58
	s_nop 0
	v_add_f32_e32 v58, 1.0, v58
	v_cmp_gt_f32_e32 vcc, s92, v58
	s_nop 1
	v_cndmask_b32_e64 v66, 0, 32, vcc
	v_ldexp_f32 v58, v58, v66
	v_log_f32_e32 v58, v58
	s_nop 0
	v_mul_f32_e32 v66, 0x3f317217, v58
	v_fma_f32 v66, v58, s94, -v66
	v_fmac_f32_e32 v66, 0x3377d1cf, v58
	v_fmac_f32_e32 v66, 0x3f317217, v58
	v_cmp_lt_f32_e64 s[0:1], |v58|, s95
	s_nop 1
	v_cndmask_b32_e64 v58, v58, v66, s[0:1]
	v_cndmask_b32_e32 v66, 0, v239, vcc
	v_sub_f32_e32 v58, v58, v66
	v_add_f32_e32 v58, v62, v58
	v_mul_f32_e32 v62, 0xbd800000, v58
	v_mov_b32_e32 v66, v49
	s_nop 1
	v_mov_b32_dpp v66, v62 row_shr:1 row_mask:0xf bank_mask:0xf
	v_fmac_f32_e32 v66, 0xbd800000, v58
	s_nop 1
	v_add_f32_dpp v62, v66, v66 row_shr:2 row_mask:0xf bank_mask:0xf bound_ctrl:1
	v_mov_b32_e32 v66, v49
	s_nop 0
	v_add_f32_dpp v62, v62, v62 row_shr:4 row_mask:0xf bank_mask:0xf bound_ctrl:1
	s_nop 1
	v_add_f32_dpp v62, v62, v62 row_shr:8 row_mask:0xf bank_mask:0xf bound_ctrl:1
	s_nop 1
	v_mov_b32_dpp v66, v62 row_bcast:15 row_mask:0xa bank_mask:0xf
	v_add_f32_e32 v62, v62, v66
	v_mov_b32_e32 v66, v49
	s_nop 1
	v_mov_b32_dpp v66, v62 row_bcast:31 row_mask:0xc bank_mask:0xf
	v_add_f32_e32 v62, v62, v66
	s_nop 0
	v_readlane_b32 s20, v62, 63
	s_nop 1
	v_sub_f32_e32 v66, s20, v62
	v_fmac_f32_e32 v62, 0x3d800000, v58
	v_pk_mul_f32 v[58:59], v[114:115], v[206:207]
	v_cndmask_b32_e64 v62, v62, v66, s[8:9]
	v_add_f32_e32 v58, v63, v58
	v_add_f32_e32 v63, v58, v59
	v_pk_mul_f32 v[58:59], v[122:123], v[204:205]
	v_lshlrev_b32_e32 v66, 16, v55
	v_add_f32_e32 v58, v63, v58
	v_add_f32_e32 v58, v58, v59
	v_max_f32_e64 v59, -v58, 0
	v_mul_f32_e64 v58, |v58|, s93
	v_exp_f32_e32 v58, v58
	s_nop 0
	v_add_f32_e32 v58, 1.0, v58
	v_cmp_gt_f32_e32 vcc, s92, v58
	s_nop 1
	v_cndmask_b32_e64 v63, 0, 32, vcc
	v_ldexp_f32 v58, v58, v63
	v_log_f32_e32 v58, v58
	s_nop 0
	v_mul_f32_e32 v63, 0x3f317217, v58
	v_fma_f32 v63, v58, s94, -v63
	v_fmac_f32_e32 v63, 0x3377d1cf, v58
	v_fmac_f32_e32 v63, 0x3f317217, v58
	v_cmp_lt_f32_e64 s[0:1], |v58|, s95
	s_nop 1
	v_cndmask_b32_e64 v58, v58, v63, s[0:1]
	v_cndmask_b32_e32 v63, 0, v239, vcc
	v_sub_f32_e32 v58, v58, v63
	v_add_f32_e32 v58, v59, v58
	v_mul_f32_e32 v59, 0xbd800000, v58
	v_mov_b32_e32 v63, v49
	s_nop 1
	v_mov_b32_dpp v63, v59 row_shr:1 row_mask:0xf bank_mask:0xf
	v_fmac_f32_e32 v63, 0xbd800000, v58
	s_nop 1
	v_add_f32_dpp v59, v63, v63 row_shr:2 row_mask:0xf bank_mask:0xf bound_ctrl:1
	v_mov_b32_e32 v63, v49
	s_nop 0
	v_add_f32_dpp v59, v59, v59 row_shr:4 row_mask:0xf bank_mask:0xf bound_ctrl:1
	s_nop 1
	v_add_f32_dpp v59, v59, v59 row_shr:8 row_mask:0xf bank_mask:0xf bound_ctrl:1
	s_nop 1
	v_mov_b32_dpp v63, v59 row_bcast:15 row_mask:0xa bank_mask:0xf
	v_add_f32_e32 v59, v59, v63
	v_mov_b32_e32 v63, v49
	s_nop 1
	v_mov_b32_dpp v63, v59 row_bcast:31 row_mask:0xc bank_mask:0xf
	v_add_f32_e32 v59, v59, v63
	s_nop 0
	v_readlane_b32 s21, v59, 63
	s_nop 1
	v_sub_f32_e32 v63, s21, v59
	v_fmac_f32_e32 v59, 0x3d800000, v58
	v_cndmask_b32_e64 v63, v59, v63, s[8:9]
	v_mov_b32_e32 v58, v112
	v_mov_b32_e32 v59, v116
	v_pk_mul_f32 v[58:59], v[58:59], v[206:207]
	v_mov_b32_e32 v116, v113
	v_add_f32_e32 v58, v60, v58
	v_add_f32_e32 v60, v58, v59
	v_mov_b32_e32 v58, v120
	v_mov_b32_e32 v59, v124
	v_pk_mul_f32 v[58:59], v[58:59], v[204:205]
	v_mov_b32_e32 v124, v121
	v_add_f32_e32 v58, v60, v58
	v_add_f32_e32 v58, v58, v59
	v_max_f32_e64 v59, -v58, 0
	v_mul_f32_e64 v58, |v58|, s93
	v_exp_f32_e32 v58, v58
	s_nop 0
	v_add_f32_e32 v58, 1.0, v58
	v_cmp_gt_f32_e32 vcc, s92, v58
	s_nop 1
	v_cndmask_b32_e64 v60, 0, 32, vcc
	v_ldexp_f32 v58, v58, v60
	v_log_f32_e32 v58, v58
	s_nop 0
	v_mul_f32_e32 v60, 0x3f317217, v58
	v_fma_f32 v60, v58, s94, -v60
	v_fmac_f32_e32 v60, 0x3377d1cf, v58
	v_fmac_f32_e32 v60, 0x3f317217, v58
	v_cmp_lt_f32_e64 s[0:1], |v58|, s95
	s_nop 1
	v_cndmask_b32_e64 v58, v58, v60, s[0:1]
	v_cndmask_b32_e32 v60, 0, v239, vcc
	v_sub_f32_e32 v58, v58, v60
	v_add_f32_e32 v58, v59, v58
	v_mul_f32_e32 v59, 0xbd800000, v58
	v_mov_b32_e32 v60, v49
	s_nop 1
	v_mov_b32_dpp v60, v59 row_shr:1 row_mask:0xf bank_mask:0xf
	v_fmac_f32_e32 v60, 0xbd800000, v58
	s_nop 1
	v_add_f32_dpp v59, v60, v60 row_shr:2 row_mask:0xf bank_mask:0xf bound_ctrl:1
	v_mov_b32_e32 v60, v49
	s_nop 0
	v_add_f32_dpp v59, v59, v59 row_shr:4 row_mask:0xf bank_mask:0xf bound_ctrl:1
	s_nop 1
	v_add_f32_dpp v59, v59, v59 row_shr:8 row_mask:0xf bank_mask:0xf bound_ctrl:1
	s_nop 1
	v_mov_b32_dpp v60, v59 row_bcast:15 row_mask:0xa bank_mask:0xf
	v_add_f32_e32 v59, v59, v60
	v_mov_b32_e32 v60, v49
	s_nop 1
	v_mov_b32_dpp v60, v59 row_bcast:31 row_mask:0xc bank_mask:0xf
	v_add_f32_e32 v59, v59, v60
	s_nop 0
	v_readlane_b32 s18, v59, 63
	s_nop 1
	v_sub_f32_e32 v60, s18, v59
	v_fmac_f32_e32 v59, 0x3d800000, v58
	v_cndmask_b32_e64 v60, v59, v60, s[8:9]
	v_pk_mul_f32 v[58:59], v[116:117], v[206:207]
	s_nop 0
	v_add_f32_e32 v58, v61, v58
	v_add_f32_e32 v61, v58, v59
	v_pk_mul_f32 v[58:59], v[124:125], v[204:205]
	s_nop 0
	v_add_f32_e32 v58, v61, v58
	v_add_f32_e32 v58, v58, v59
	v_max_f32_e64 v59, -v58, 0
	v_mul_f32_e64 v58, |v58|, s93
	v_exp_f32_e32 v58, v58
	s_nop 0
	v_add_f32_e32 v58, 1.0, v58
	v_cmp_gt_f32_e32 vcc, s92, v58
	s_nop 1
	v_cndmask_b32_e64 v61, 0, 32, vcc
	v_ldexp_f32 v58, v58, v61
	v_log_f32_e32 v58, v58
	s_nop 0
	v_mul_f32_e32 v61, 0x3f317217, v58
	v_fma_f32 v61, v58, s94, -v61
	v_fmac_f32_e32 v61, 0x3377d1cf, v58
	v_fmac_f32_e32 v61, 0x3f317217, v58
	v_cmp_lt_f32_e64 s[0:1], |v58|, s95
	s_nop 1
	v_cndmask_b32_e64 v58, v58, v61, s[0:1]
	v_cndmask_b32_e32 v61, 0, v239, vcc
	v_sub_f32_e32 v58, v58, v61
	v_add_f32_e32 v58, v59, v58
	v_mul_f32_e32 v59, 0xbd800000, v58
	v_mov_b32_e32 v61, v49
	v_readlane_b32 s0, v254, 14
	s_add_u32 s0, s90, s0
	v_mov_b32_dpp v61, v59 row_shr:1 row_mask:0xf bank_mask:0xf
	v_fmac_f32_e32 v61, 0xbd800000, v58
	v_readlane_b32 s1, v254, 16
	s_addc_u32 s1, s15, s1
	v_add_f32_dpp v59, v61, v61 row_shr:2 row_mask:0xf bank_mask:0xf bound_ctrl:1
	v_mov_b32_e32 v61, v49
	s_lshl_b64 s[0:1], s[0:1], 10
	v_add_f32_dpp v59, v59, v59 row_shr:4 row_mask:0xf bank_mask:0xf bound_ctrl:1
	s_mov_b64 s[90:91], 0
	s_nop 0
	v_add_f32_dpp v59, v59, v59 row_shr:8 row_mask:0xf bank_mask:0xf bound_ctrl:1
	s_nop 1
	v_mov_b32_dpp v61, v59 row_bcast:15 row_mask:0xa bank_mask:0xf
	v_add_f32_e32 v59, v59, v61
	v_mov_b32_e32 v61, v49
	s_nop 1
	v_mov_b32_dpp v61, v59 row_bcast:31 row_mask:0xc bank_mask:0xf
	v_add_f32_e32 v59, v59, v61
	s_nop 0
	v_readlane_b32 s19, v59, 63
	s_nop 1
	v_sub_f32_e32 v61, s19, v59
	v_fmac_f32_e32 v59, 0x3d800000, v58
	v_cndmask_b32_e64 v58, v59, v61, s[8:9]
	v_mul_f32_e32 v59, 0x3fb8aa3b, v126
	v_exp_f32_e32 v72, v59
	v_mul_f32_e32 v59, 0x3fb8aa3b, v127
	v_mul_f32_e32 v58, 0x3fb8aa3b, v58
	v_exp_f32_e32 v73, v59
	v_exp_f32_e32 v78, v58
	v_cvt_pk_bf16_f32 v58, v48, v72
	v_mul_f32_e32 v48, v48, v64
	v_mul_f32_e32 v59, 0x3fb8aa3b, v130
	v_cvt_pk_bf16_f32 v48, v48, s0
	v_exp_f32_e32 v74, v59
	ds_write_b16 v208, v48 offset:61056
	v_mul_f32_e32 v48, v72, v65
	v_mul_f32_e32 v59, 0x3fb8aa3b, v62
	v_cvt_pk_bf16_f32 v48, v48, s0
	v_exp_f32_e32 v75, v59
	ds_write_b16 v208, v48 offset:61200
	v_mul_f32_e32 v48, v73, v66
	v_mul_f32_e32 v59, 0x3fb8aa3b, v63
	v_cvt_pk_bf16_f32 v48, v48, s0
	v_exp_f32_e32 v76, v59
	ds_write_b16 v208, v48 offset:61344
	v_mul_f32_e32 v48, v74, v67
	v_mul_f32_e32 v59, 0x3fb8aa3b, v60
	v_cvt_pk_bf16_f32 v48, v48, s0
	v_exp_f32_e32 v77, v59
	ds_write_b16 v208, v48 offset:61488
	v_mul_f32_e32 v48, v75, v68
	v_cvt_pk_bf16_f32 v48, v48, s0
	ds_write_b16 v208, v48 offset:61632
	v_mul_f32_e32 v48, v76, v69
	v_cvt_pk_bf16_f32 v48, v48, s0
	ds_write_b16 v208, v48 offset:61776
	v_mul_f32_e32 v48, v77, v70
	v_cvt_pk_bf16_f32 v48, v48, s0
	ds_write_b16 v208, v48 offset:61920
	v_mul_f32_e32 v48, v78, v71
	v_cvt_pk_bf16_f32 v59, v73, v74
	v_cvt_pk_bf16_f32 v60, v75, v76
	v_cvt_pk_bf16_f32 v61, v77, v78
	v_lshl_add_u64 v[62:63], v[202:203], 0, s[0:1]
	v_cvt_pk_bf16_f32 v48, v48, s0
	s_mov_b64 s[0:1], 0
	global_store_dwordx4 v[62:63], v[58:61], off
	ds_write_b16 v208, v48 offset:62064
	s_and_saveexec_b64 vcc, s[10:11]
	s_xor_b64 vcc, exec, vcc
	s_cbranch_execz .LBB0_669
	v_mul_f32_e32 v48, s4, v240
	v_exp_f32_e32 v58, v48
	v_mul_f32_e32 v48, s5, v240
	v_exp_f32_e32 v59, v48
	v_mul_f32_e32 v48, s6, v240
	v_exp_f32_e32 v60, v48
	v_mul_f32_e32 v48, s7, v240
	v_exp_f32_e32 v61, v48
	s_add_u32 s28, s16, s88
	s_addc_u32 s29, s17, s89
	v_mul_f32_e32 v48, s20, v240
	global_store_dwordx4 v49, v[58:61], s[28:29] offset:160
	s_mov_b64 s[90:91], exec
	s_nop 0
	v_exp_f32_e32 v58, v48
	v_mul_f32_e32 v48, s21, v240
	v_exp_f32_e32 v59, v48
	v_mul_f32_e32 v48, s18, v240
	v_exp_f32_e32 v60, v48
	v_mul_f32_e32 v48, s19, v240
	global_store_dwordx3 v49, v[58:60], s[28:29] offset:176
	s_nop 1
	v_exp_f32_e32 v58, v48
